# write-through (sc1) stores in GEMM+attention epilogues, GQA prefetch-wait ladder fix, dropped the data-free cooperative-groups grid.sync
# baseline (speedup 1.0000x reference)
; __device__ __forceinline__ unsigned cvt_pk_bf16(float lo, float hi) { f32x2_t v = {lo, hi}; bf16x2_t r = __builtin_convertvector(v, bf16x2_t); return __builtin_bit_cast(unsigned, r); }
; __device__ __forceinline__ int opaque_v(int v) { asm volatile("" : "+v"(v)); return v; }
; #define PG8_BAR __builtin_amdgcn_s_barrier()
;     __device__ __forceinline__ void operator()(const f32x4 (&acc)[2][2][4][2], const Unit& u, int wr, int wc, int fr, int fq) const {
;         fr = opaque_v(fr); fq = opaque_v(fq);
;         const int row0 = u.pm * BM + wr * 64 + fr, col0 = u.pn * BM + wc * 32 + 8 * fq;
; #pragma unroll
;         for (int ai = 0; ai < 2; ++ai)
; #pragma unroll
;             for (int m = 0; m < 4; ++m) { bf16_t* rowp = O + (size_t)(row0 + ai * HALF + m * 16) * ldc + col0;
; #pragma unroll
;                 for (int bj = 0; bj < 2; ++bj) { const f32x4 v0 = acc[ai][bj][m][0], v1 = acc[ai][bj][m][1];
;                     u32x4 w; w.x = cvt_pk_bf16(v0[0], v0[1]); w.y = cvt_pk_bf16(v0[2], v0[3]); w.z = cvt_pk_bf16(v1[0], v1[1]); w.w = cvt_pk_bf16(v1[2], v1[3]);
;                     *(u32x4*)(rowp + bj * HALF) = w; } }
; template <class Epi, class Sched>
; __device__ __forceinline__ void gemm_phase(LAS unsigned char* lds, const Gemm g, const Sched& S, const Epi& E, const int tid) {
;     ...
;         if (wr == 0) PG8_BAR;
;         E(acc, cur, wr, wc, fr, fq);
;         if (!has_next) break;
; #pragma unroll
;         for (int a = 0; a < 2; ++a)
; #pragma unroll
;             for (int b = 0; b < 2; ++b)
; #pragma unroll
;                 for (int m = 0; m < 4; ++m)
; #pragma unroll
;                     for (int n = 0; n < 2; ++n) acc[a][b][m][n] = (f32x4){0.f, 0.f, 0.f, 0.f};
;         cur = nxt; cA = nA; cB = nB; ++ui;
;         if (wr == 1) PG8_BAR;
.LBB0_145:
	v_mov_b32_e32 v142, v138
	s_lshl_b32 s15, s30, 8
	s_add_i32 s15, s15, s52
	v_mov_b32_e32 v143, v139
	v_add_u32_e32 v142, s15, v142
	s_lshl_b32 s15, s31, 8
	s_or_b32 s15, s15, s53
	v_lshl_add_u32 v144, v143, 3, s15
	v_ashrrev_i32_e32 v143, 31, v142
	v_lshlrev_b64 v[142:143], 12, v[142:143]
	v_ashrrev_i32_e32 v145, 31, v144
	v_lshl_add_u64 v[142:143], s[8:9], 0, v[142:143]
	v_lshl_add_u64 v[142:143], v[144:145], 1, v[142:143]
	v_cvt_pk_bf16_f32 v108, v108, v109
	v_cvt_pk_bf16_f32 v109, v110, v111
	v_cvt_pk_bf16_f32 v110, v104, v105
	v_cvt_pk_bf16_f32 v111, v106, v107
	s_mov_b32 s15, 0x10000
	global_store_dwordx4 v[142:143], v[108:111], off offset:256 sc1
	s_mov_b64 s[30:31], 0x10000
	v_cvt_pk_bf16_f32 v92, v92, v93
	v_add_co_u32_e32 v110, vcc, s15, v142
	v_lshl_add_u64 v[108:109], v[142:143], 0, s[30:31]
	s_nop 0
	v_addc_co_u32_e32 v111, vcc, 0, v143, vcc
	v_cvt_pk_bf16_f32 v93, v94, v95
	v_cvt_pk_bf16_f32 v94, v88, v89
	v_cvt_pk_bf16_f32 v95, v90, v91
	s_mov_b32 s15, 0x20000
	global_store_dwordx4 v[108:109], v[92:95], off offset:256 sc1
	s_mov_b64 s[30:31], 0x20000
	v_cvt_pk_bf16_f32 v76, v76, v77
	v_add_co_u32_e32 v94, vcc, s15, v142
	v_lshl_add_u64 v[92:93], v[142:143], 0, s[30:31]
	s_nop 0
	v_addc_co_u32_e32 v95, vcc, 0, v143, vcc
	v_cvt_pk_bf16_f32 v77, v78, v79
	v_cvt_pk_bf16_f32 v78, v72, v73
	v_cvt_pk_bf16_f32 v79, v74, v75
	s_mov_b32 s15, 0x30000
	global_store_dwordx4 v[92:93], v[76:79], off offset:256 sc1
	s_mov_b64 s[30:31], 0x30000
	v_cvt_pk_bf16_f32 v60, v60, v61
	v_add_co_u32_e32 v78, vcc, s15, v142
	s_mov_b32 s15, 0x80000
	s_nop 0
	v_addc_co_u32_e32 v79, vcc, 0, v143, vcc
	v_lshl_add_u64 v[76:77], v[142:143], 0, s[30:31]
	s_mov_b64 s[30:31], 0x80000
	v_cvt_pk_bf16_f32 v61, v62, v63
	v_cvt_pk_bf16_f32 v62, v56, v57
	v_add_co_u32_e32 v56, vcc, s15, v142
	v_cvt_pk_bf16_f32 v68, v68, v69
	v_cvt_pk_bf16_f32 v69, v70, v71
	v_cvt_pk_bf16_f32 v70, v64, v65
	v_lshl_add_u64 v[64:65], v[142:143], 0, s[30:31]
	v_addc_co_u32_e32 v57, vcc, 0, v143, vcc
	v_cvt_pk_bf16_f32 v44, v44, v45
	v_cvt_pk_bf16_f32 v45, v46, v47
	v_cvt_pk_bf16_f32 v46, v40, v41
	v_cvt_pk_bf16_f32 v47, v42, v43
	s_mov_b32 s15, 0x90000
	global_store_dwordx4 v[64:65], v[44:47], off offset:256 sc1
	s_mov_b64 s[30:31], 0x90000
	v_cvt_pk_bf16_f32 v28, v28, v29
	v_add_co_u32_e32 v46, vcc, s15, v142
	v_lshl_add_u64 v[44:45], v[142:143], 0, s[30:31]
	s_nop 0
	v_addc_co_u32_e32 v47, vcc, 0, v143, vcc
	v_cvt_pk_bf16_f32 v29, v30, v31
	v_cvt_pk_bf16_f32 v30, v24, v25
	v_cvt_pk_bf16_f32 v31, v26, v27
	s_mov_b32 s15, 0xa0000
	global_store_dwordx4 v[44:45], v[28:31], off offset:256 sc1
	s_mov_b64 s[30:31], 0xa0000
	v_cvt_pk_bf16_f32 v12, v12, v13
	v_add_co_u32_e32 v30, vcc, s15, v142
	v_lshl_add_u64 v[28:29], v[142:143], 0, s[30:31]
	s_nop 0
	v_addc_co_u32_e32 v31, vcc, 0, v143, vcc
	v_cvt_pk_bf16_f32 v13, v14, v15
	v_cvt_pk_bf16_f32 v14, v8, v9
	v_cvt_pk_bf16_f32 v15, v10, v11
	s_mov_b32 s15, 0xb0000
	global_store_dwordx4 v[28:29], v[12:15], off offset:256 sc1
	s_mov_b64 s[30:31], 0xb0000
	v_cvt_pk_bf16_f32 v124, v124, v125
	v_add_co_u32_e32 v14, vcc, s15, v142
	v_cvt_pk_bf16_f32 v125, v126, v127
	s_nop 0
	v_addc_co_u32_e32 v15, vcc, 0, v143, vcc
	v_cvt_pk_bf16_f32 v126, v120, v121
	v_cvt_pk_bf16_f32 v127, v122, v123
	v_cvt_pk_bf16_f32 v104, v116, v117
	v_cvt_pk_bf16_f32 v105, v118, v119
	v_cvt_pk_bf16_f32 v106, v112, v113
	v_cvt_pk_bf16_f32 v107, v114, v115
	v_cvt_pk_bf16_f32 v88, v100, v101
	v_cvt_pk_bf16_f32 v89, v102, v103
	v_cvt_pk_bf16_f32 v90, v96, v97
	v_cvt_pk_bf16_f32 v91, v98, v99
	v_cvt_pk_bf16_f32 v72, v84, v85
	v_cvt_pk_bf16_f32 v73, v86, v87
	v_cvt_pk_bf16_f32 v74, v80, v81
	v_cvt_pk_bf16_f32 v75, v82, v83
	v_cvt_pk_bf16_f32 v71, v66, v67
	v_cvt_pk_bf16_f32 v63, v58, v59
	v_cvt_pk_bf16_f32 v40, v52, v53
	v_cvt_pk_bf16_f32 v41, v54, v55
	v_cvt_pk_bf16_f32 v42, v48, v49
	v_cvt_pk_bf16_f32 v43, v50, v51
	v_cvt_pk_bf16_f32 v24, v36, v37
	v_cvt_pk_bf16_f32 v25, v38, v39
	v_cvt_pk_bf16_f32 v26, v32, v33
	v_cvt_pk_bf16_f32 v27, v34, v35
	v_lshl_add_u64 v[12:13], v[142:143], 0, s[30:31]
	v_cvt_pk_bf16_f32 v8, v20, v21
	v_cvt_pk_bf16_f32 v9, v22, v23
	v_cvt_pk_bf16_f32 v10, v16, v17
	v_cvt_pk_bf16_f32 v11, v18, v19
	v_cvt_pk_bf16_f32 v4, v4, v5
	v_cvt_pk_bf16_f32 v5, v6, v7
	v_cvt_pk_bf16_f32 v6, v0, v1
	v_cvt_pk_bf16_f32 v7, v2, v3
	s_andn2_b64 vcc, exec, s[36:37]
	s_mov_b64 s[30:31], -1
	global_store_dwordx4 v[142:143], v[124:127], off sc1
	global_store_dwordx4 v[110:111], v[104:107], off sc1
	global_store_dwordx4 v[94:95], v[88:91], off sc1
	global_store_dwordx4 v[78:79], v[72:75], off sc1
	global_store_dwordx4 v[76:77], v[68:71], off offset:256 sc1
	global_store_dwordx4 v[56:57], v[60:63], off sc1
	global_store_dwordx4 v[46:47], v[40:43], off sc1
	global_store_dwordx4 v[30:31], v[24:27], off sc1
	global_store_dwordx4 v[14:15], v[8:11], off sc1
	global_store_dwordx4 v[12:13], v[4:7], off offset:256 sc1
	s_cbranch_vccnz .LBB0_134
	s_andn2_b64 vcc, exec, s[0:1]
	s_cbranch_vccnz .LBB0_133
	s_barrier
	s_branch .LBB0_133

; __device__ __forceinline__ unsigned cvt_pk_bf16(float lo, float hi) { f32x2_t v = {lo, hi}; bf16x2_t r = __builtin_convertvector(v, bf16x2_t); return __builtin_bit_cast(unsigned, r); }
; __device__ __forceinline__ float bf_lo(unsigned w) { return __uint_as_float(w << 16); }
; __device__ __forceinline__ float bf_hi(unsigned w) { return __uint_as_float(w & 0xffff0000u); }
; __device__ __forceinline__ int opaque_v(int v) { asm volatile("" : "+v"(v)); return v; }
;     __device__ __forceinline__ void operator()(const f32x4 (&acc)[2][2][4][2], const Unit& u, int wr, int wc, int fr, int fq) const {
;         fr = opaque_v(fr); fq = opaque_v(fq);
;         const int row0 = u.pm * BM + wr * 64 + fr, col0 = u.pn * BM + wc * 32 + 8 * fq;
;         const u32x4* pc = gbase(2, u, wr, wc, fr, fq);
; #pragma unroll
;         for (int h = 0; h < 2; ++h) {
;             u32x4 c[8];
; #pragma unroll
;             for (int k = 0; k < 8; ++k) c[k] = pc[(h * 8 + k) * 64];
;             asm volatile("" ::: "memory");
; #pragma unroll
;             for (int k = 0; k < 8; ++k) { const int f = h * 8 + k, ai = f >> 3, m = (f >> 1) & 3, bj = f & 1;
;                 bf16_t* rowp = O + (size_t)(row0 + ai * HALF + m * 16) * DM + col0; const f32x4 v0 = acc[ai][bj][m][0], v1 = acc[ai][bj][m][1];
;                 u32x4 w; w.x = cvt_pk_bf16(v0[0] * bf_lo(c[k].x), v0[1] * bf_hi(c[k].x)); w.y = cvt_pk_bf16(v0[2] * bf_lo(c[k].y), v0[3] * bf_hi(c[k].y));
;                 w.z = cvt_pk_bf16(v1[0] * bf_lo(c[k].z), v1[1] * bf_hi(c[k].z)); w.w = cvt_pk_bf16(v1[2] * bf_lo(c[k].w), v1[3] * bf_hi(c[k].w));
;                 *(u32x4*)(rowp + bj * HALF) = w; }
.LBB0_183:
	s_lshl_b32 s2, s64, 8
	v_mov_b32_e32 v128, v233
	s_add_i32 s2, s2, s54
	v_mov_b32_e32 v129, v234
	v_add_u32_e32 v152, s2, v128
	s_lshl_b32 s2, s16, 8
	s_or_b32 s2, s2, s55
	v_ashrrev_i32_e32 v153, 31, v152
	v_lshl_add_u32 v166, v129, 3, s2
	s_add_i32 s2, s19, 0x400
	s_ashr_i32 s3, s2, 31
	s_lshl_b64 s[2:3], s[2:3], 17
	s_add_u32 s2, s58, s2
	v_lshlrev_b32_e32 v130, 4, v129
	s_addc_u32 s3, s59, s3
	v_ashrrev_i32_e32 v131, 31, v130
	v_lshl_add_u64 v[130:131], v[130:131], 4, s[2:3]
	v_ashrrev_i32_e32 v129, 31, v128
	v_lshl_add_u64 v[154:155], v[128:129], 4, v[130:131]
	global_load_dwordx4 v[158:161], v[154:155], off
	global_load_dwordx4 v[162:165], v[154:155], off offset:1024
	global_load_dwordx4 v[148:151], v[154:155], off offset:2048
	global_load_dwordx4 v[144:147], v[154:155], off offset:3072
	v_add_co_u32_e32 v128, vcc, s33, v154
	s_movk_i32 s2, 0x2000
	s_nop 0
	v_addc_co_u32_e32 v129, vcc, 0, v155, vcc
	v_add_co_u32_e32 v156, vcc, s2, v154
	v_lshlrev_b64 v[152:153], 12, v[152:153]
	s_nop 0
	v_addc_co_u32_e32 v157, vcc, 0, v155, vcc
	global_load_dwordx4 v[140:143], v[156:157], off offset:-4096
	global_load_dwordx4 v[136:139], v[128:129], off offset:1024
	global_load_dwordx4 v[132:135], v[128:129], off offset:2048
	s_nop 0
	global_load_dwordx4 v[128:131], v[128:129], off offset:3072
	v_ashrrev_i32_e32 v167, 31, v166
	v_lshl_add_u64 v[152:153], s[10:11], 0, v[152:153]
	v_lshl_add_u64 v[152:153], v[166:167], 1, v[152:153]
	s_mov_b64 s[2:3], 0x10000
	s_waitcnt vmcnt(0)
	v_lshlrev_b32_e32 v166, 16, v158
	v_and_b32_e32 v167, 0xffff0000, v158
	v_lshlrev_b32_e32 v158, 16, v159
	v_and_b32_e32 v159, 0xffff0000, v159
	v_pk_mul_f32 v[124:125], v[124:125], v[166:167]
	v_pk_mul_f32 v[126:127], v[126:127], v[158:159]
	v_cvt_pk_bf16_f32 v124, v124, v125
	v_cvt_pk_bf16_f32 v125, v126, v127
	v_lshlrev_b32_e32 v126, 16, v160
	v_and_b32_e32 v127, 0xffff0000, v160
	v_pk_mul_f32 v[120:121], v[120:121], v[126:127]
	s_nop 0
	v_cvt_pk_bf16_f32 v126, v120, v121
	v_lshlrev_b32_e32 v120, 16, v161
	v_and_b32_e32 v121, 0xffff0000, v161
	v_pk_mul_f32 v[120:121], v[122:123], v[120:121]
	s_nop 0
	v_cvt_pk_bf16_f32 v127, v120, v121
	v_lshlrev_b32_e32 v120, 16, v162
	v_and_b32_e32 v121, 0xffff0000, v162
	v_pk_mul_f32 v[116:117], v[116:117], v[120:121]
	v_lshlrev_b32_e32 v120, 16, v163
	v_and_b32_e32 v121, 0xffff0000, v163
	v_pk_mul_f32 v[118:119], v[118:119], v[120:121]
	v_cvt_pk_bf16_f32 v116, v116, v117
	v_cvt_pk_bf16_f32 v117, v118, v119
	v_lshlrev_b32_e32 v118, 16, v164
	v_and_b32_e32 v119, 0xffff0000, v164
	v_pk_mul_f32 v[112:113], v[112:113], v[118:119]
	global_store_dwordx4 v[152:153], v[124:127], off sc1
	v_cvt_pk_bf16_f32 v118, v112, v113
	v_lshlrev_b32_e32 v112, 16, v165
	v_and_b32_e32 v113, 0xffff0000, v165
	v_pk_mul_f32 v[112:113], v[114:115], v[112:113]
	v_lshlrev_b32_e32 v114, 16, v148
	v_and_b32_e32 v115, 0xffff0000, v148
	v_pk_mul_f32 v[108:109], v[108:109], v[114:115]
	v_lshlrev_b32_e32 v114, 16, v149
	v_and_b32_e32 v115, 0xffff0000, v149
	v_pk_mul_f32 v[110:111], v[110:111], v[114:115]
	v_cvt_pk_bf16_f32 v108, v108, v109
	v_cvt_pk_bf16_f32 v109, v110, v111
	v_lshlrev_b32_e32 v110, 16, v150
	v_and_b32_e32 v111, 0xffff0000, v150
	v_pk_mul_f32 v[104:105], v[104:105], v[110:111]
	v_cvt_pk_bf16_f32 v119, v112, v113
	v_cvt_pk_bf16_f32 v110, v104, v105
	v_lshlrev_b32_e32 v104, 16, v151
	v_and_b32_e32 v105, 0xffff0000, v151
	v_lshl_add_u64 v[112:113], v[152:153], 0, s[2:3]
	v_pk_mul_f32 v[104:105], v[106:107], v[104:105]
	s_mov_b32 s2, 0x10000
	v_cvt_pk_bf16_f32 v111, v104, v105
	v_add_co_u32_e32 v104, vcc, s2, v152
	s_mov_b64 s[2:3], 0x20000
	s_nop 0
	v_addc_co_u32_e32 v105, vcc, 0, v153, vcc
	global_store_dwordx4 v[104:105], v[108:111], off sc1
	v_lshlrev_b32_e32 v104, 16, v144
	v_and_b32_e32 v105, 0xffff0000, v144
	v_pk_mul_f32 v[100:101], v[100:101], v[104:105]
	v_lshlrev_b32_e32 v104, 16, v145
	v_and_b32_e32 v105, 0xffff0000, v145
	v_pk_mul_f32 v[102:103], v[102:103], v[104:105]
	v_cvt_pk_bf16_f32 v100, v100, v101
	v_cvt_pk_bf16_f32 v101, v102, v103
	v_lshlrev_b32_e32 v102, 16, v146
	v_and_b32_e32 v103, 0xffff0000, v146
	v_pk_mul_f32 v[92:93], v[92:93], v[102:103]
	global_store_dwordx4 v[152:153], v[116:119], off offset:256 sc1
	v_cvt_pk_bf16_f32 v102, v92, v93
	v_lshlrev_b32_e32 v92, 16, v147
	v_and_b32_e32 v93, 0xffff0000, v147
	v_pk_mul_f32 v[92:93], v[94:95], v[92:93]
	v_lshlrev_b32_e32 v94, 16, v141
	v_cvt_pk_bf16_f32 v103, v92, v93
	v_lshlrev_b32_e32 v92, 16, v140
	v_and_b32_e32 v93, 0xffff0000, v140
	v_and_b32_e32 v95, 0xffff0000, v141
	v_pk_mul_f32 v[92:93], v[96:97], v[92:93]
	v_pk_mul_f32 v[94:95], v[98:99], v[94:95]
	v_cvt_pk_bf16_f32 v92, v92, v93
	v_cvt_pk_bf16_f32 v93, v94, v95
	v_lshlrev_b32_e32 v94, 16, v142
	v_and_b32_e32 v95, 0xffff0000, v142
	v_pk_mul_f32 v[88:89], v[88:89], v[94:95]
	global_store_dwordx4 v[112:113], v[100:103], off offset:256 sc1
	v_cvt_pk_bf16_f32 v94, v88, v89
	v_lshlrev_b32_e32 v88, 16, v143
	v_and_b32_e32 v89, 0xffff0000, v143
	v_lshl_add_u64 v[100:101], v[152:153], 0, s[2:3]
	v_pk_mul_f32 v[88:89], v[90:91], v[88:89]
	s_mov_b32 s2, 0x20000
	v_cvt_pk_bf16_f32 v95, v88, v89
	v_add_co_u32_e32 v88, vcc, s2, v152
	s_mov_b64 s[2:3], 0x30000
	s_nop 0
	v_addc_co_u32_e32 v89, vcc, 0, v153, vcc
	global_store_dwordx4 v[88:89], v[92:95], off sc1
	v_lshlrev_b32_e32 v88, 16, v136
	v_and_b32_e32 v89, 0xffff0000, v136
	v_pk_mul_f32 v[84:85], v[84:85], v[88:89]
	v_lshlrev_b32_e32 v88, 16, v137
	v_and_b32_e32 v89, 0xffff0000, v137
	v_pk_mul_f32 v[86:87], v[86:87], v[88:89]
	v_cvt_pk_bf16_f32 v84, v84, v85
	v_cvt_pk_bf16_f32 v85, v86, v87
	v_lshlrev_b32_e32 v86, 16, v138
	v_and_b32_e32 v87, 0xffff0000, v138
; __device__ __forceinline__ unsigned cvt_pk_bf16(float lo, float hi) { f32x2_t v = {lo, hi}; bf16x2_t r = __builtin_convertvector(v, bf16x2_t); return __builtin_bit_cast(unsigned, r); }
; __device__ __forceinline__ float bf_lo(unsigned w) { return __uint_as_float(w << 16); }
; __device__ __forceinline__ float bf_hi(unsigned w) { return __uint_as_float(w & 0xffff0000u); }
;     __device__ __forceinline__ void operator()(const f32x4 (&acc)[2][2][4][2], const Unit& u, int wr, int wc, int fr, int fq) const {
;     ...
; #pragma unroll
;         for (int h = 0; h < 2; ++h) {
;             u32x4 c[8];
; #pragma unroll
;             for (int k = 0; k < 8; ++k) c[k] = pc[(h * 8 + k) * 64];
;             asm volatile("" ::: "memory");
; #pragma unroll
;             for (int k = 0; k < 8; ++k) { const int f = h * 8 + k, ai = f >> 3, m = (f >> 1) & 3, bj = f & 1;
;                 bf16_t* rowp = O + (size_t)(row0 + ai * HALF + m * 16) * DM + col0; const f32x4 v0 = acc[ai][bj][m][0], v1 = acc[ai][bj][m][1];
;                 u32x4 w; w.x = cvt_pk_bf16(v0[0] * bf_lo(c[k].x), v0[1] * bf_hi(c[k].x)); w.y = cvt_pk_bf16(v0[2] * bf_lo(c[k].y), v0[3] * bf_hi(c[k].y));
;                 w.z = cvt_pk_bf16(v1[0] * bf_lo(c[k].z), v1[1] * bf_hi(c[k].z)); w.w = cvt_pk_bf16(v1[2] * bf_lo(c[k].w), v1[3] * bf_hi(c[k].w));
;                 *(u32x4*)(rowp + bj * HALF) = w; }
	v_pk_mul_f32 v[76:77], v[76:77], v[86:87]
	s_nop 0
	v_cvt_pk_bf16_f32 v86, v76, v77
	v_lshlrev_b32_e32 v76, 16, v139
	v_and_b32_e32 v77, 0xffff0000, v139
	v_pk_mul_f32 v[76:77], v[78:79], v[76:77]
	v_lshlrev_b32_e32 v78, 16, v133
	v_cvt_pk_bf16_f32 v87, v76, v77
	v_lshlrev_b32_e32 v76, 16, v132
	v_and_b32_e32 v77, 0xffff0000, v132
	v_and_b32_e32 v79, 0xffff0000, v133
	v_pk_mul_f32 v[76:77], v[80:81], v[76:77]
	v_pk_mul_f32 v[78:79], v[82:83], v[78:79]
	v_cvt_pk_bf16_f32 v76, v76, v77
	v_cvt_pk_bf16_f32 v77, v78, v79
	v_lshlrev_b32_e32 v78, 16, v134
	v_and_b32_e32 v79, 0xffff0000, v134
	v_pk_mul_f32 v[72:73], v[72:73], v[78:79]
	global_store_dwordx4 v[100:101], v[84:87], off offset:256 sc1
	v_cvt_pk_bf16_f32 v78, v72, v73
	v_lshlrev_b32_e32 v72, 16, v135
	v_and_b32_e32 v73, 0xffff0000, v135
	v_lshl_add_u64 v[84:85], v[152:153], 0, s[2:3]
	v_pk_mul_f32 v[72:73], v[74:75], v[72:73]
	s_mov_b32 s2, 0x30000
	v_cvt_pk_bf16_f32 v79, v72, v73
	v_add_co_u32_e32 v72, vcc, s2, v152
	s_movk_i32 s2, 0x3000
	s_nop 0
	v_addc_co_u32_e32 v73, vcc, 0, v153, vcc
	global_store_dwordx4 v[72:73], v[76:79], off sc1
	v_lshlrev_b32_e32 v72, 16, v128
	v_and_b32_e32 v73, 0xffff0000, v128
	v_pk_mul_f32 v[68:69], v[68:69], v[72:73]
	v_lshlrev_b32_e32 v72, 16, v129
	v_and_b32_e32 v73, 0xffff0000, v129
	v_pk_mul_f32 v[70:71], v[70:71], v[72:73]
	v_cvt_pk_bf16_f32 v68, v68, v69
	v_cvt_pk_bf16_f32 v69, v70, v71
	v_lshlrev_b32_e32 v70, 16, v130
	v_and_b32_e32 v71, 0xffff0000, v130
	v_pk_mul_f32 v[64:65], v[64:65], v[70:71]
	s_nop 0
	v_cvt_pk_bf16_f32 v70, v64, v65
	v_lshlrev_b32_e32 v64, 16, v131
	v_and_b32_e32 v65, 0xffff0000, v131
	v_pk_mul_f32 v[64:65], v[66:67], v[64:65]
	s_nop 0
	v_cvt_pk_bf16_f32 v71, v64, v65
	global_store_dwordx4 v[84:85], v[68:71], off offset:256 sc1
	global_load_dwordx4 v[68:71], v[156:157], off
	s_nop 0
	global_load_dwordx4 v[72:75], v[156:157], off offset:1024
	global_load_dwordx4 v[76:79], v[156:157], off offset:2048
	global_load_dwordx4 v[80:83], v[156:157], off offset:3072
	v_add_co_u32_e32 v64, vcc, s2, v154
	s_mov_b64 s[2:3], 0x80000
	s_nop 0
	v_addc_co_u32_e32 v65, vcc, 0, v155, vcc
	global_load_dwordx4 v[84:87], v[64:65], off
	global_load_dwordx4 v[88:91], v[64:65], off offset:1024
	global_load_dwordx4 v[92:95], v[64:65], off offset:2048
	s_nop 0
	global_load_dwordx4 v[64:67], v[64:65], off offset:3072
	v_lshl_add_u64 v[96:97], v[152:153], 0, s[2:3]
	s_mov_b32 s2, 0x80000
	s_waitcnt vmcnt(7)
	v_lshlrev_b32_e32 v98, 16, v68
	v_and_b32_e32 v99, 0xffff0000, v68
	v_lshlrev_b32_e32 v68, 16, v69
	v_and_b32_e32 v69, 0xffff0000, v69
	v_pk_mul_f32 v[60:61], v[60:61], v[98:99]
	v_pk_mul_f32 v[62:63], v[62:63], v[68:69]
	v_cvt_pk_bf16_f32 v60, v60, v61
	v_cvt_pk_bf16_f32 v61, v62, v63
	v_lshlrev_b32_e32 v62, 16, v70
	v_and_b32_e32 v63, 0xffff0000, v70
	v_pk_mul_f32 v[56:57], v[56:57], v[62:63]
	s_nop 0
	v_cvt_pk_bf16_f32 v62, v56, v57
	v_lshlrev_b32_e32 v56, 16, v71
	v_and_b32_e32 v57, 0xffff0000, v71
	v_pk_mul_f32 v[56:57], v[58:59], v[56:57]
	s_nop 0
	v_cvt_pk_bf16_f32 v63, v56, v57
	v_add_co_u32_e32 v56, vcc, s2, v152
	s_mov_b64 s[2:3], 0x90000
	s_nop 0
	v_addc_co_u32_e32 v57, vcc, 0, v153, vcc
	global_store_dwordx4 v[56:57], v[60:63], off sc1
	s_waitcnt vmcnt(7)
	v_lshlrev_b32_e32 v56, 16, v72
	v_and_b32_e32 v57, 0xffff0000, v72
	v_pk_mul_f32 v[52:53], v[52:53], v[56:57]
	v_lshlrev_b32_e32 v56, 16, v73
	v_and_b32_e32 v57, 0xffff0000, v73
	v_pk_mul_f32 v[54:55], v[54:55], v[56:57]
	v_cvt_pk_bf16_f32 v52, v52, v53
	v_cvt_pk_bf16_f32 v53, v54, v55
	v_lshlrev_b32_e32 v54, 16, v74
	v_and_b32_e32 v55, 0xffff0000, v74
	v_pk_mul_f32 v[44:45], v[44:45], v[54:55]
	s_nop 0
	v_cvt_pk_bf16_f32 v54, v44, v45
	v_lshlrev_b32_e32 v44, 16, v75
	v_and_b32_e32 v45, 0xffff0000, v75
	v_pk_mul_f32 v[44:45], v[46:47], v[44:45]
	s_waitcnt vmcnt(6)
; __device__ __forceinline__ unsigned cvt_pk_bf16(float lo, float hi) { f32x2_t v = {lo, hi}; bf16x2_t r = __builtin_convertvector(v, bf16x2_t); return __builtin_bit_cast(unsigned, r); }
; __device__ __forceinline__ float bf_lo(unsigned w) { return __uint_as_float(w << 16); }
; __device__ __forceinline__ float bf_hi(unsigned w) { return __uint_as_float(w & 0xffff0000u); }
; #define PG8_BAR __builtin_amdgcn_s_barrier()
;     __device__ __forceinline__ void operator()(const f32x4 (&acc)[2][2][4][2], const Unit& u, int wr, int wc, int fr, int fq) const {
;     ...
; #pragma unroll
;         for (int h = 0; h < 2; ++h) {
;             u32x4 c[8];
; #pragma unroll
;             for (int k = 0; k < 8; ++k) c[k] = pc[(h * 8 + k) * 64];
;             asm volatile("" ::: "memory");
; #pragma unroll
;             for (int k = 0; k < 8; ++k) { const int f = h * 8 + k, ai = f >> 3, m = (f >> 1) & 3, bj = f & 1;
;                 bf16_t* rowp = O + (size_t)(row0 + ai * HALF + m * 16) * DM + col0; const f32x4 v0 = acc[ai][bj][m][0], v1 = acc[ai][bj][m][1];
;                 u32x4 w; w.x = cvt_pk_bf16(v0[0] * bf_lo(c[k].x), v0[1] * bf_hi(c[k].x)); w.y = cvt_pk_bf16(v0[2] * bf_lo(c[k].y), v0[3] * bf_hi(c[k].y));
;                 w.z = cvt_pk_bf16(v1[0] * bf_lo(c[k].z), v1[1] * bf_hi(c[k].z)); w.w = cvt_pk_bf16(v1[2] * bf_lo(c[k].w), v1[3] * bf_hi(c[k].w));
;                 *(u32x4*)(rowp + bj * HALF) = w; }
; template <class Epi, class Sched>
; __device__ __forceinline__ void gemm_phase(LAS unsigned char* lds, const Gemm g, const Sched& S, const Epi& E, const int tid) {
;     ...
;         if (wr == 0) PG8_BAR;
;         E(acc, cur, wr, wc, fr, fq);
;         if (!has_next) break;
; #pragma unroll
;         for (int a = 0; a < 2; ++a)
; #pragma unroll
;             for (int b = 0; b < 2; ++b)
; #pragma unroll
;                 for (int m = 0; m < 4; ++m)
; #pragma unroll
;                     for (int n = 0; n < 2; ++n) acc[a][b][m][n] = (f32x4){0.f, 0.f, 0.f, 0.f};
;         cur = nxt; cA = nA; cB = nB; ++ui;
;         if (wr == 1) PG8_BAR;
	v_lshlrev_b32_e32 v46, 16, v77
	v_cvt_pk_bf16_f32 v55, v44, v45
	v_lshlrev_b32_e32 v44, 16, v76
	v_and_b32_e32 v45, 0xffff0000, v76
	v_and_b32_e32 v47, 0xffff0000, v77
	v_pk_mul_f32 v[44:45], v[48:49], v[44:45]
	v_pk_mul_f32 v[46:47], v[50:51], v[46:47]
	v_cvt_pk_bf16_f32 v44, v44, v45
	v_cvt_pk_bf16_f32 v45, v46, v47
	v_lshlrev_b32_e32 v46, 16, v78
	v_and_b32_e32 v47, 0xffff0000, v78
	v_pk_mul_f32 v[40:41], v[40:41], v[46:47]
	global_store_dwordx4 v[96:97], v[52:55], off offset:256 sc1
	v_cvt_pk_bf16_f32 v46, v40, v41
	v_lshlrev_b32_e32 v40, 16, v79
	v_and_b32_e32 v41, 0xffff0000, v79
	v_lshl_add_u64 v[52:53], v[152:153], 0, s[2:3]
	v_pk_mul_f32 v[40:41], v[42:43], v[40:41]
	s_mov_b32 s2, 0x90000
	v_cvt_pk_bf16_f32 v47, v40, v41
	v_add_co_u32_e32 v40, vcc, s2, v152
	s_mov_b64 s[2:3], 0xa0000
	s_nop 0
	v_addc_co_u32_e32 v41, vcc, 0, v153, vcc
	global_store_dwordx4 v[40:41], v[44:47], off sc1
	s_waitcnt vmcnt(7)
	v_lshlrev_b32_e32 v40, 16, v80
	v_and_b32_e32 v41, 0xffff0000, v80
	v_pk_mul_f32 v[36:37], v[36:37], v[40:41]
	v_lshlrev_b32_e32 v40, 16, v81
	v_and_b32_e32 v41, 0xffff0000, v81
	v_pk_mul_f32 v[38:39], v[38:39], v[40:41]
	v_cvt_pk_bf16_f32 v36, v36, v37
	v_cvt_pk_bf16_f32 v37, v38, v39
	v_lshlrev_b32_e32 v38, 16, v82
	v_and_b32_e32 v39, 0xffff0000, v82
	v_pk_mul_f32 v[28:29], v[28:29], v[38:39]
	s_nop 0
	v_cvt_pk_bf16_f32 v38, v28, v29
	v_lshlrev_b32_e32 v28, 16, v83
	v_and_b32_e32 v29, 0xffff0000, v83
	v_pk_mul_f32 v[28:29], v[30:31], v[28:29]
	s_waitcnt vmcnt(6)
	v_lshlrev_b32_e32 v30, 16, v85
	v_cvt_pk_bf16_f32 v39, v28, v29
	v_lshlrev_b32_e32 v28, 16, v84
	v_and_b32_e32 v29, 0xffff0000, v84
	v_and_b32_e32 v31, 0xffff0000, v85
	v_pk_mul_f32 v[28:29], v[32:33], v[28:29]
	v_pk_mul_f32 v[30:31], v[34:35], v[30:31]
	v_cvt_pk_bf16_f32 v28, v28, v29
	v_cvt_pk_bf16_f32 v29, v30, v31
	v_lshlrev_b32_e32 v30, 16, v86
	v_and_b32_e32 v31, 0xffff0000, v86
	v_pk_mul_f32 v[24:25], v[24:25], v[30:31]
	global_store_dwordx4 v[52:53], v[36:39], off offset:256 sc1
	v_cvt_pk_bf16_f32 v30, v24, v25
	v_lshlrev_b32_e32 v24, 16, v87
	v_and_b32_e32 v25, 0xffff0000, v87
	v_lshl_add_u64 v[36:37], v[152:153], 0, s[2:3]
	v_pk_mul_f32 v[24:25], v[26:27], v[24:25]
	s_mov_b32 s2, 0xa0000
	v_cvt_pk_bf16_f32 v31, v24, v25
	v_add_co_u32_e32 v24, vcc, s2, v152
	s_mov_b64 s[2:3], 0xb0000
	s_nop 0
	v_addc_co_u32_e32 v25, vcc, 0, v153, vcc
	global_store_dwordx4 v[24:25], v[28:31], off sc1
	s_waitcnt vmcnt(7)
	v_lshlrev_b32_e32 v24, 16, v88
	v_and_b32_e32 v25, 0xffff0000, v88
	v_pk_mul_f32 v[20:21], v[20:21], v[24:25]
	v_lshlrev_b32_e32 v24, 16, v89
	v_and_b32_e32 v25, 0xffff0000, v89
	v_pk_mul_f32 v[22:23], v[22:23], v[24:25]
	v_cvt_pk_bf16_f32 v20, v20, v21
	v_cvt_pk_bf16_f32 v21, v22, v23
	v_lshlrev_b32_e32 v22, 16, v90
	v_and_b32_e32 v23, 0xffff0000, v90
	v_pk_mul_f32 v[12:13], v[12:13], v[22:23]
	s_nop 0
	v_cvt_pk_bf16_f32 v22, v12, v13
	v_lshlrev_b32_e32 v12, 16, v91
	v_and_b32_e32 v13, 0xffff0000, v91
	v_pk_mul_f32 v[12:13], v[14:15], v[12:13]
	s_waitcnt vmcnt(6)
	v_lshlrev_b32_e32 v14, 16, v93
	v_cvt_pk_bf16_f32 v23, v12, v13
	v_lshlrev_b32_e32 v12, 16, v92
	v_and_b32_e32 v13, 0xffff0000, v92
	v_and_b32_e32 v15, 0xffff0000, v93
	v_pk_mul_f32 v[12:13], v[16:17], v[12:13]
	v_pk_mul_f32 v[14:15], v[18:19], v[14:15]
	v_cvt_pk_bf16_f32 v12, v12, v13
	v_cvt_pk_bf16_f32 v13, v14, v15
	v_lshlrev_b32_e32 v14, 16, v94
	v_and_b32_e32 v15, 0xffff0000, v94
	v_pk_mul_f32 v[8:9], v[8:9], v[14:15]
	global_store_dwordx4 v[36:37], v[20:23], off offset:256 sc1
	v_cvt_pk_bf16_f32 v14, v8, v9
	v_lshlrev_b32_e32 v8, 16, v95
	v_and_b32_e32 v9, 0xffff0000, v95
	v_lshl_add_u64 v[20:21], v[152:153], 0, s[2:3]
	v_pk_mul_f32 v[8:9], v[10:11], v[8:9]
	s_mov_b32 s2, 0xb0000
	v_cvt_pk_bf16_f32 v15, v8, v9
	v_add_co_u32_e32 v8, vcc, s2, v152
	s_mov_b64 s[2:3], -1
	s_nop 0
	v_addc_co_u32_e32 v9, vcc, 0, v153, vcc
	global_store_dwordx4 v[8:9], v[12:15], off sc1
	s_waitcnt vmcnt(7)
	v_lshlrev_b32_e32 v8, 16, v64
	v_and_b32_e32 v9, 0xffff0000, v64
	v_pk_mul_f32 v[4:5], v[4:5], v[8:9]
	v_lshlrev_b32_e32 v8, 16, v65
	v_and_b32_e32 v9, 0xffff0000, v65
	v_pk_mul_f32 v[6:7], v[6:7], v[8:9]
	v_cvt_pk_bf16_f32 v4, v4, v5
	v_cvt_pk_bf16_f32 v5, v6, v7
	v_lshlrev_b32_e32 v6, 16, v66
	v_and_b32_e32 v7, 0xffff0000, v66
	v_pk_mul_f32 v[0:1], v[0:1], v[6:7]
	s_and_b64 vcc, exec, s[36:37]
	v_cvt_pk_bf16_f32 v6, v0, v1
	v_lshlrev_b32_e32 v0, 16, v67
	v_and_b32_e32 v1, 0xffff0000, v67
	v_pk_mul_f32 v[0:1], v[2:3], v[0:1]
	s_nop 0
	v_cvt_pk_bf16_f32 v7, v0, v1
	global_store_dwordx4 v[20:21], v[4:7], off offset:256 sc1
	s_cbranch_vccnz .LBB0_162
	s_andn2_b64 vcc, exec, s[8:9]
	s_cbranch_vccnz .LBB0_161
	s_barrier
	s_branch .LBB0_161

; __device__ __forceinline__ unsigned cvt_pk_bf16(float lo, float hi) { f32x2_t v = {lo, hi}; bf16x2_t r = __builtin_convertvector(v, bf16x2_t); return __builtin_bit_cast(unsigned, r); }
; __device__ __forceinline__ int crow(int r, int hi) { return (r & 3) + 8 * (r >> 2) + 4 * hi; }
; template <int MODE, int SDEPTH, bool SIMPLE>
; __device__ __forceinline__ void attn_body(const Unit& U, char* lds, const int tid) {
;     ...
;   if (hi == 0) li_l[r32] = l_reg; asm volatile("s_waitcnt lgkmcnt(0)" ::: "memory");
;   if constexpr (MODE == 2) { if (hi == 0) U.LSE[(long)(wid * QBLK + r32) * U.ldl] = m_reg * SCALE + __logf(l_reg); }
;   __syncthreads();
;   constexpr int OP = 136;
;   bf16_t* ol = (bf16_t*)lds + wid * (32 * OP);
; #pragma unroll
;   for (int r = 0; r < 16; ++r) { const float rl = __builtin_amdgcn_rcpf(li_l[crow(r, hi)]); bf16_t* op = ol + crow(r, hi) * OP + r32;
; #pragma unroll
;     for (int d0 = 0; d0 < 4; ++d0) op[d0 * 32] = (bf16_t)(cvt_pk_bf16(o[d0][r] * rl, 0.f) & 0xffffu); }
;   asm volatile("s_waitcnt lgkmcnt(0)" ::: "memory");
.LBB0_197:
	s_or_b64 exec, exec, s[0:1]
	s_ashr_i32 s31, s30, 31
	s_lshl_b64 s[0:1], s[30:31], 13
	s_or_b32 s0, s0, s19
	s_mul_i32 s2, s1, 0x1400
	s_mul_hi_u32 s3, s0, 0x1400
	s_add_i32 s3, s3, s2
	s_mul_i32 s2, s0, 0x1400
	s_add_u32 s2, s38, s2
	s_mul_i32 s1, s1, 0x8c00
	s_mul_hi_u32 s15, s0, 0x8c00
	v_add_u32_e32 v65, v185, v192
	s_addc_u32 s3, s39, s3
	s_add_i32 s15, s15, s1
	s_mul_i32 s0, s0, 0x8c00
	s_waitcnt lgkmcnt(0)
	s_waitcnt lgkmcnt(0)
	s_barrier
	ds_read_b128 v[66:69], v65
	s_add_u32 s19, s8, s0
	s_addc_u32 s15, s9, s15
	s_lshl_b32 s16, s16, 8
	s_add_u32 s0, s2, s16
	s_addc_u32 s1, s3, 0
	s_add_u32 s2, s19, s16
	s_waitcnt lgkmcnt(0)
	v_rcp_f32_e32 v66, v66
	s_addc_u32 s3, s15, 0
	s_movk_i32 s15, 0x2200
	v_mul_lo_u32 v64, v184, s15
	v_add_u32_e32 v64, 0, v64
	v_lshl_add_u32 v70, v183, 1, v64
	s_movk_i32 s15, 0x440
	v_mul_f32_e32 v0, v0, v66
	v_mad_u32_u24 v71, v182, s15, v70
	v_cvt_pk_bf16_f32 v0, v0, s0
	ds_write_b16 v71, v0
	v_mul_f32_e32 v0, v48, v66
	v_cvt_pk_bf16_f32 v0, v0, s0
	ds_write_b16 v71, v0 offset:64
	v_mul_f32_e32 v0, v32, v66
	v_cvt_pk_bf16_f32 v0, v0, s0
	v_rcp_f32_e32 v32, v67
	ds_write_b16 v71, v0 offset:128
	v_mul_f32_e32 v0, v16, v66
	v_cvt_pk_bf16_f32 v0, v0, s0
	ds_write_b16 v71, v0 offset:192
	v_lshl_or_b32 v0, v182, 2, 1
	s_movk_i32 s15, 0x110
	v_mad_u32_u24 v16, v0, s15, v70
	v_mul_f32_e32 v0, v1, v32
	v_cvt_pk_bf16_f32 v0, v0, s0
	ds_write_b16 v16, v0
	v_mul_f32_e32 v0, v49, v32
	v_cvt_pk_bf16_f32 v0, v0, s0
	ds_write_b16 v16, v0 offset:64
	v_mul_f32_e32 v0, v33, v32
	v_cvt_pk_bf16_f32 v0, v0, s0
	ds_write_b16 v16, v0 offset:128
	v_mul_f32_e32 v0, v17, v32
	v_cvt_pk_bf16_f32 v0, v0, s0
	ds_write_b16 v16, v0 offset:192
	v_rcp_f32_e32 v0, v68
	v_lshlrev_b32_e32 v192, 1, v176
	s_add_i32 s62, s62, 1
	s_add_i32 s28, s28, s56
	v_mul_f32_e32 v1, v2, v0
	v_cvt_pk_bf16_f32 v1, v1, s0
	ds_write_b16 v16, v1 offset:272
	v_mul_f32_e32 v1, v50, v0
	v_cvt_pk_bf16_f32 v1, v1, s0
	ds_write_b16 v16, v1 offset:336
	v_mul_f32_e32 v1, v34, v0
	v_mul_f32_e32 v0, v18, v0
	v_cvt_pk_bf16_f32 v0, v0, s0
	ds_write_b16 v16, v0 offset:464
	v_rcp_f32_e32 v0, v69
	v_cvt_pk_bf16_f32 v1, v1, s0
	ds_write_b16 v16, v1 offset:400
	s_movk_i32 s69, 0x1400
	v_mul_f32_e32 v1, v3, v0
	v_cvt_pk_bf16_f32 v1, v1, s0
	ds_write_b16 v16, v1 offset:544
	v_mul_f32_e32 v1, v51, v0
	v_cvt_pk_bf16_f32 v1, v1, s0
	ds_write_b16 v16, v1 offset:608
	v_mul_f32_e32 v1, v35, v0
	v_mul_f32_e32 v0, v19, v0
	v_cvt_pk_bf16_f32 v1, v1, s0
	v_cvt_pk_bf16_f32 v0, v0, s0
	ds_write_b16 v16, v1 offset:672
	ds_write_b16 v16, v0 offset:736
	ds_read_b128 v[0:3], v65 offset:32
	s_waitcnt lgkmcnt(0)
	v_rcp_f32_e32 v0, v0
	s_nop 0
	v_mul_f32_e32 v4, v4, v0
	v_cvt_pk_bf16_f32 v4, v4, s0
	ds_write_b16 v16, v4 offset:1904
	v_mul_f32_e32 v4, v52, v0
	v_cvt_pk_bf16_f32 v4, v4, s0
	ds_write_b16 v16, v4 offset:1968
	v_mul_f32_e32 v4, v36, v0
	v_mul_f32_e32 v0, v20, v0
	v_cvt_pk_bf16_f32 v0, v0, s0
	ds_write_b16 v16, v0 offset:2096
	v_rcp_f32_e32 v0, v1
	v_cvt_pk_bf16_f32 v4, v4, s0
	ds_write_b16 v16, v4 offset:2032
	v_mul_f32_e32 v1, v5, v0
	v_cvt_pk_bf16_f32 v1, v1, s0
	ds_write_b16 v16, v1 offset:2176
	v_mul_f32_e32 v1, v53, v0
	v_cvt_pk_bf16_f32 v1, v1, s0
	ds_write_b16 v16, v1 offset:2240
	v_mul_f32_e32 v1, v37, v0
	v_mul_f32_e32 v0, v21, v0
	v_cvt_pk_bf16_f32 v0, v0, s0
	ds_write_b16 v16, v0 offset:2368
	v_rcp_f32_e32 v0, v2
	v_cvt_pk_bf16_f32 v1, v1, s0
	ds_write_b16 v16, v1 offset:2304
	v_mul_f32_e32 v1, v6, v0
	v_cvt_pk_bf16_f32 v1, v1, s0
	ds_write_b16 v16, v1 offset:2448
	v_mul_f32_e32 v1, v54, v0
	v_cvt_pk_bf16_f32 v1, v1, s0
	ds_write_b16 v16, v1 offset:2512
	v_mul_f32_e32 v1, v38, v0
	v_mul_f32_e32 v0, v22, v0
	v_cvt_pk_bf16_f32 v0, v0, s0
	ds_write_b16 v16, v0 offset:2640
	v_rcp_f32_e32 v0, v3
	v_cvt_pk_bf16_f32 v1, v1, s0
	ds_write_b16 v16, v1 offset:2576
	v_mul_f32_e32 v1, v7, v0
	v_cvt_pk_bf16_f32 v1, v1, s0
	ds_write_b16 v16, v1 offset:2720
	v_mul_f32_e32 v1, v55, v0
	v_cvt_pk_bf16_f32 v1, v1, s0
	ds_write_b16 v16, v1 offset:2784
	v_mul_f32_e32 v1, v39, v0
	v_mul_f32_e32 v0, v23, v0
	v_cvt_pk_bf16_f32 v1, v1, s0
	v_cvt_pk_bf16_f32 v0, v0, s0
	ds_write_b16 v16, v1 offset:2848
	ds_write_b16 v16, v0 offset:2912
	ds_read_b128 v[0:3], v65 offset:64
	s_waitcnt lgkmcnt(0)
	v_rcp_f32_e32 v0, v0
	s_nop 0
	v_mul_f32_e32 v4, v8, v0
	v_cvt_pk_bf16_f32 v4, v4, s0
	ds_write_b16 v16, v4 offset:4080
	v_mul_f32_e32 v4, v56, v0
	v_cvt_pk_bf16_f32 v4, v4, s0
	ds_write_b16 v16, v4 offset:4144
	v_mul_f32_e32 v4, v40, v0
	v_mul_f32_e32 v0, v24, v0
	v_cvt_pk_bf16_f32 v0, v0, s0
	ds_write_b16 v16, v0 offset:4272
	v_rcp_f32_e32 v0, v1
	v_cvt_pk_bf16_f32 v4, v4, s0
	ds_write_b16 v16, v4 offset:4208
	v_mul_f32_e32 v1, v9, v0
	v_cvt_pk_bf16_f32 v1, v1, s0
	ds_write_b16 v16, v1 offset:4352
	v_mul_f32_e32 v1, v57, v0
	v_cvt_pk_bf16_f32 v1, v1, s0
	ds_write_b16 v16, v1 offset:4416
	v_mul_f32_e32 v1, v41, v0
	v_mul_f32_e32 v0, v25, v0
	v_cvt_pk_bf16_f32 v0, v0, s0
	ds_write_b16 v16, v0 offset:4544
	v_rcp_f32_e32 v0, v2
	v_cvt_pk_bf16_f32 v1, v1, s0
	ds_write_b16 v16, v1 offset:4480
	v_mul_f32_e32 v1, v10, v0
	v_cvt_pk_bf16_f32 v1, v1, s0
	ds_write_b16 v16, v1 offset:4624
	v_mul_f32_e32 v1, v58, v0
	v_cvt_pk_bf16_f32 v1, v1, s0
	ds_write_b16 v16, v1 offset:4688
	v_mul_f32_e32 v1, v42, v0
	v_mul_f32_e32 v0, v26, v0
	v_cvt_pk_bf16_f32 v0, v0, s0
	ds_write_b16 v16, v0 offset:4816
	v_rcp_f32_e32 v0, v3
	v_cvt_pk_bf16_f32 v1, v1, s0
	ds_write_b16 v16, v1 offset:4752
	v_mul_f32_e32 v1, v11, v0
	v_cvt_pk_bf16_f32 v1, v1, s0
	ds_write_b16 v16, v1 offset:4896
	v_mul_f32_e32 v1, v59, v0
	v_cvt_pk_bf16_f32 v1, v1, s0
	ds_write_b16 v16, v1 offset:4960
	v_mul_f32_e32 v1, v43, v0
	v_mul_f32_e32 v0, v27, v0
	v_cvt_pk_bf16_f32 v1, v1, s0
	v_cvt_pk_bf16_f32 v0, v0, s0
	ds_write_b16 v16, v1 offset:5024
	ds_write_b16 v16, v0 offset:5088
	ds_read_b128 v[0:3], v65 offset:96
	s_waitcnt lgkmcnt(0)
; __device__ __forceinline__ unsigned cvt_pk_bf16(float lo, float hi) { f32x2_t v = {lo, hi}; bf16x2_t r = __builtin_convertvector(v, bf16x2_t); return __builtin_bit_cast(unsigned, r); }
; __device__ __forceinline__ float bf_lo(unsigned w) { return __uint_as_float(w << 16); }
; __device__ __forceinline__ float bf_hi(unsigned w) { return __uint_as_float(w & 0xffff0000u); }
; __device__ __forceinline__ int crow(int r, int hi) { return (r & 3) + 8 * (r >> 2) + 4 * hi; }
; template <int MODE, int SDEPTH, bool SIMPLE>
; __device__ __forceinline__ void attn_body(const Unit& U, char* lds, const int tid) {
;     ...
;   for (int r = 0; r < 16; ++r) { const float rl = __builtin_amdgcn_rcpf(li_l[crow(r, hi)]); bf16_t* op = ol + crow(r, hi) * OP + r32;
; #pragma unroll
;     for (int d0 = 0; d0 < 4; ++d0) op[d0 * 32] = (bf16_t)(cvt_pk_bf16(o[d0][r] * rl, 0.f) & 0xffffu); }
;   asm volatile("s_waitcnt lgkmcnt(0)" ::: "memory");
;   { const int cc = (lane & 15) * 8, rb = lane >> 4;
;     u32x4 zz[8];
;     if constexpr (MODE != 2) {
; #pragma unroll
;       for (int i = 0; i < 8; ++i) zz[i] = *(const u32x4*)(U.Z + (long)(wid * QBLK + rb + 4 * i) * U.ldz + cc);
;     }
; #pragma unroll
;     for (int i = 0; i < 8; ++i) { const int row = rb + 4 * i; const long orow = wid * QBLK + row;
;       u32x4 v = *(const u32x4*)(ol + row * OP + cc);
;       if constexpr (MODE != 2) { const u32x4 z = zz[i];
; #pragma unroll
;         for (int q = 0; q < 4; ++q) v[q] = cvt_pk_bf16(bf_lo(v[q]) * bf_lo(z[q]), bf_hi(v[q]) * bf_hi(z[q])); }
;       *(u32x4*)(U.O + orow * U.ldo + cc) = v; } }
	v_rcp_f32_e32 v0, v0
	s_nop 0
	v_mul_f32_e32 v4, v12, v0
	v_cvt_pk_bf16_f32 v4, v4, s0
	ds_write_b16 v16, v4 offset:6256
	v_mul_f32_e32 v4, v60, v0
	v_cvt_pk_bf16_f32 v4, v4, s0
	ds_write_b16 v16, v4 offset:6320
	v_mul_f32_e32 v4, v44, v0
	v_mul_f32_e32 v0, v28, v0
	v_cvt_pk_bf16_f32 v0, v0, s0
	ds_write_b16 v16, v0 offset:6448
	v_rcp_f32_e32 v0, v1
	v_cvt_pk_bf16_f32 v4, v4, s0
	v_lshrrev_b32_e32 v28, 4, v181
	ds_write_b16 v16, v4 offset:6384
	v_mul_f32_e32 v1, v13, v0
	v_cvt_pk_bf16_f32 v1, v1, s0
	ds_write_b16 v16, v1 offset:6528
	v_mul_f32_e32 v1, v61, v0
	v_cvt_pk_bf16_f32 v1, v1, s0
	ds_write_b16 v16, v1 offset:6592
	v_mul_f32_e32 v1, v45, v0
	v_mul_f32_e32 v0, v29, v0
	v_cvt_pk_bf16_f32 v0, v0, s0
	ds_write_b16 v16, v0 offset:6720
	v_rcp_f32_e32 v0, v2
	v_cvt_pk_bf16_f32 v1, v1, s0
	ds_write_b16 v16, v1 offset:6656
	v_mul_f32_e32 v1, v14, v0
	v_cvt_pk_bf16_f32 v1, v1, s0
	ds_write_b16 v16, v1 offset:6800
	v_mul_f32_e32 v1, v62, v0
	v_cvt_pk_bf16_f32 v1, v1, s0
	ds_write_b16 v16, v1 offset:6864
	v_mul_f32_e32 v1, v46, v0
	v_mul_f32_e32 v0, v30, v0
	v_cvt_pk_bf16_f32 v0, v0, s0
	ds_write_b16 v16, v0 offset:6992
	v_rcp_f32_e32 v0, v3
	v_cvt_pk_bf16_f32 v1, v1, s0
	ds_write_b16 v16, v1 offset:6928
	v_or_b32_e32 v46, v28, v180
	v_mul_f32_e32 v1, v15, v0
	v_cvt_pk_bf16_f32 v1, v1, s0
	ds_write_b16 v16, v1 offset:7072
	v_mul_f32_e32 v1, v63, v0
	v_cvt_pk_bf16_f32 v1, v1, s0
	ds_write_b16 v16, v1 offset:7136
	v_mul_f32_e32 v1, v47, v0
	v_mul_f32_e32 v0, v31, v0
	v_cvt_pk_bf16_f32 v1, v1, s0
	v_cvt_pk_bf16_f32 v0, v0, s0
	ds_write_b16 v16, v1 offset:7200
	ds_write_b16 v16, v0 offset:7264
	v_lshl_add_u64 v[0:1], s[2:3], 0, v[192:193]
	s_mov_b64 s[2:3], 0x5000
	v_lshl_add_u64 v[0:1], v[0:1], 0, s[2:3]
	s_waitcnt lgkmcnt(0)
	v_mad_i64_i32 v[2:3], s[2:3], v46, s14, v[0:1]
	global_load_dwordx4 v[36:39], v[2:3], off
	v_or_b32_e32 v47, 4, v46
	v_mad_i64_i32 v[2:3], s[2:3], v47, s14, v[0:1]
	global_load_dwordx4 v[24:27], v[2:3], off
	v_or_b32_e32 v48, 8, v46
	v_mad_i64_i32 v[2:3], s[2:3], v48, s14, v[0:1]
	global_load_dwordx4 v[20:23], v[2:3], off
	v_or_b32_e32 v35, 12, v46
	v_mad_i64_i32 v[2:3], s[2:3], v35, s14, v[0:1]
	global_load_dwordx4 v[16:19], v[2:3], off
	v_or_b32_e32 v34, 16, v46
	v_mad_i64_i32 v[2:3], s[2:3], v34, s14, v[0:1]
	global_load_dwordx4 v[12:15], v[2:3], off
	v_mul_u32_u24_e32 v28, 0x110, v28
	v_or_b32_e32 v33, 20, v46
	v_add3_u32 v31, v64, v192, v28
	v_mad_i64_i32 v[2:3], s[2:3], v33, s14, v[0:1]
	ds_read_b128 v[40:43], v31
	global_load_dwordx4 v[8:11], v[2:3], off
	v_or_b32_e32 v32, 24, v46
	v_or_b32_e32 v30, 28, v46
	v_mad_i64_i32 v[2:3], s[2:3], v32, s14, v[0:1]
	s_waitcnt lgkmcnt(0)
	v_lshlrev_b32_e32 v28, 16, v40
	v_and_b32_e32 v29, 0xffff0000, v40
	v_mad_i64_i32 v[0:1], s[2:3], v30, s14, v[0:1]
	s_movk_i32 s2, 0x1400
	global_load_dwordx4 v[4:7], v[2:3], off
	s_waitcnt vmcnt(6)
	v_lshlrev_b32_e32 v44, 16, v36
	v_and_b32_e32 v45, 0xffff0000, v36
	v_pk_mul_f32 v[28:29], v[44:45], v[28:29]
	v_lshlrev_b32_e32 v40, 16, v37
	v_cvt_pk_bf16_f32 v36, v28, v29
	v_lshlrev_b32_e32 v28, 16, v41
	v_and_b32_e32 v29, 0xffff0000, v41
	v_and_b32_e32 v41, 0xffff0000, v37
	v_pk_mul_f32 v[28:29], v[40:41], v[28:29]
	v_lshlrev_b32_e32 v40, 16, v38
	v_cvt_pk_bf16_f32 v37, v28, v29
	v_lshlrev_b32_e32 v28, 16, v42
	v_and_b32_e32 v29, 0xffff0000, v42
	v_and_b32_e32 v41, 0xffff0000, v38
	v_pk_mul_f32 v[28:29], v[40:41], v[28:29]
	v_lshlrev_b32_e32 v40, 16, v39
	v_cvt_pk_bf16_f32 v38, v28, v29
	v_lshlrev_b32_e32 v28, 16, v43
	v_and_b32_e32 v29, 0xffff0000, v43
	v_and_b32_e32 v41, 0xffff0000, v39
	v_pk_mul_f32 v[28:29], v[40:41], v[28:29]
	global_load_dwordx4 v[0:3], v[0:1], off
	v_cvt_pk_bf16_f32 v39, v28, v29
	v_mov_b64_e32 v[28:29], s[0:1]
	v_mad_i64_i32 v[40:41], s[0:1], v46, s2, v[28:29]
	v_lshl_add_u64 v[40:41], v[40:41], 0, v[192:193]
	global_store_dwordx4 v[40:41], v[36:39], off offset:2048 sc1
	ds_read_b128 v[36:39], v31 offset:1088
	s_waitcnt vmcnt(7)
	v_lshlrev_b32_e32 v42, 16, v24
	v_and_b32_e32 v43, 0xffff0000, v24
	s_waitcnt lgkmcnt(0)
	v_lshlrev_b32_e32 v40, 16, v36
	v_and_b32_e32 v41, 0xffff0000, v36
	v_pk_mul_f32 v[40:41], v[42:43], v[40:41]
	v_lshlrev_b32_e32 v36, 16, v37
	v_cvt_pk_bf16_f32 v24, v40, v41
	v_and_b32_e32 v37, 0xffff0000, v37
	v_lshlrev_b32_e32 v40, 16, v25
	v_and_b32_e32 v41, 0xffff0000, v25
	v_pk_mul_f32 v[36:37], v[40:41], v[36:37]
	v_lshlrev_b32_e32 v40, 16, v26
	v_cvt_pk_bf16_f32 v25, v36, v37
	v_lshlrev_b32_e32 v36, 16, v38
	v_and_b32_e32 v37, 0xffff0000, v38
	v_and_b32_e32 v41, 0xffff0000, v26
	v_pk_mul_f32 v[36:37], v[40:41], v[36:37]
	v_lshlrev_b32_e32 v38, 16, v27
	v_cvt_pk_bf16_f32 v26, v36, v37
	v_lshlrev_b32_e32 v36, 16, v39
	v_and_b32_e32 v37, 0xffff0000, v39
	v_and_b32_e32 v39, 0xffff0000, v27
	v_pk_mul_f32 v[36:37], v[38:39], v[36:37]
	s_waitcnt vmcnt(6)
	v_lshlrev_b32_e32 v38, 16, v20
	v_cvt_pk_bf16_f32 v27, v36, v37
	v_mad_i64_i32 v[36:37], s[0:1], v47, s2, v[28:29]
	v_lshl_add_u64 v[36:37], v[36:37], 0, v[192:193]
	global_store_dwordx4 v[36:37], v[24:27], off offset:2048 sc1
	ds_read_b128 v[24:27], v31 offset:2176
	v_and_b32_e32 v39, 0xffff0000, v20
	s_waitcnt lgkmcnt(0)
	v_lshlrev_b32_e32 v36, 16, v24
	v_and_b32_e32 v37, 0xffff0000, v24
	v_pk_mul_f32 v[36:37], v[38:39], v[36:37]
	v_lshlrev_b32_e32 v24, 16, v25
	v_cvt_pk_bf16_f32 v20, v36, v37
	v_and_b32_e32 v25, 0xffff0000, v25
	v_lshlrev_b32_e32 v36, 16, v21
	v_and_b32_e32 v37, 0xffff0000, v21
	v_pk_mul_f32 v[24:25], v[36:37], v[24:25]
	v_lshlrev_b32_e32 v36, 16, v22
	v_cvt_pk_bf16_f32 v21, v24, v25
	v_lshlrev_b32_e32 v24, 16, v26
	v_and_b32_e32 v25, 0xffff0000, v26
	v_and_b32_e32 v37, 0xffff0000, v22
	v_pk_mul_f32 v[24:25], v[36:37], v[24:25]
	v_lshlrev_b32_e32 v26, 16, v23
	v_cvt_pk_bf16_f32 v22, v24, v25
	v_lshlrev_b32_e32 v24, 16, v27
	v_and_b32_e32 v25, 0xffff0000, v27
	v_and_b32_e32 v27, 0xffff0000, v23
	v_pk_mul_f32 v[24:25], v[26:27], v[24:25]
	s_waitcnt vmcnt(6)
; __device__ __forceinline__ unsigned cvt_pk_bf16(float lo, float hi) { f32x2_t v = {lo, hi}; bf16x2_t r = __builtin_convertvector(v, bf16x2_t); return __builtin_bit_cast(unsigned, r); }
; __device__ __forceinline__ float bf_lo(unsigned w) { return __uint_as_float(w << 16); }
; __device__ __forceinline__ float bf_hi(unsigned w) { return __uint_as_float(w & 0xffff0000u); }
; template <int MODE, int SDEPTH, bool SIMPLE>
; __device__ __forceinline__ void attn_body(const Unit& U, char* lds, const int tid) {
;     ...
;       for (int i = 0; i < 8; ++i) zz[i] = *(const u32x4*)(U.Z + (long)(wid * QBLK + rb + 4 * i) * U.ldz + cc);
;     }
; #pragma unroll
;     for (int i = 0; i < 8; ++i) { const int row = rb + 4 * i; const long orow = wid * QBLK + row;
;       u32x4 v = *(const u32x4*)(ol + row * OP + cc);
;       if constexpr (MODE != 2) { const u32x4 z = zz[i];
; #pragma unroll
;         for (int q = 0; q < 4; ++q) v[q] = cvt_pk_bf16(bf_lo(v[q]) * bf_lo(z[q]), bf_hi(v[q]) * bf_hi(z[q])); }
;       *(u32x4*)(U.O + orow * U.ldo + cc) = v; } }
; __global__ void __launch_bounds__(512) mega(Args a) {
;     ...
;       for (int i = 0;; ++i) {
;         const int un = i * G + cu; if (un >= NB * 8 * 32) break;
	v_lshlrev_b32_e32 v26, 16, v16
	v_cvt_pk_bf16_f32 v23, v24, v25
	v_mad_i64_i32 v[24:25], s[0:1], v48, s2, v[28:29]
	v_lshl_add_u64 v[24:25], v[24:25], 0, v[192:193]
	global_store_dwordx4 v[24:25], v[20:23], off offset:2048 sc1
	ds_read_b128 v[20:23], v31 offset:3264
	v_and_b32_e32 v27, 0xffff0000, v16
	s_waitcnt lgkmcnt(0)
	v_lshlrev_b32_e32 v24, 16, v20
	v_and_b32_e32 v25, 0xffff0000, v20
	v_pk_mul_f32 v[24:25], v[26:27], v[24:25]
	v_lshlrev_b32_e32 v20, 16, v21
	v_cvt_pk_bf16_f32 v16, v24, v25
	v_and_b32_e32 v21, 0xffff0000, v21
	v_lshlrev_b32_e32 v24, 16, v17
	v_and_b32_e32 v25, 0xffff0000, v17
	v_pk_mul_f32 v[20:21], v[24:25], v[20:21]
	v_lshlrev_b32_e32 v24, 16, v18
	v_cvt_pk_bf16_f32 v17, v20, v21
	v_lshlrev_b32_e32 v20, 16, v22
	v_and_b32_e32 v21, 0xffff0000, v22
	v_and_b32_e32 v25, 0xffff0000, v18
	v_pk_mul_f32 v[20:21], v[24:25], v[20:21]
	v_lshlrev_b32_e32 v22, 16, v19
	v_cvt_pk_bf16_f32 v18, v20, v21
	v_lshlrev_b32_e32 v20, 16, v23
	v_and_b32_e32 v21, 0xffff0000, v23
	v_and_b32_e32 v23, 0xffff0000, v19
	v_pk_mul_f32 v[20:21], v[22:23], v[20:21]
	s_waitcnt vmcnt(6)
	v_lshlrev_b32_e32 v22, 16, v12
	v_cvt_pk_bf16_f32 v19, v20, v21
	v_mad_i64_i32 v[20:21], s[0:1], v35, s2, v[28:29]
	v_lshl_add_u64 v[20:21], v[20:21], 0, v[192:193]
	global_store_dwordx4 v[20:21], v[16:19], off offset:2048 sc1
	ds_read_b128 v[16:19], v31 offset:4352
	v_and_b32_e32 v23, 0xffff0000, v12
	s_waitcnt lgkmcnt(0)
	v_lshlrev_b32_e32 v20, 16, v16
	v_and_b32_e32 v21, 0xffff0000, v16
	v_pk_mul_f32 v[20:21], v[22:23], v[20:21]
	v_lshlrev_b32_e32 v16, 16, v17
	v_cvt_pk_bf16_f32 v12, v20, v21
	v_and_b32_e32 v17, 0xffff0000, v17
	v_lshlrev_b32_e32 v20, 16, v13
	v_and_b32_e32 v21, 0xffff0000, v13
	v_pk_mul_f32 v[16:17], v[20:21], v[16:17]
	v_lshlrev_b32_e32 v20, 16, v14
	v_cvt_pk_bf16_f32 v13, v16, v17
	v_lshlrev_b32_e32 v16, 16, v18
	v_and_b32_e32 v17, 0xffff0000, v18
	v_and_b32_e32 v21, 0xffff0000, v14
	v_pk_mul_f32 v[16:17], v[20:21], v[16:17]
	v_lshlrev_b32_e32 v18, 16, v15
	v_cvt_pk_bf16_f32 v14, v16, v17
	v_lshlrev_b32_e32 v16, 16, v19
	v_and_b32_e32 v17, 0xffff0000, v19
	v_and_b32_e32 v19, 0xffff0000, v15
	v_pk_mul_f32 v[16:17], v[18:19], v[16:17]
	s_waitcnt vmcnt(6)
	v_lshlrev_b32_e32 v18, 16, v8
	v_cvt_pk_bf16_f32 v15, v16, v17
	v_mad_i64_i32 v[16:17], s[0:1], v34, s2, v[28:29]
	v_lshl_add_u64 v[16:17], v[16:17], 0, v[192:193]
	global_store_dwordx4 v[16:17], v[12:15], off offset:2048 sc1
	ds_read_b128 v[12:15], v31 offset:5440
	v_and_b32_e32 v19, 0xffff0000, v8
	s_waitcnt lgkmcnt(0)
	v_lshlrev_b32_e32 v16, 16, v12
	v_and_b32_e32 v17, 0xffff0000, v12
	v_pk_mul_f32 v[16:17], v[18:19], v[16:17]
	v_lshlrev_b32_e32 v12, 16, v13
	v_cvt_pk_bf16_f32 v8, v16, v17
	v_and_b32_e32 v13, 0xffff0000, v13
	v_lshlrev_b32_e32 v16, 16, v9
	v_and_b32_e32 v17, 0xffff0000, v9
	v_pk_mul_f32 v[12:13], v[16:17], v[12:13]
	v_lshlrev_b32_e32 v16, 16, v10
	v_cvt_pk_bf16_f32 v9, v12, v13
	v_lshlrev_b32_e32 v12, 16, v14
	v_and_b32_e32 v13, 0xffff0000, v14
	v_and_b32_e32 v17, 0xffff0000, v10
	v_pk_mul_f32 v[12:13], v[16:17], v[12:13]
	v_lshlrev_b32_e32 v14, 16, v11
	v_cvt_pk_bf16_f32 v10, v12, v13
	v_lshlrev_b32_e32 v12, 16, v15
	v_and_b32_e32 v13, 0xffff0000, v15
	v_and_b32_e32 v15, 0xffff0000, v11
	v_pk_mul_f32 v[12:13], v[14:15], v[12:13]
	s_waitcnt vmcnt(6)
	v_lshlrev_b32_e32 v14, 16, v4
	v_cvt_pk_bf16_f32 v11, v12, v13
	v_mad_i64_i32 v[12:13], s[0:1], v33, s2, v[28:29]
	v_lshl_add_u64 v[12:13], v[12:13], 0, v[192:193]
	global_store_dwordx4 v[12:13], v[8:11], off offset:2048 sc1
	ds_read_b128 v[8:11], v31 offset:6528
	v_and_b32_e32 v15, 0xffff0000, v4
	s_waitcnt lgkmcnt(0)
	v_lshlrev_b32_e32 v12, 16, v8
	v_and_b32_e32 v13, 0xffff0000, v8
	v_pk_mul_f32 v[12:13], v[14:15], v[12:13]
	v_lshlrev_b32_e32 v8, 16, v9
	v_cvt_pk_bf16_f32 v4, v12, v13
	v_and_b32_e32 v9, 0xffff0000, v9
	v_lshlrev_b32_e32 v12, 16, v5
	v_and_b32_e32 v13, 0xffff0000, v5
	v_pk_mul_f32 v[8:9], v[12:13], v[8:9]
	v_lshlrev_b32_e32 v12, 16, v6
	v_cvt_pk_bf16_f32 v5, v8, v9
	v_lshlrev_b32_e32 v8, 16, v10
	v_and_b32_e32 v9, 0xffff0000, v10
	v_and_b32_e32 v13, 0xffff0000, v6
	v_pk_mul_f32 v[8:9], v[12:13], v[8:9]
	v_lshlrev_b32_e32 v10, 16, v7
	v_cvt_pk_bf16_f32 v6, v8, v9
	v_lshlrev_b32_e32 v8, 16, v11
	v_and_b32_e32 v9, 0xffff0000, v11
	v_and_b32_e32 v11, 0xffff0000, v7
	v_pk_mul_f32 v[8:9], v[10:11], v[8:9]
	s_waitcnt vmcnt(6)
	v_lshlrev_b32_e32 v10, 16, v0
	v_cvt_pk_bf16_f32 v7, v8, v9
	v_mad_i64_i32 v[8:9], s[0:1], v32, s2, v[28:29]
	v_lshl_add_u64 v[8:9], v[8:9], 0, v[192:193]
	global_store_dwordx4 v[8:9], v[4:7], off offset:2048 sc1
	ds_read_b128 v[4:7], v31 offset:7616
	v_and_b32_e32 v11, 0xffff0000, v0
	s_waitcnt lgkmcnt(0)
	v_lshlrev_b32_e32 v8, 16, v4
	v_and_b32_e32 v9, 0xffff0000, v4
	v_pk_mul_f32 v[8:9], v[10:11], v[8:9]
	v_lshlrev_b32_e32 v4, 16, v5
	v_cvt_pk_bf16_f32 v0, v8, v9
	v_and_b32_e32 v5, 0xffff0000, v5
	v_lshlrev_b32_e32 v8, 16, v1
	v_and_b32_e32 v9, 0xffff0000, v1
	v_pk_mul_f32 v[4:5], v[8:9], v[4:5]
	v_lshlrev_b32_e32 v8, 16, v2
	v_cvt_pk_bf16_f32 v1, v4, v5
	v_lshlrev_b32_e32 v4, 16, v6
	v_and_b32_e32 v5, 0xffff0000, v6
	v_and_b32_e32 v9, 0xffff0000, v2
	v_pk_mul_f32 v[4:5], v[8:9], v[4:5]
	v_lshlrev_b32_e32 v6, 16, v3
	v_cvt_pk_bf16_f32 v2, v4, v5
	v_lshlrev_b32_e32 v4, 16, v7
	v_and_b32_e32 v5, 0xffff0000, v7
	v_and_b32_e32 v7, 0xffff0000, v3
	v_pk_mul_f32 v[4:5], v[6:7], v[4:5]
	s_nop 0
	v_cvt_pk_bf16_f32 v3, v4, v5
	v_mad_i64_i32 v[4:5], s[0:1], v30, s2, v[28:29]
	s_mul_i32 s0, s62, s56
	s_add_i32 s0, s0, s57
	v_lshl_add_u64 v[4:5], v[4:5], 0, v[192:193]
	s_cmpk_gt_i32 s0, 0x1ff
	global_store_dwordx4 v[4:5], v[0:3], off offset:2048 sc1
	s_cbranch_scc1 .LBB0_217

; __device__ __forceinline__ unsigned cvt_pk_bf16(float lo, float hi) { f32x2_t v = {lo, hi}; bf16x2_t r = __builtin_convertvector(v, bf16x2_t); return __builtin_bit_cast(unsigned, r); }
; __device__ __forceinline__ int crow(int r, int hi) { return (r & 3) + 8 * (r >> 2) + 4 * hi; }
; template <int MODE, int SDEPTH, bool SIMPLE>
; __device__ __forceinline__ void attn_body(const Unit& U, char* lds, const int tid) {
;     ...
;   if (hi == 0) li_l[r32] = l_reg; asm volatile("s_waitcnt lgkmcnt(0)" ::: "memory");
;   if constexpr (MODE == 2) { if (hi == 0) U.LSE[(long)(wid * QBLK + r32) * U.ldl] = m_reg * SCALE + __logf(l_reg); }
;   __syncthreads();
;   constexpr int OP = 136;
;   bf16_t* ol = (bf16_t*)lds + wid * (32 * OP);
; #pragma unroll
;   for (int r = 0; r < 16; ++r) { const float rl = __builtin_amdgcn_rcpf(li_l[crow(r, hi)]); bf16_t* op = ol + crow(r, hi) * OP + r32;
; #pragma unroll
;     for (int d0 = 0; d0 < 4; ++d0) op[d0 * 32] = (bf16_t)(cvt_pk_bf16(o[d0][r] * rl, 0.f) & 0xffffu); }
;   asm volatile("s_waitcnt lgkmcnt(0)" ::: "memory");
.LBB0_281:
	s_or_b64 exec, exec, s[0:1]
	v_lshl_add_u32 v65, v156, 4, v157
	s_waitcnt lgkmcnt(0)
	s_waitcnt lgkmcnt(0)
	s_barrier
	ds_read_b128 v[66:69], v65
	s_mul_i32 s0, s3, 0x1400
	s_mul_hi_u32 s1, s20, 0x1400
	s_add_i32 s1, s1, s0
	s_mulk_i32 s20, 0x1400
	s_waitcnt lgkmcnt(0)
	v_rcp_f32_e32 v66, v66
	v_readlane_b32 s0, v250, 0
	s_movk_i32 s4, 0x2200
	s_add_u32 s0, s0, s20
	v_mul_lo_u32 v64, v158, s4
	s_addc_u32 s1, s19, s1
	s_lshl_b32 s2, s27, 1
	v_add_u32_e32 v64, 0, v64
	s_add_u32 s0, s0, s2
	v_lshl_add_u32 v70, v159, 1, v64
	s_movk_i32 s4, 0x440
	v_mul_f32_e32 v0, v0, v66
	v_mad_u32_u24 v71, v156, s4, v70
	v_cvt_pk_bf16_f32 v0, v0, s0
	ds_write_b16 v71, v0
	v_mul_f32_e32 v0, v48, v66
	v_cvt_pk_bf16_f32 v0, v0, s0
	ds_write_b16 v71, v0 offset:64
	v_mul_f32_e32 v0, v32, v66
	v_cvt_pk_bf16_f32 v0, v0, s0
	v_rcp_f32_e32 v32, v67
	ds_write_b16 v71, v0 offset:128
	v_mul_f32_e32 v0, v16, v66
	v_cvt_pk_bf16_f32 v0, v0, s0
	ds_write_b16 v71, v0 offset:192
	v_lshl_or_b32 v0, v156, 2, 1
	s_movk_i32 s4, 0x110
	v_mad_u32_u24 v16, v0, s4, v70
	v_mul_f32_e32 v0, v1, v32
	v_cvt_pk_bf16_f32 v0, v0, s0
	ds_write_b16 v16, v0
	v_mul_f32_e32 v0, v49, v32
	v_cvt_pk_bf16_f32 v0, v0, s0
	ds_write_b16 v16, v0 offset:64
	v_mul_f32_e32 v0, v33, v32
	v_cvt_pk_bf16_f32 v0, v0, s0
	ds_write_b16 v16, v0 offset:128
	v_mul_f32_e32 v0, v17, v32
	v_cvt_pk_bf16_f32 v0, v0, s0
	ds_write_b16 v16, v0 offset:192
	v_rcp_f32_e32 v0, v68
	s_addc_u32 s1, s1, 0
	s_add_u32 s2, s26, s2
	s_addc_u32 s3, s24, 0
	v_mul_f32_e32 v1, v2, v0
	v_cvt_pk_bf16_f32 v1, v1, s0
	ds_write_b16 v16, v1 offset:272
	v_mul_f32_e32 v1, v50, v0
	v_cvt_pk_bf16_f32 v1, v1, s0
	ds_write_b16 v16, v1 offset:336
	v_mul_f32_e32 v1, v34, v0
	v_mul_f32_e32 v0, v18, v0
	v_cvt_pk_bf16_f32 v0, v0, s0
	ds_write_b16 v16, v0 offset:464
	v_rcp_f32_e32 v0, v69
	v_cvt_pk_bf16_f32 v1, v1, s0
	ds_write_b16 v16, v1 offset:400
	s_add_i32 s21, s21, s16
	v_mul_f32_e32 v1, v3, v0
	v_cvt_pk_bf16_f32 v1, v1, s0
	ds_write_b16 v16, v1 offset:544
	v_mul_f32_e32 v1, v51, v0
	v_cvt_pk_bf16_f32 v1, v1, s0
	ds_write_b16 v16, v1 offset:608
	v_mul_f32_e32 v1, v35, v0
	v_mul_f32_e32 v0, v19, v0
	v_cvt_pk_bf16_f32 v1, v1, s0
	v_cvt_pk_bf16_f32 v0, v0, s0
	ds_write_b16 v16, v1 offset:672
	ds_write_b16 v16, v0 offset:736
	ds_read_b128 v[0:3], v65 offset:32
	s_movk_i32 s69, 0x1400
	s_waitcnt lgkmcnt(0)
	v_rcp_f32_e32 v0, v0
	s_nop 0
	v_mul_f32_e32 v4, v4, v0
	v_cvt_pk_bf16_f32 v4, v4, s0
	ds_write_b16 v16, v4 offset:1904
	v_mul_f32_e32 v4, v52, v0
	v_cvt_pk_bf16_f32 v4, v4, s0
	ds_write_b16 v16, v4 offset:1968
	v_mul_f32_e32 v4, v36, v0
	v_mul_f32_e32 v0, v20, v0
	v_cvt_pk_bf16_f32 v0, v0, s0
	ds_write_b16 v16, v0 offset:2096
	v_rcp_f32_e32 v0, v1
	v_cvt_pk_bf16_f32 v4, v4, s0
	ds_write_b16 v16, v4 offset:2032
	v_mul_f32_e32 v1, v5, v0
	v_cvt_pk_bf16_f32 v1, v1, s0
	ds_write_b16 v16, v1 offset:2176
	v_mul_f32_e32 v1, v53, v0
	v_cvt_pk_bf16_f32 v1, v1, s0
	ds_write_b16 v16, v1 offset:2240
	v_mul_f32_e32 v1, v37, v0
	v_mul_f32_e32 v0, v21, v0
	v_cvt_pk_bf16_f32 v0, v0, s0
	ds_write_b16 v16, v0 offset:2368
	v_rcp_f32_e32 v0, v2
	v_cvt_pk_bf16_f32 v1, v1, s0
	ds_write_b16 v16, v1 offset:2304
	v_mul_f32_e32 v1, v6, v0
	v_cvt_pk_bf16_f32 v1, v1, s0
	ds_write_b16 v16, v1 offset:2448
	v_mul_f32_e32 v1, v54, v0
	v_cvt_pk_bf16_f32 v1, v1, s0
	ds_write_b16 v16, v1 offset:2512
	v_mul_f32_e32 v1, v38, v0
	v_mul_f32_e32 v0, v22, v0
	v_cvt_pk_bf16_f32 v0, v0, s0
	ds_write_b16 v16, v0 offset:2640
	v_rcp_f32_e32 v0, v3
	v_cvt_pk_bf16_f32 v1, v1, s0
	ds_write_b16 v16, v1 offset:2576
	v_mul_f32_e32 v1, v7, v0
	v_cvt_pk_bf16_f32 v1, v1, s0
	ds_write_b16 v16, v1 offset:2720
	v_mul_f32_e32 v1, v55, v0
	v_cvt_pk_bf16_f32 v1, v1, s0
	ds_write_b16 v16, v1 offset:2784
	v_mul_f32_e32 v1, v39, v0
	v_mul_f32_e32 v0, v23, v0
	v_cvt_pk_bf16_f32 v1, v1, s0
	v_cvt_pk_bf16_f32 v0, v0, s0
	ds_write_b16 v16, v1 offset:2848
	ds_write_b16 v16, v0 offset:2912
	ds_read_b128 v[0:3], v65 offset:64
	s_waitcnt lgkmcnt(0)
	v_rcp_f32_e32 v0, v0
	s_nop 0
	v_mul_f32_e32 v4, v8, v0
	v_cvt_pk_bf16_f32 v4, v4, s0
	ds_write_b16 v16, v4 offset:4080
	v_mul_f32_e32 v4, v56, v0
	v_cvt_pk_bf16_f32 v4, v4, s0
	ds_write_b16 v16, v4 offset:4144
	v_mul_f32_e32 v4, v40, v0
	v_mul_f32_e32 v0, v24, v0
	v_cvt_pk_bf16_f32 v0, v0, s0
	ds_write_b16 v16, v0 offset:4272
	v_rcp_f32_e32 v0, v1
	v_cvt_pk_bf16_f32 v4, v4, s0
	ds_write_b16 v16, v4 offset:4208
	v_mul_f32_e32 v1, v9, v0
	v_cvt_pk_bf16_f32 v1, v1, s0
	ds_write_b16 v16, v1 offset:4352
	v_mul_f32_e32 v1, v57, v0
	v_cvt_pk_bf16_f32 v1, v1, s0
	ds_write_b16 v16, v1 offset:4416
	v_mul_f32_e32 v1, v41, v0
	v_mul_f32_e32 v0, v25, v0
	v_cvt_pk_bf16_f32 v0, v0, s0
	ds_write_b16 v16, v0 offset:4544
	v_rcp_f32_e32 v0, v2
	v_cvt_pk_bf16_f32 v1, v1, s0
	ds_write_b16 v16, v1 offset:4480
	v_mul_f32_e32 v1, v10, v0
	v_cvt_pk_bf16_f32 v1, v1, s0
	ds_write_b16 v16, v1 offset:4624
	v_mul_f32_e32 v1, v58, v0
	v_cvt_pk_bf16_f32 v1, v1, s0
	ds_write_b16 v16, v1 offset:4688
	v_mul_f32_e32 v1, v42, v0
	v_mul_f32_e32 v0, v26, v0
	v_cvt_pk_bf16_f32 v0, v0, s0
	ds_write_b16 v16, v0 offset:4816
	v_rcp_f32_e32 v0, v3
	v_cvt_pk_bf16_f32 v1, v1, s0
	ds_write_b16 v16, v1 offset:4752
	v_mul_f32_e32 v1, v11, v0
	v_cvt_pk_bf16_f32 v1, v1, s0
	ds_write_b16 v16, v1 offset:4896
	v_mul_f32_e32 v1, v59, v0
	v_cvt_pk_bf16_f32 v1, v1, s0
	ds_write_b16 v16, v1 offset:4960
	v_mul_f32_e32 v1, v43, v0
	v_mul_f32_e32 v0, v27, v0
	v_cvt_pk_bf16_f32 v1, v1, s0
	v_cvt_pk_bf16_f32 v0, v0, s0
	ds_write_b16 v16, v1 offset:5024
	ds_write_b16 v16, v0 offset:5088
	ds_read_b128 v[0:3], v65 offset:96
	s_waitcnt lgkmcnt(0)
; __device__ __forceinline__ unsigned cvt_pk_bf16(float lo, float hi) { f32x2_t v = {lo, hi}; bf16x2_t r = __builtin_convertvector(v, bf16x2_t); return __builtin_bit_cast(unsigned, r); }
; __device__ __forceinline__ float bf_lo(unsigned w) { return __uint_as_float(w << 16); }
; __device__ __forceinline__ float bf_hi(unsigned w) { return __uint_as_float(w & 0xffff0000u); }
; __device__ __forceinline__ int crow(int r, int hi) { return (r & 3) + 8 * (r >> 2) + 4 * hi; }
; template <int MODE, int SDEPTH, bool SIMPLE>
; __device__ __forceinline__ void attn_body(const Unit& U, char* lds, const int tid) {
;     ...
;   for (int r = 0; r < 16; ++r) { const float rl = __builtin_amdgcn_rcpf(li_l[crow(r, hi)]); bf16_t* op = ol + crow(r, hi) * OP + r32;
; #pragma unroll
;     for (int d0 = 0; d0 < 4; ++d0) op[d0 * 32] = (bf16_t)(cvt_pk_bf16(o[d0][r] * rl, 0.f) & 0xffffu); }
;   asm volatile("s_waitcnt lgkmcnt(0)" ::: "memory");
;   { const int cc = (lane & 15) * 8, rb = lane >> 4;
;     u32x4 zz[8];
;     if constexpr (MODE != 2) {
; #pragma unroll
;       for (int i = 0; i < 8; ++i) zz[i] = *(const u32x4*)(U.Z + (long)(wid * QBLK + rb + 4 * i) * U.ldz + cc);
;     }
; #pragma unroll
;     for (int i = 0; i < 8; ++i) { const int row = rb + 4 * i; const long orow = wid * QBLK + row;
;       u32x4 v = *(const u32x4*)(ol + row * OP + cc);
;       if constexpr (MODE != 2) { const u32x4 z = zz[i];
; #pragma unroll
;         for (int q = 0; q < 4; ++q) v[q] = cvt_pk_bf16(bf_lo(v[q]) * bf_lo(z[q]), bf_hi(v[q]) * bf_hi(z[q])); }
;       *(u32x4*)(U.O + orow * U.ldo + cc) = v; } }
	v_rcp_f32_e32 v0, v0
	s_nop 0
	v_mul_f32_e32 v4, v12, v0
	v_cvt_pk_bf16_f32 v4, v4, s0
	ds_write_b16 v16, v4 offset:6256
	v_mul_f32_e32 v4, v60, v0
	v_cvt_pk_bf16_f32 v4, v4, s0
	ds_write_b16 v16, v4 offset:6320
	v_mul_f32_e32 v4, v44, v0
	v_mul_f32_e32 v0, v28, v0
	v_cvt_pk_bf16_f32 v0, v0, s0
	ds_write_b16 v16, v0 offset:6448
	v_rcp_f32_e32 v0, v1
	v_cvt_pk_bf16_f32 v4, v4, s0
	v_lshrrev_b32_e32 v28, 4, v154
	ds_write_b16 v16, v4 offset:6384
	v_mul_f32_e32 v1, v13, v0
	v_cvt_pk_bf16_f32 v1, v1, s0
	ds_write_b16 v16, v1 offset:6528
	v_mul_f32_e32 v1, v61, v0
	v_cvt_pk_bf16_f32 v1, v1, s0
	ds_write_b16 v16, v1 offset:6592
	v_mul_f32_e32 v1, v45, v0
	v_mul_f32_e32 v0, v29, v0
	v_cvt_pk_bf16_f32 v0, v0, s0
	ds_write_b16 v16, v0 offset:6720
	v_rcp_f32_e32 v0, v2
	v_cvt_pk_bf16_f32 v1, v1, s0
	ds_write_b16 v16, v1 offset:6656
	v_mul_f32_e32 v1, v14, v0
	v_cvt_pk_bf16_f32 v1, v1, s0
	ds_write_b16 v16, v1 offset:6800
	v_mul_f32_e32 v1, v62, v0
	v_cvt_pk_bf16_f32 v1, v1, s0
	ds_write_b16 v16, v1 offset:6864
	v_mul_f32_e32 v1, v46, v0
	v_mul_f32_e32 v0, v30, v0
	v_cvt_pk_bf16_f32 v0, v0, s0
	ds_write_b16 v16, v0 offset:6992
	v_rcp_f32_e32 v0, v3
	v_cvt_pk_bf16_f32 v1, v1, s0
	ds_write_b16 v16, v1 offset:6928
	v_or_b32_e32 v46, v28, v155
	v_mul_f32_e32 v1, v15, v0
	v_cvt_pk_bf16_f32 v1, v1, s0
	ds_write_b16 v16, v1 offset:7072
	v_mul_f32_e32 v1, v63, v0
	v_cvt_pk_bf16_f32 v1, v1, s0
	ds_write_b16 v16, v1 offset:7136
	v_mul_f32_e32 v1, v47, v0
	v_mul_f32_e32 v0, v31, v0
	v_cvt_pk_bf16_f32 v1, v1, s0
	v_cvt_pk_bf16_f32 v0, v0, s0
	ds_write_b16 v16, v1 offset:7200
	ds_write_b16 v16, v0 offset:7264
	v_lshl_add_u64 v[0:1], s[2:3], 0, v[192:193]
	s_mov_b64 s[2:3], 0x4800
	v_lshl_add_u64 v[0:1], v[0:1], 0, s[2:3]
	s_waitcnt lgkmcnt(0)
	v_mad_i64_i32 v[2:3], s[2:3], v46, s14, v[0:1]
	global_load_dwordx4 v[36:39], v[2:3], off
	v_or_b32_e32 v47, 4, v46
	v_mad_i64_i32 v[2:3], s[2:3], v47, s14, v[0:1]
	global_load_dwordx4 v[24:27], v[2:3], off
	v_or_b32_e32 v48, 8, v46
	v_mad_i64_i32 v[2:3], s[2:3], v48, s14, v[0:1]
	global_load_dwordx4 v[20:23], v[2:3], off
	v_or_b32_e32 v35, 12, v46
	v_mad_i64_i32 v[2:3], s[2:3], v35, s14, v[0:1]
	global_load_dwordx4 v[16:19], v[2:3], off
	v_or_b32_e32 v34, 16, v46
	v_mad_i64_i32 v[2:3], s[2:3], v34, s14, v[0:1]
	global_load_dwordx4 v[12:15], v[2:3], off
	v_mul_u32_u24_e32 v28, 0x110, v28
	v_or_b32_e32 v33, 20, v46
	v_add3_u32 v31, v64, v192, v28
	v_mad_i64_i32 v[2:3], s[2:3], v33, s14, v[0:1]
	ds_read_b128 v[40:43], v31
	global_load_dwordx4 v[8:11], v[2:3], off
	v_or_b32_e32 v32, 24, v46
	v_or_b32_e32 v30, 28, v46
	v_mad_i64_i32 v[2:3], s[2:3], v32, s14, v[0:1]
	s_waitcnt lgkmcnt(0)
	v_lshlrev_b32_e32 v28, 16, v40
	v_and_b32_e32 v29, 0xffff0000, v40
	v_mad_i64_i32 v[0:1], s[2:3], v30, s14, v[0:1]
	s_movk_i32 s2, 0x1400
	global_load_dwordx4 v[4:7], v[2:3], off
	s_waitcnt vmcnt(6)
	v_lshlrev_b32_e32 v44, 16, v36
	v_and_b32_e32 v45, 0xffff0000, v36
	v_pk_mul_f32 v[28:29], v[44:45], v[28:29]
	v_lshlrev_b32_e32 v40, 16, v37
	v_cvt_pk_bf16_f32 v36, v28, v29
	v_lshlrev_b32_e32 v28, 16, v41
	v_and_b32_e32 v29, 0xffff0000, v41
	v_and_b32_e32 v41, 0xffff0000, v37
	v_pk_mul_f32 v[28:29], v[40:41], v[28:29]
	v_lshlrev_b32_e32 v40, 16, v38
	v_cvt_pk_bf16_f32 v37, v28, v29
	v_lshlrev_b32_e32 v28, 16, v42
	v_and_b32_e32 v29, 0xffff0000, v42
	v_and_b32_e32 v41, 0xffff0000, v38
	v_pk_mul_f32 v[28:29], v[40:41], v[28:29]
	v_lshlrev_b32_e32 v40, 16, v39
	v_cvt_pk_bf16_f32 v38, v28, v29
	v_lshlrev_b32_e32 v28, 16, v43
	v_and_b32_e32 v29, 0xffff0000, v43
	v_and_b32_e32 v41, 0xffff0000, v39
	v_pk_mul_f32 v[28:29], v[40:41], v[28:29]
	global_load_dwordx4 v[0:3], v[0:1], off
	v_cvt_pk_bf16_f32 v39, v28, v29
	v_mov_b64_e32 v[28:29], s[0:1]
	v_mad_i64_i32 v[40:41], s[0:1], v46, s2, v[28:29]
	v_lshl_add_u64 v[40:41], v[40:41], 0, v[192:193]
	global_store_dwordx4 v[40:41], v[36:39], off sc1
	ds_read_b128 v[36:39], v31 offset:1088
	s_waitcnt vmcnt(7)
	v_lshlrev_b32_e32 v42, 16, v24
	v_and_b32_e32 v43, 0xffff0000, v24
	s_waitcnt lgkmcnt(0)
	v_lshlrev_b32_e32 v40, 16, v36
	v_and_b32_e32 v41, 0xffff0000, v36
	v_pk_mul_f32 v[40:41], v[42:43], v[40:41]
	v_lshlrev_b32_e32 v36, 16, v37
	v_cvt_pk_bf16_f32 v24, v40, v41
	v_and_b32_e32 v37, 0xffff0000, v37
	v_lshlrev_b32_e32 v40, 16, v25
	v_and_b32_e32 v41, 0xffff0000, v25
	v_pk_mul_f32 v[36:37], v[40:41], v[36:37]
	v_lshlrev_b32_e32 v40, 16, v26
	v_cvt_pk_bf16_f32 v25, v36, v37
	v_lshlrev_b32_e32 v36, 16, v38
	v_and_b32_e32 v37, 0xffff0000, v38
	v_and_b32_e32 v41, 0xffff0000, v26
	v_pk_mul_f32 v[36:37], v[40:41], v[36:37]
	v_lshlrev_b32_e32 v38, 16, v27
	v_cvt_pk_bf16_f32 v26, v36, v37
	v_lshlrev_b32_e32 v36, 16, v39
	v_and_b32_e32 v37, 0xffff0000, v39
	v_and_b32_e32 v39, 0xffff0000, v27
	v_pk_mul_f32 v[36:37], v[38:39], v[36:37]
	s_waitcnt vmcnt(6)
	v_lshlrev_b32_e32 v38, 16, v20
	v_cvt_pk_bf16_f32 v27, v36, v37
	v_mad_i64_i32 v[36:37], s[0:1], v47, s2, v[28:29]
	v_lshl_add_u64 v[36:37], v[36:37], 0, v[192:193]
	global_store_dwordx4 v[36:37], v[24:27], off sc1
	ds_read_b128 v[24:27], v31 offset:2176
	v_and_b32_e32 v39, 0xffff0000, v20
	s_waitcnt lgkmcnt(0)
	v_lshlrev_b32_e32 v36, 16, v24
	v_and_b32_e32 v37, 0xffff0000, v24
	v_pk_mul_f32 v[36:37], v[38:39], v[36:37]
	v_lshlrev_b32_e32 v24, 16, v25
	v_cvt_pk_bf16_f32 v20, v36, v37
	v_and_b32_e32 v25, 0xffff0000, v25
	v_lshlrev_b32_e32 v36, 16, v21
	v_and_b32_e32 v37, 0xffff0000, v21
	v_pk_mul_f32 v[24:25], v[36:37], v[24:25]
	v_lshlrev_b32_e32 v36, 16, v22
	v_cvt_pk_bf16_f32 v21, v24, v25
	v_lshlrev_b32_e32 v24, 16, v26
	v_and_b32_e32 v25, 0xffff0000, v26
	v_and_b32_e32 v37, 0xffff0000, v22
	v_pk_mul_f32 v[24:25], v[36:37], v[24:25]
	v_lshlrev_b32_e32 v26, 16, v23
	v_cvt_pk_bf16_f32 v22, v24, v25
	v_lshlrev_b32_e32 v24, 16, v27
	v_and_b32_e32 v25, 0xffff0000, v27
	v_and_b32_e32 v27, 0xffff0000, v23
	v_pk_mul_f32 v[24:25], v[26:27], v[24:25]
	s_waitcnt vmcnt(6)
; __device__ __forceinline__ unsigned cvt_pk_bf16(float lo, float hi) { f32x2_t v = {lo, hi}; bf16x2_t r = __builtin_convertvector(v, bf16x2_t); return __builtin_bit_cast(unsigned, r); }
; __device__ __forceinline__ float bf_lo(unsigned w) { return __uint_as_float(w << 16); }
; __device__ __forceinline__ float bf_hi(unsigned w) { return __uint_as_float(w & 0xffff0000u); }
; template <int MODE, int SDEPTH, bool SIMPLE>
; __device__ __forceinline__ void attn_body(const Unit& U, char* lds, const int tid) {
;     ...
;       for (int i = 0; i < 8; ++i) zz[i] = *(const u32x4*)(U.Z + (long)(wid * QBLK + rb + 4 * i) * U.ldz + cc);
;     }
; #pragma unroll
;     for (int i = 0; i < 8; ++i) { const int row = rb + 4 * i; const long orow = wid * QBLK + row;
;       u32x4 v = *(const u32x4*)(ol + row * OP + cc);
;       if constexpr (MODE != 2) { const u32x4 z = zz[i];
; #pragma unroll
;         for (int q = 0; q < 4; ++q) v[q] = cvt_pk_bf16(bf_lo(v[q]) * bf_lo(z[q]), bf_hi(v[q]) * bf_hi(z[q])); }
;       *(u32x4*)(U.O + orow * U.ldo + cc) = v; } }
; __global__ void __launch_bounds__(512) mega(Args a) {
;     ...
;       if (P2MASK & 2) for (int un = cu; un < NB * 8 * 32; un += G) {
	v_lshlrev_b32_e32 v26, 16, v16
	v_cvt_pk_bf16_f32 v23, v24, v25
	v_mad_i64_i32 v[24:25], s[0:1], v48, s2, v[28:29]
	v_lshl_add_u64 v[24:25], v[24:25], 0, v[192:193]
	global_store_dwordx4 v[24:25], v[20:23], off sc1
	ds_read_b128 v[20:23], v31 offset:3264
	v_and_b32_e32 v27, 0xffff0000, v16
	s_waitcnt lgkmcnt(0)
	v_lshlrev_b32_e32 v24, 16, v20
	v_and_b32_e32 v25, 0xffff0000, v20
	v_pk_mul_f32 v[24:25], v[26:27], v[24:25]
	v_lshlrev_b32_e32 v20, 16, v21
	v_cvt_pk_bf16_f32 v16, v24, v25
	v_and_b32_e32 v21, 0xffff0000, v21
	v_lshlrev_b32_e32 v24, 16, v17
	v_and_b32_e32 v25, 0xffff0000, v17
	v_pk_mul_f32 v[20:21], v[24:25], v[20:21]
	v_lshlrev_b32_e32 v24, 16, v18
	v_cvt_pk_bf16_f32 v17, v20, v21
	v_lshlrev_b32_e32 v20, 16, v22
	v_and_b32_e32 v21, 0xffff0000, v22
	v_and_b32_e32 v25, 0xffff0000, v18
	v_pk_mul_f32 v[20:21], v[24:25], v[20:21]
	v_lshlrev_b32_e32 v22, 16, v19
	v_cvt_pk_bf16_f32 v18, v20, v21
	v_lshlrev_b32_e32 v20, 16, v23
	v_and_b32_e32 v21, 0xffff0000, v23
	v_and_b32_e32 v23, 0xffff0000, v19
	v_pk_mul_f32 v[20:21], v[22:23], v[20:21]
	s_waitcnt vmcnt(6)
	v_lshlrev_b32_e32 v22, 16, v12
	v_cvt_pk_bf16_f32 v19, v20, v21
	v_mad_i64_i32 v[20:21], s[0:1], v35, s2, v[28:29]
	v_lshl_add_u64 v[20:21], v[20:21], 0, v[192:193]
	global_store_dwordx4 v[20:21], v[16:19], off sc1
	ds_read_b128 v[16:19], v31 offset:4352
	v_and_b32_e32 v23, 0xffff0000, v12
	s_waitcnt lgkmcnt(0)
	v_lshlrev_b32_e32 v20, 16, v16
	v_and_b32_e32 v21, 0xffff0000, v16
	v_pk_mul_f32 v[20:21], v[22:23], v[20:21]
	v_lshlrev_b32_e32 v16, 16, v17
	v_cvt_pk_bf16_f32 v12, v20, v21
	v_and_b32_e32 v17, 0xffff0000, v17
	v_lshlrev_b32_e32 v20, 16, v13
	v_and_b32_e32 v21, 0xffff0000, v13
	v_pk_mul_f32 v[16:17], v[20:21], v[16:17]
	v_lshlrev_b32_e32 v20, 16, v14
	v_cvt_pk_bf16_f32 v13, v16, v17
	v_lshlrev_b32_e32 v16, 16, v18
	v_and_b32_e32 v17, 0xffff0000, v18
	v_and_b32_e32 v21, 0xffff0000, v14
	v_pk_mul_f32 v[16:17], v[20:21], v[16:17]
	v_lshlrev_b32_e32 v18, 16, v15
	v_cvt_pk_bf16_f32 v14, v16, v17
	v_lshlrev_b32_e32 v16, 16, v19
	v_and_b32_e32 v17, 0xffff0000, v19
	v_and_b32_e32 v19, 0xffff0000, v15
	v_pk_mul_f32 v[16:17], v[18:19], v[16:17]
	s_waitcnt vmcnt(6)
	v_lshlrev_b32_e32 v18, 16, v8
	v_cvt_pk_bf16_f32 v15, v16, v17
	v_mad_i64_i32 v[16:17], s[0:1], v34, s2, v[28:29]
	v_lshl_add_u64 v[16:17], v[16:17], 0, v[192:193]
	global_store_dwordx4 v[16:17], v[12:15], off sc1
	ds_read_b128 v[12:15], v31 offset:5440
	v_and_b32_e32 v19, 0xffff0000, v8
	s_waitcnt lgkmcnt(0)
	v_lshlrev_b32_e32 v16, 16, v12
	v_and_b32_e32 v17, 0xffff0000, v12
	v_pk_mul_f32 v[16:17], v[18:19], v[16:17]
	v_lshlrev_b32_e32 v12, 16, v13
	v_cvt_pk_bf16_f32 v8, v16, v17
	v_and_b32_e32 v13, 0xffff0000, v13
	v_lshlrev_b32_e32 v16, 16, v9
	v_and_b32_e32 v17, 0xffff0000, v9
	v_pk_mul_f32 v[12:13], v[16:17], v[12:13]
	v_lshlrev_b32_e32 v16, 16, v10
	v_cvt_pk_bf16_f32 v9, v12, v13
	v_lshlrev_b32_e32 v12, 16, v14
	v_and_b32_e32 v13, 0xffff0000, v14
	v_and_b32_e32 v17, 0xffff0000, v10
	v_pk_mul_f32 v[12:13], v[16:17], v[12:13]
	v_lshlrev_b32_e32 v14, 16, v11
	v_cvt_pk_bf16_f32 v10, v12, v13
	v_lshlrev_b32_e32 v12, 16, v15
	v_and_b32_e32 v13, 0xffff0000, v15
	v_and_b32_e32 v15, 0xffff0000, v11
	v_pk_mul_f32 v[12:13], v[14:15], v[12:13]
	s_waitcnt vmcnt(6)
	v_lshlrev_b32_e32 v14, 16, v4
	v_cvt_pk_bf16_f32 v11, v12, v13
	v_mad_i64_i32 v[12:13], s[0:1], v33, s2, v[28:29]
	v_lshl_add_u64 v[12:13], v[12:13], 0, v[192:193]
	global_store_dwordx4 v[12:13], v[8:11], off sc1
	ds_read_b128 v[8:11], v31 offset:6528
	v_and_b32_e32 v15, 0xffff0000, v4
	s_waitcnt lgkmcnt(0)
	v_lshlrev_b32_e32 v12, 16, v8
	v_and_b32_e32 v13, 0xffff0000, v8
	v_pk_mul_f32 v[12:13], v[14:15], v[12:13]
	v_lshlrev_b32_e32 v8, 16, v9
	v_cvt_pk_bf16_f32 v4, v12, v13
	v_and_b32_e32 v9, 0xffff0000, v9
	v_lshlrev_b32_e32 v12, 16, v5
	v_and_b32_e32 v13, 0xffff0000, v5
	v_pk_mul_f32 v[8:9], v[12:13], v[8:9]
	v_lshlrev_b32_e32 v12, 16, v6
	v_cvt_pk_bf16_f32 v5, v8, v9
	v_lshlrev_b32_e32 v8, 16, v10
	v_and_b32_e32 v9, 0xffff0000, v10
	v_and_b32_e32 v13, 0xffff0000, v6
	v_pk_mul_f32 v[8:9], v[12:13], v[8:9]
	v_lshlrev_b32_e32 v10, 16, v7
	v_cvt_pk_bf16_f32 v6, v8, v9
	v_lshlrev_b32_e32 v8, 16, v11
	v_and_b32_e32 v9, 0xffff0000, v11
	v_and_b32_e32 v11, 0xffff0000, v7
	v_pk_mul_f32 v[8:9], v[10:11], v[8:9]
	s_waitcnt vmcnt(6)
	v_lshlrev_b32_e32 v10, 16, v0
	v_cvt_pk_bf16_f32 v7, v8, v9
	v_mad_i64_i32 v[8:9], s[0:1], v32, s2, v[28:29]
	v_lshl_add_u64 v[8:9], v[8:9], 0, v[192:193]
	global_store_dwordx4 v[8:9], v[4:7], off sc1
	ds_read_b128 v[4:7], v31 offset:7616
	v_and_b32_e32 v11, 0xffff0000, v0
	s_waitcnt lgkmcnt(0)
	v_lshlrev_b32_e32 v8, 16, v4
	v_and_b32_e32 v9, 0xffff0000, v4
	v_pk_mul_f32 v[8:9], v[10:11], v[8:9]
	v_lshlrev_b32_e32 v4, 16, v5
	v_cvt_pk_bf16_f32 v0, v8, v9
	v_and_b32_e32 v5, 0xffff0000, v5
	v_lshlrev_b32_e32 v8, 16, v1
	v_and_b32_e32 v9, 0xffff0000, v1
	v_pk_mul_f32 v[4:5], v[8:9], v[4:5]
	v_lshlrev_b32_e32 v8, 16, v2
	v_cvt_pk_bf16_f32 v1, v4, v5
	v_lshlrev_b32_e32 v4, 16, v6
	v_and_b32_e32 v5, 0xffff0000, v6
	v_and_b32_e32 v9, 0xffff0000, v2
	v_pk_mul_f32 v[4:5], v[8:9], v[4:5]
	v_lshlrev_b32_e32 v6, 16, v3
	v_cvt_pk_bf16_f32 v2, v4, v5
	v_lshlrev_b32_e32 v4, 16, v7
	v_and_b32_e32 v5, 0xffff0000, v7
	v_and_b32_e32 v7, 0xffff0000, v3
	v_pk_mul_f32 v[4:5], v[6:7], v[4:5]
	s_nop 0
	v_cvt_pk_bf16_f32 v3, v4, v5
	v_mad_i64_i32 v[4:5], s[0:1], v30, s2, v[28:29]
	v_readlane_b32 s0, v251, 63
	s_add_i32 s17, s17, s0
	v_lshl_add_u64 v[4:5], v[4:5], 0, v[192:193]
	s_cmpk_gt_i32 s17, 0x1ff
	global_store_dwordx4 v[4:5], v[0:3], off sc1
	s_cbranch_scc1 .LBB0_298

; __device__ __forceinline__ unsigned cvt_pk_bf16(float lo, float hi) { f32x2_t v = {lo, hi}; bf16x2_t r = __builtin_convertvector(v, bf16x2_t); return __builtin_bit_cast(unsigned, r); }
; __device__ __forceinline__ int crow(int r, int hi) { return (r & 3) + 8 * (r >> 2) + 4 * hi; }
; template <int MODE, int SDEPTH, bool SIMPLE>
; __device__ __forceinline__ void attn_body(const Unit& U, char* lds, const int tid) {
;     ...
;   if (hi == 0) li_l[r32] = l_reg; asm volatile("s_waitcnt lgkmcnt(0)" ::: "memory");
;   if constexpr (MODE == 2) { if (hi == 0) U.LSE[(long)(wid * QBLK + r32) * U.ldl] = m_reg * SCALE + __logf(l_reg); }
;   __syncthreads();
;   constexpr int OP = 136;
;   bf16_t* ol = (bf16_t*)lds + wid * (32 * OP);
; #pragma unroll
;   for (int r = 0; r < 16; ++r) { const float rl = __builtin_amdgcn_rcpf(li_l[crow(r, hi)]); bf16_t* op = ol + crow(r, hi) * OP + r32;
; #pragma unroll
;     for (int d0 = 0; d0 < 4; ++d0) op[d0 * 32] = (bf16_t)(cvt_pk_bf16(o[d0][r] * rl, 0.f) & 0xffffu); }
;   asm volatile("s_waitcnt lgkmcnt(0)" ::: "memory");
.LBB0_300:
	s_or_b64 exec, exec, s[36:37]
	v_lshl_add_u32 v65, v155, 4, v156
	s_waitcnt lgkmcnt(0)
	s_barrier
	ds_read_b128 v[66:69], v65
	s_lshl_b64 s[0:1], s[2:3], 10
	s_add_u32 s0, s16, s0
	s_addc_u32 s1, s17, s1
	s_lshl_b32 s2, s27, 8
	s_waitcnt lgkmcnt(0)
	v_rcp_f32_e32 v66, v66
	s_add_u32 s0, s0, s2
	s_movk_i32 s2, 0x2200
	v_mul_lo_u32 v64, v157, s2
	v_add_u32_e32 v64, 0, v64
	v_lshl_add_u32 v70, v158, 1, v64
	s_movk_i32 s2, 0x440
	v_mul_f32_e32 v0, v0, v66
	v_mad_u32_u24 v71, v155, s2, v70
	v_cvt_pk_bf16_f32 v0, v0, s0
	ds_write_b16 v71, v0
	v_mul_f32_e32 v0, v48, v66
	v_cvt_pk_bf16_f32 v0, v0, s0
	ds_write_b16 v71, v0 offset:64
	v_mul_f32_e32 v0, v32, v66
	v_cvt_pk_bf16_f32 v0, v0, s0
	v_rcp_f32_e32 v32, v67
	ds_write_b16 v71, v0 offset:128
	v_mul_f32_e32 v0, v16, v66
	v_cvt_pk_bf16_f32 v0, v0, s0
	ds_write_b16 v71, v0 offset:192
	v_lshl_or_b32 v0, v155, 2, 1
	s_movk_i32 s2, 0x110
	v_mad_u32_u24 v16, v0, s2, v70
	v_mul_f32_e32 v0, v1, v32
	v_cvt_pk_bf16_f32 v0, v0, s0
	ds_write_b16 v16, v0
	v_mul_f32_e32 v0, v49, v32
	v_cvt_pk_bf16_f32 v0, v0, s0
	ds_write_b16 v16, v0 offset:64
	v_mul_f32_e32 v0, v33, v32
	v_cvt_pk_bf16_f32 v0, v0, s0
	ds_write_b16 v16, v0 offset:128
	v_mul_f32_e32 v0, v17, v32
	v_cvt_pk_bf16_f32 v0, v0, s0
	ds_write_b16 v16, v0 offset:192
	v_rcp_f32_e32 v0, v68
	s_addc_u32 s1, s1, 0
	s_and_b64 s[2:3], s[4:5], exec
	s_cselect_b32 s4, 11, 13
	v_mul_f32_e32 v1, v2, v0
	v_cvt_pk_bf16_f32 v1, v1, s0
	ds_write_b16 v16, v1 offset:272
	v_mul_f32_e32 v1, v50, v0
	v_cvt_pk_bf16_f32 v1, v1, s0
	ds_write_b16 v16, v1 offset:336
	v_mul_f32_e32 v1, v34, v0
	v_mul_f32_e32 v0, v18, v0
	v_cvt_pk_bf16_f32 v0, v0, s0
	ds_write_b16 v16, v0 offset:464
	v_rcp_f32_e32 v0, v69
	v_cvt_pk_bf16_f32 v1, v1, s0
	ds_write_b16 v16, v1 offset:400
	s_and_b64 s[2:3], s[8:9], exec
	v_mul_f32_e32 v1, v3, v0
	v_cvt_pk_bf16_f32 v1, v1, s0
	ds_write_b16 v16, v1 offset:544
	v_mul_f32_e32 v1, v51, v0
	v_cvt_pk_bf16_f32 v1, v1, s0
	ds_write_b16 v16, v1 offset:608
	v_mul_f32_e32 v1, v35, v0
	v_mul_f32_e32 v0, v19, v0
	v_cvt_pk_bf16_f32 v1, v1, s0
	v_cvt_pk_bf16_f32 v0, v0, s0
	ds_write_b16 v16, v1 offset:672
	ds_write_b16 v16, v0 offset:736
	ds_read_b128 v[0:3], v65 offset:32
	s_cselect_b32 s2, 9, s4
	s_add_i32 s21, s21, s23
	s_waitcnt lgkmcnt(0)
	v_rcp_f32_e32 v0, v0
	s_nop 0
	v_mul_f32_e32 v4, v4, v0
	v_cvt_pk_bf16_f32 v4, v4, s0
	ds_write_b16 v16, v4 offset:1904
	v_mul_f32_e32 v4, v52, v0
	v_cvt_pk_bf16_f32 v4, v4, s0
	ds_write_b16 v16, v4 offset:1968
	v_mul_f32_e32 v4, v36, v0
	v_mul_f32_e32 v0, v20, v0
	v_cvt_pk_bf16_f32 v0, v0, s0
	ds_write_b16 v16, v0 offset:2096
	v_rcp_f32_e32 v0, v1
	v_cvt_pk_bf16_f32 v4, v4, s0
	ds_write_b16 v16, v4 offset:2032
	v_mul_f32_e32 v1, v5, v0
	v_cvt_pk_bf16_f32 v1, v1, s0
	ds_write_b16 v16, v1 offset:2176
	v_mul_f32_e32 v1, v53, v0
	v_cvt_pk_bf16_f32 v1, v1, s0
	ds_write_b16 v16, v1 offset:2240
	v_mul_f32_e32 v1, v37, v0
	v_mul_f32_e32 v0, v21, v0
	v_cvt_pk_bf16_f32 v0, v0, s0
	ds_write_b16 v16, v0 offset:2368
	v_rcp_f32_e32 v0, v2
	v_cvt_pk_bf16_f32 v1, v1, s0
	ds_write_b16 v16, v1 offset:2304
	v_mul_f32_e32 v1, v6, v0
	v_cvt_pk_bf16_f32 v1, v1, s0
	ds_write_b16 v16, v1 offset:2448
	v_mul_f32_e32 v1, v54, v0
	v_cvt_pk_bf16_f32 v1, v1, s0
	ds_write_b16 v16, v1 offset:2512
	v_mul_f32_e32 v1, v38, v0
	v_mul_f32_e32 v0, v22, v0
	v_cvt_pk_bf16_f32 v0, v0, s0
	ds_write_b16 v16, v0 offset:2640
	v_rcp_f32_e32 v0, v3
	v_cvt_pk_bf16_f32 v1, v1, s0
	ds_write_b16 v16, v1 offset:2576
	v_mul_f32_e32 v1, v7, v0
	v_cvt_pk_bf16_f32 v1, v1, s0
	ds_write_b16 v16, v1 offset:2720
	v_mul_f32_e32 v1, v55, v0
	v_cvt_pk_bf16_f32 v1, v1, s0
	ds_write_b16 v16, v1 offset:2784
	v_mul_f32_e32 v1, v39, v0
	v_mul_f32_e32 v0, v23, v0
	v_cvt_pk_bf16_f32 v1, v1, s0
	v_cvt_pk_bf16_f32 v0, v0, s0
	ds_write_b16 v16, v1 offset:2848
	ds_write_b16 v16, v0 offset:2912
	ds_read_b128 v[0:3], v65 offset:64
	s_waitcnt lgkmcnt(0)
	v_rcp_f32_e32 v0, v0
	s_nop 0
	v_mul_f32_e32 v4, v8, v0
	v_cvt_pk_bf16_f32 v4, v4, s0
	ds_write_b16 v16, v4 offset:4080
	v_mul_f32_e32 v4, v56, v0
	v_cvt_pk_bf16_f32 v4, v4, s0
	ds_write_b16 v16, v4 offset:4144
	v_mul_f32_e32 v4, v40, v0
	v_mul_f32_e32 v0, v24, v0
	v_cvt_pk_bf16_f32 v0, v0, s0
	ds_write_b16 v16, v0 offset:4272
	v_rcp_f32_e32 v0, v1
	v_cvt_pk_bf16_f32 v4, v4, s0
	ds_write_b16 v16, v4 offset:4208
	v_mul_f32_e32 v1, v9, v0
	v_cvt_pk_bf16_f32 v1, v1, s0
	ds_write_b16 v16, v1 offset:4352
	v_mul_f32_e32 v1, v57, v0
	v_cvt_pk_bf16_f32 v1, v1, s0
	ds_write_b16 v16, v1 offset:4416
	v_mul_f32_e32 v1, v41, v0
	v_mul_f32_e32 v0, v25, v0
	v_cvt_pk_bf16_f32 v0, v0, s0
	ds_write_b16 v16, v0 offset:4544
	v_rcp_f32_e32 v0, v2
	v_cvt_pk_bf16_f32 v1, v1, s0
	ds_write_b16 v16, v1 offset:4480
	v_mul_f32_e32 v1, v10, v0
	v_cvt_pk_bf16_f32 v1, v1, s0
	ds_write_b16 v16, v1 offset:4624
	v_mul_f32_e32 v1, v58, v0
	v_cvt_pk_bf16_f32 v1, v1, s0
	ds_write_b16 v16, v1 offset:4688
	v_mul_f32_e32 v1, v42, v0
	v_mul_f32_e32 v0, v26, v0
	v_cvt_pk_bf16_f32 v0, v0, s0
	ds_write_b16 v16, v0 offset:4816
	v_rcp_f32_e32 v0, v3
	v_cvt_pk_bf16_f32 v1, v1, s0
	ds_write_b16 v16, v1 offset:4752
	v_mul_f32_e32 v1, v11, v0
	v_cvt_pk_bf16_f32 v1, v1, s0
	ds_write_b16 v16, v1 offset:4896
	v_mul_f32_e32 v1, v59, v0
	v_cvt_pk_bf16_f32 v1, v1, s0
	ds_write_b16 v16, v1 offset:4960
	v_mul_f32_e32 v1, v43, v0
	v_mul_f32_e32 v0, v27, v0
	v_cvt_pk_bf16_f32 v1, v1, s0
	v_cvt_pk_bf16_f32 v0, v0, s0
	ds_write_b16 v16, v1 offset:5024
	ds_write_b16 v16, v0 offset:5088
	ds_read_b128 v[0:3], v65 offset:96
	s_waitcnt lgkmcnt(0)
; __device__ __forceinline__ unsigned cvt_pk_bf16(float lo, float hi) { f32x2_t v = {lo, hi}; bf16x2_t r = __builtin_convertvector(v, bf16x2_t); return __builtin_bit_cast(unsigned, r); }
; __device__ __forceinline__ float bf_lo(unsigned w) { return __uint_as_float(w << 16); }
; __device__ __forceinline__ float bf_hi(unsigned w) { return __uint_as_float(w & 0xffff0000u); }
; template <int MODE, int SDEPTH, bool SIMPLE>
; __device__ __forceinline__ void attn_body(const Unit& U, char* lds, const int tid) {
;     ...
; #pragma unroll
;     for (int i = 0; i < 8; ++i) { const int row = rb + 4 * i; const long orow = wid * QBLK + row;
;       u32x4 v = *(const u32x4*)(ol + row * OP + cc);
;       if constexpr (MODE != 2) { const u32x4 z = zz[i];
; #pragma unroll
;         for (int q = 0; q < 4; ++q) v[q] = cvt_pk_bf16(bf_lo(v[q]) * bf_lo(z[q]), bf_hi(v[q]) * bf_hi(z[q])); }
;       *(u32x4*)(U.O + orow * U.ldo + cc) = v; } }
; __global__ void __launch_bounds__(512) mega(Args a) {
;     ...
;       if (P2MASK & 4) for (int un = cu; un < 3 * NB * 4 * 32; un += G) {
	v_rcp_f32_e32 v0, v0
	s_nop 0
	v_mul_f32_e32 v4, v12, v0
	v_cvt_pk_bf16_f32 v4, v4, s0
	ds_write_b16 v16, v4 offset:6256
	v_mul_f32_e32 v4, v60, v0
	v_cvt_pk_bf16_f32 v4, v4, s0
	ds_write_b16 v16, v4 offset:6320
	v_mul_f32_e32 v4, v44, v0
	v_mul_f32_e32 v0, v28, v0
	v_cvt_pk_bf16_f32 v0, v0, s0
	ds_write_b16 v16, v0 offset:6448
	v_rcp_f32_e32 v0, v1
	v_cvt_pk_bf16_f32 v4, v4, s0
	ds_write_b16 v16, v4 offset:6384
	v_mul_f32_e32 v1, v13, v0
	v_cvt_pk_bf16_f32 v1, v1, s0
	ds_write_b16 v16, v1 offset:6528
	v_mul_f32_e32 v1, v61, v0
	v_cvt_pk_bf16_f32 v1, v1, s0
	ds_write_b16 v16, v1 offset:6592
	v_mul_f32_e32 v1, v45, v0
	v_mul_f32_e32 v0, v29, v0
	v_cvt_pk_bf16_f32 v0, v0, s0
	ds_write_b16 v16, v0 offset:6720
	v_rcp_f32_e32 v0, v2
	v_cvt_pk_bf16_f32 v1, v1, s0
	ds_write_b16 v16, v1 offset:6656
	v_mul_f32_e32 v1, v14, v0
	v_cvt_pk_bf16_f32 v1, v1, s0
	ds_write_b16 v16, v1 offset:6800
	v_mul_f32_e32 v1, v62, v0
	v_cvt_pk_bf16_f32 v1, v1, s0
	ds_write_b16 v16, v1 offset:6864
	v_mul_f32_e32 v1, v46, v0
	v_mul_f32_e32 v0, v30, v0
	v_cvt_pk_bf16_f32 v0, v0, s0
	ds_write_b16 v16, v0 offset:6992
	v_rcp_f32_e32 v0, v3
	v_cvt_pk_bf16_f32 v1, v1, s0
	ds_write_b16 v16, v1 offset:6928
	v_mul_f32_e32 v1, v15, v0
	v_cvt_pk_bf16_f32 v1, v1, s0
	ds_write_b16 v16, v1 offset:7072
	v_mul_f32_e32 v1, v63, v0
	v_cvt_pk_bf16_f32 v1, v1, s0
	ds_write_b16 v16, v1 offset:7136
	v_mul_f32_e32 v1, v47, v0
	v_mul_f32_e32 v0, v31, v0
	v_cvt_pk_bf16_f32 v0, v0, s0
	v_cvt_pk_bf16_f32 v1, v1, s0
	ds_write_b16 v16, v0 offset:7264
	v_lshrrev_b32_e32 v0, 4, v147
	ds_write_b16 v16, v1 offset:7200
	v_or_b32_e32 v4, v0, v154
	v_mul_u32_u24_e32 v0, 0x110, v0
	s_waitcnt lgkmcnt(0)
	v_add3_u32 v8, v64, v192, v0
	ds_read_b128 v[0:3], v8
	v_ashrrev_i32_e32 v5, 31, v4
	v_lshlrev_b64 v[6:7], s2, v[4:5]
	v_lshl_add_u64 v[6:7], v[6:7], 1, s[0:1]
	v_lshl_add_u64 v[6:7], v[6:7], 0, v[192:193]
	s_waitcnt lgkmcnt(0)
	global_store_dwordx4 v[6:7], v[0:3], off sc1
	v_or_b32_e32 v6, 4, v4
	ds_read_b128 v[0:3], v8 offset:1088
	v_ashrrev_i32_e32 v7, 31, v6
	v_lshlrev_b64 v[6:7], s2, v[6:7]
	v_lshl_add_u64 v[6:7], v[6:7], 1, s[0:1]
	v_lshl_add_u64 v[6:7], v[6:7], 0, v[192:193]
	s_waitcnt lgkmcnt(0)
	global_store_dwordx4 v[6:7], v[0:3], off sc1
	v_or_b32_e32 v6, 8, v4
	ds_read_b128 v[0:3], v8 offset:2176
	v_ashrrev_i32_e32 v7, 31, v6
	v_lshlrev_b64 v[6:7], s2, v[6:7]
	v_lshl_add_u64 v[6:7], v[6:7], 1, s[0:1]
	v_lshl_add_u64 v[6:7], v[6:7], 0, v[192:193]
	s_waitcnt lgkmcnt(0)
	global_store_dwordx4 v[6:7], v[0:3], off sc1
	v_or_b32_e32 v6, 12, v4
	ds_read_b128 v[0:3], v8 offset:3264
	v_ashrrev_i32_e32 v7, 31, v6
	v_lshlrev_b64 v[6:7], s2, v[6:7]
	v_lshl_add_u64 v[6:7], v[6:7], 1, s[0:1]
	v_lshl_add_u64 v[6:7], v[6:7], 0, v[192:193]
	s_waitcnt lgkmcnt(0)
	global_store_dwordx4 v[6:7], v[0:3], off sc1
	v_or_b32_e32 v6, 16, v4
	ds_read_b128 v[0:3], v8 offset:4352
	v_ashrrev_i32_e32 v7, 31, v6
	v_lshlrev_b64 v[6:7], s2, v[6:7]
	v_lshl_add_u64 v[6:7], v[6:7], 1, s[0:1]
	v_lshl_add_u64 v[6:7], v[6:7], 0, v[192:193]
	s_waitcnt lgkmcnt(0)
	global_store_dwordx4 v[6:7], v[0:3], off sc1
	v_or_b32_e32 v6, 20, v4
	ds_read_b128 v[0:3], v8 offset:5440
	v_ashrrev_i32_e32 v7, 31, v6
	v_lshlrev_b64 v[6:7], s2, v[6:7]
	v_lshl_add_u64 v[6:7], v[6:7], 1, s[0:1]
	v_lshl_add_u64 v[6:7], v[6:7], 0, v[192:193]
	s_waitcnt lgkmcnt(0)
	global_store_dwordx4 v[6:7], v[0:3], off sc1
	v_or_b32_e32 v6, 24, v4
	ds_read_b128 v[0:3], v8 offset:6528
	v_ashrrev_i32_e32 v7, 31, v6
	v_lshlrev_b64 v[6:7], s2, v[6:7]
	v_lshl_add_u64 v[6:7], v[6:7], 1, s[0:1]
	v_lshl_add_u64 v[6:7], v[6:7], 0, v[192:193]
	v_or_b32_e32 v4, 28, v4
	s_waitcnt lgkmcnt(0)
	global_store_dwordx4 v[6:7], v[0:3], off sc1
	v_ashrrev_i32_e32 v5, 31, v4
	ds_read_b128 v[0:3], v8 offset:7616
	v_lshlrev_b64 v[4:5], s2, v[4:5]
	v_lshl_add_u64 v[4:5], v[4:5], 1, s[0:1]
	v_readlane_b32 s0, v251, 63
	s_add_i32 s22, s22, s0
	v_lshl_add_u64 v[4:5], v[4:5], 0, v[192:193]
	s_cmpk_gt_i32 s22, 0x2ff
	s_waitcnt lgkmcnt(0)
	global_store_dwordx4 v[4:5], v[0:3], off sc1
	s_cbranch_scc1 .LBB0_317

; __device__ __forceinline__ unsigned cvt_pk_bf16(float lo, float hi) { f32x2_t v = {lo, hi}; bf16x2_t r = __builtin_convertvector(v, bf16x2_t); return __builtin_bit_cast(unsigned, r); }
; __device__ __forceinline__ float sigmoidf_(float v) { return __builtin_amdgcn_rcpf(1.0f + __builtin_amdgcn_exp2f(-1.4426950408889634f * v)); }
;     __device__ __forceinline__ void operator()(const f32x4 (&acc)[2][2][4][2], const Unit& u, int wr, int wc, int fr, int fq) const {
;     ...
; #pragma unroll
;         for (int ai = 0; ai < 2; ++ai)
; #pragma unroll
;             for (int m = 0; m < 4; ++m) { bf16_t* rowp = O + (size_t)(row0 + ai * HALF + m * 16) * NIN + col0;
; #pragma unroll
;                 for (int bj = 0; bj < 2; ++bj) { f32x4 v0 = acc[ai][bj][m][0], v1 = acc[ai][bj][m][1];
;                     if (mode != 0) {
; #pragma unroll
;                         for (int j = 0; j < 4; ++j) { v0[j] *= sigmoidf_(v0[j]); v1[j] *= sigmoidf_(v1[j]); }
;                     }
;                     u32x4 w; w.x = cvt_pk_bf16(v0[0], v0[1]); w.y = cvt_pk_bf16(v0[2], v0[3]); w.z = cvt_pk_bf16(v1[0], v1[1]); w.w = cvt_pk_bf16(v1[2], v1[3]);
;                     *(u32x4*)(rowp + bj * HALF) = w; } }
.LBB0_355:
	s_lshl_b32 s11, s44, 8
	s_add_i32 s11, s11, s54
	v_add_u32_e32 v141, s11, v154
	v_mov_b64_e32 v[138:139], s[4:5]
	v_ashrrev_i32_e32 v137, 31, v136
	v_mad_i64_i32 v[138:139], s[20:21], v141, s14, v[138:139]
	v_lshl_add_u64 v[138:139], v[136:137], 1, v[138:139]
	v_cvt_pk_bf16_f32 v128, v128, v129
	v_cvt_pk_bf16_f32 v129, v130, v131
	v_cvt_pk_bf16_f32 v130, v132, v133
	v_cvt_pk_bf16_f32 v131, v134, v135
	global_store_dwordx4 v[138:139], v[128:131], off sc1
	v_mov_b64_e32 v[134:135], v[114:115]
	s_andn2_b64 vcc, exec, s[2:3]
	v_cndmask_b32_e64 v128, 0, 1, s[2:3]
	v_cmp_ne_u32_e64 s[38:39], 1, v128
	v_mov_b64_e32 v[130:131], v[118:119]
	v_mov_b64_e32 v[128:129], v[116:117]
	v_mov_b64_e32 v[132:133], v[112:113]
	s_cbranch_vccnz .LBB0_357
	v_mul_f32_e32 v129, 0xbfb8aa3b, v112
	v_mul_f32_e32 v130, 0xbfb8aa3b, v117
	v_exp_f32_e32 v129, v129
	v_exp_f32_e32 v130, v130
	v_mul_f32_e32 v131, 0xbfb8aa3b, v118
	v_mul_f32_e32 v133, 0xbfb8aa3b, v114
	v_add_f32_e32 v129, 1.0, v129
	v_rcp_f32_e32 v132, v129
	v_add_f32_e32 v129, 1.0, v130
	v_mul_f32_e32 v130, 0xbfb8aa3b, v113
	v_exp_f32_e32 v130, v130
	v_exp_f32_e32 v131, v131
	v_exp_f32_e32 v133, v133
	v_mul_f32_e32 v128, 0xbfb8aa3b, v116
	v_add_f32_e32 v142, 1.0, v130
	v_add_f32_e32 v130, 1.0, v131
	v_add_f32_e32 v131, 1.0, v133
	v_mul_f32_e32 v133, 0xbfb8aa3b, v119
	v_mul_f32_e32 v134, 0xbfb8aa3b, v115
	v_exp_f32_e32 v128, v128
	v_exp_f32_e32 v133, v133
	v_exp_f32_e32 v135, v134
	v_rcp_f32_e32 v134, v131
	v_add_f32_e32 v128, 1.0, v128
	v_add_f32_e32 v131, 1.0, v133
	v_add_f32_e32 v133, 1.0, v135
	v_rcp_f32_e32 v128, v128
	v_rcp_f32_e32 v129, v129
	v_rcp_f32_e32 v130, v130
	v_rcp_f32_e32 v131, v131
	v_rcp_f32_e32 v135, v133
	v_rcp_f32_e32 v133, v142
	v_pk_mul_f32 v[128:129], v[116:117], v[128:129]
	v_pk_mul_f32 v[130:131], v[118:119], v[130:131]
	v_pk_mul_f32 v[134:135], v[114:115], v[134:135]
	v_pk_mul_f32 v[132:133], v[112:113], v[132:133]
.LBB0_357:
	v_cvt_pk_bf16_f32 v128, v128, v129
	v_cvt_pk_bf16_f32 v129, v130, v131
	v_cvt_pk_bf16_f32 v130, v132, v133
	v_cvt_pk_bf16_f32 v131, v134, v135
	global_store_dwordx4 v[138:139], v[128:131], off offset:256 sc1
	v_mov_b64_e32 v[134:135], v[106:107]
	s_and_b64 vcc, exec, s[38:39]
	v_mov_b64_e32 v[130:131], v[110:111]
	v_mov_b64_e32 v[128:129], v[108:109]
	v_mov_b64_e32 v[132:133], v[104:105]
	s_cbranch_vccnz .LBB0_359
	v_mul_f32_e32 v129, 0xbfb8aa3b, v104
	v_mul_f32_e32 v130, 0xbfb8aa3b, v109
	v_exp_f32_e32 v129, v129
	v_exp_f32_e32 v130, v130
	v_mul_f32_e32 v131, 0xbfb8aa3b, v110
	v_mul_f32_e32 v133, 0xbfb8aa3b, v106
	v_add_f32_e32 v129, 1.0, v129
	v_rcp_f32_e32 v132, v129
	v_add_f32_e32 v129, 1.0, v130
	v_mul_f32_e32 v130, 0xbfb8aa3b, v105
	v_exp_f32_e32 v130, v130
	v_exp_f32_e32 v131, v131
	v_exp_f32_e32 v133, v133
	v_mul_f32_e32 v128, 0xbfb8aa3b, v108
	v_add_f32_e32 v138, 1.0, v130
	v_add_f32_e32 v130, 1.0, v131
	v_add_f32_e32 v131, 1.0, v133
	v_mul_f32_e32 v133, 0xbfb8aa3b, v111
	v_mul_f32_e32 v134, 0xbfb8aa3b, v107
	v_exp_f32_e32 v128, v128
	v_exp_f32_e32 v133, v133
	v_exp_f32_e32 v135, v134
	v_rcp_f32_e32 v134, v131
	v_add_f32_e32 v128, 1.0, v128
	v_add_f32_e32 v131, 1.0, v133
	v_add_f32_e32 v133, 1.0, v135
	v_rcp_f32_e32 v128, v128
	v_rcp_f32_e32 v129, v129
	v_rcp_f32_e32 v130, v130
	v_rcp_f32_e32 v131, v131
	v_rcp_f32_e32 v135, v133
	v_rcp_f32_e32 v133, v138
	v_pk_mul_f32 v[128:129], v[108:109], v[128:129]
	v_pk_mul_f32 v[130:131], v[110:111], v[130:131]
	v_pk_mul_f32 v[134:135], v[106:107], v[134:135]
	v_pk_mul_f32 v[132:133], v[104:105], v[132:133]
.LBB0_359:
	v_add_u32_e32 v142, 16, v141
	v_mov_b64_e32 v[138:139], s[4:5]
	v_mad_i64_i32 v[138:139], s[2:3], v142, s14, v[138:139]
	v_lshl_add_u64 v[138:139], v[136:137], 1, v[138:139]
	v_cvt_pk_bf16_f32 v128, v128, v129
	v_cvt_pk_bf16_f32 v129, v130, v131
	v_cvt_pk_bf16_f32 v130, v132, v133
	v_cvt_pk_bf16_f32 v131, v134, v135
	global_store_dwordx4 v[138:139], v[128:131], off sc1
	v_mov_b64_e32 v[134:135], v[98:99]
	s_and_b64 vcc, exec, s[38:39]
	v_mov_b64_e32 v[130:131], v[102:103]
	v_mov_b64_e32 v[128:129], v[100:101]
	v_mov_b64_e32 v[132:133], v[96:97]
	s_cbranch_vccnz .LBB0_361
	v_mul_f32_e32 v129, 0xbfb8aa3b, v96
	v_mul_f32_e32 v130, 0xbfb8aa3b, v101
	v_exp_f32_e32 v129, v129
	v_exp_f32_e32 v130, v130
	v_mul_f32_e32 v131, 0xbfb8aa3b, v102
	v_mul_f32_e32 v133, 0xbfb8aa3b, v98
	v_add_f32_e32 v129, 1.0, v129
	v_rcp_f32_e32 v132, v129
	v_add_f32_e32 v129, 1.0, v130
	v_mul_f32_e32 v130, 0xbfb8aa3b, v97
	v_exp_f32_e32 v130, v130
	v_exp_f32_e32 v131, v131
	v_exp_f32_e32 v133, v133
	v_mul_f32_e32 v128, 0xbfb8aa3b, v100
	v_add_f32_e32 v142, 1.0, v130
	v_add_f32_e32 v130, 1.0, v131
	v_add_f32_e32 v131, 1.0, v133
	v_mul_f32_e32 v133, 0xbfb8aa3b, v103
	v_mul_f32_e32 v134, 0xbfb8aa3b, v99
	v_exp_f32_e32 v128, v128
	v_exp_f32_e32 v133, v133
	v_exp_f32_e32 v135, v134
	v_rcp_f32_e32 v134, v131
	v_add_f32_e32 v128, 1.0, v128
	v_add_f32_e32 v131, 1.0, v133
	v_add_f32_e32 v133, 1.0, v135
	v_rcp_f32_e32 v128, v128
	v_rcp_f32_e32 v129, v129
	v_rcp_f32_e32 v130, v130
	v_rcp_f32_e32 v131, v131
	v_rcp_f32_e32 v135, v133
	v_rcp_f32_e32 v133, v142
	v_pk_mul_f32 v[128:129], v[100:101], v[128:129]
	v_pk_mul_f32 v[130:131], v[102:103], v[130:131]
	v_pk_mul_f32 v[134:135], v[98:99], v[134:135]
	v_pk_mul_f32 v[132:133], v[96:97], v[132:133]
; __device__ __forceinline__ unsigned cvt_pk_bf16(float lo, float hi) { f32x2_t v = {lo, hi}; bf16x2_t r = __builtin_convertvector(v, bf16x2_t); return __builtin_bit_cast(unsigned, r); }
; __device__ __forceinline__ float sigmoidf_(float v) { return __builtin_amdgcn_rcpf(1.0f + __builtin_amdgcn_exp2f(-1.4426950408889634f * v)); }
;     __device__ __forceinline__ void operator()(const f32x4 (&acc)[2][2][4][2], const Unit& u, int wr, int wc, int fr, int fq) const {
;     ...
; #pragma unroll
;         for (int ai = 0; ai < 2; ++ai)
; #pragma unroll
;             for (int m = 0; m < 4; ++m) { bf16_t* rowp = O + (size_t)(row0 + ai * HALF + m * 16) * NIN + col0;
; #pragma unroll
;                 for (int bj = 0; bj < 2; ++bj) { f32x4 v0 = acc[ai][bj][m][0], v1 = acc[ai][bj][m][1];
;                     if (mode != 0) {
; #pragma unroll
;                         for (int j = 0; j < 4; ++j) { v0[j] *= sigmoidf_(v0[j]); v1[j] *= sigmoidf_(v1[j]); }
;                     }
;                     u32x4 w; w.x = cvt_pk_bf16(v0[0], v0[1]); w.y = cvt_pk_bf16(v0[2], v0[3]); w.z = cvt_pk_bf16(v1[0], v1[1]); w.w = cvt_pk_bf16(v1[2], v1[3]);
;                     *(u32x4*)(rowp + bj * HALF) = w; } }
.LBB0_361:
	v_cvt_pk_bf16_f32 v128, v128, v129
	v_cvt_pk_bf16_f32 v129, v130, v131
	v_cvt_pk_bf16_f32 v130, v132, v133
	v_cvt_pk_bf16_f32 v131, v134, v135
	global_store_dwordx4 v[138:139], v[128:131], off offset:256 sc1
	v_mov_b64_e32 v[134:135], v[90:91]
	s_and_b64 vcc, exec, s[38:39]
	v_mov_b64_e32 v[130:131], v[94:95]
	v_mov_b64_e32 v[128:129], v[92:93]
	v_mov_b64_e32 v[132:133], v[88:89]
	s_cbranch_vccnz .LBB0_363
	v_mul_f32_e32 v129, 0xbfb8aa3b, v88
	v_mul_f32_e32 v130, 0xbfb8aa3b, v93
	v_exp_f32_e32 v129, v129
	v_exp_f32_e32 v130, v130
	v_mul_f32_e32 v131, 0xbfb8aa3b, v94
	v_mul_f32_e32 v133, 0xbfb8aa3b, v90
	v_add_f32_e32 v129, 1.0, v129
	v_rcp_f32_e32 v132, v129
	v_add_f32_e32 v129, 1.0, v130
	v_mul_f32_e32 v130, 0xbfb8aa3b, v89
	v_exp_f32_e32 v130, v130
	v_exp_f32_e32 v131, v131
	v_exp_f32_e32 v133, v133
	v_mul_f32_e32 v128, 0xbfb8aa3b, v92
	v_add_f32_e32 v138, 1.0, v130
	v_add_f32_e32 v130, 1.0, v131
	v_add_f32_e32 v131, 1.0, v133
	v_mul_f32_e32 v133, 0xbfb8aa3b, v95
	v_mul_f32_e32 v134, 0xbfb8aa3b, v91
	v_exp_f32_e32 v128, v128
	v_exp_f32_e32 v133, v133
	v_exp_f32_e32 v135, v134
	v_rcp_f32_e32 v134, v131
	v_add_f32_e32 v128, 1.0, v128
	v_add_f32_e32 v131, 1.0, v133
	v_add_f32_e32 v133, 1.0, v135
	v_rcp_f32_e32 v128, v128
	v_rcp_f32_e32 v129, v129
	v_rcp_f32_e32 v130, v130
	v_rcp_f32_e32 v131, v131
	v_rcp_f32_e32 v135, v133
	v_rcp_f32_e32 v133, v138
	v_pk_mul_f32 v[128:129], v[92:93], v[128:129]
	v_pk_mul_f32 v[130:131], v[94:95], v[130:131]
	v_pk_mul_f32 v[134:135], v[90:91], v[134:135]
	v_pk_mul_f32 v[132:133], v[88:89], v[132:133]
.LBB0_363:
	v_add_u32_e32 v142, 32, v141
	v_mov_b64_e32 v[138:139], s[4:5]
	v_mad_i64_i32 v[138:139], s[2:3], v142, s14, v[138:139]
	v_lshl_add_u64 v[138:139], v[136:137], 1, v[138:139]
	v_cvt_pk_bf16_f32 v128, v128, v129
	v_cvt_pk_bf16_f32 v129, v130, v131
	v_cvt_pk_bf16_f32 v130, v132, v133
	v_cvt_pk_bf16_f32 v131, v134, v135
	global_store_dwordx4 v[138:139], v[128:131], off sc1
	v_mov_b64_e32 v[134:135], v[82:83]
	s_and_b64 vcc, exec, s[38:39]
	v_mov_b64_e32 v[130:131], v[86:87]
	v_mov_b64_e32 v[128:129], v[84:85]
	v_mov_b64_e32 v[132:133], v[80:81]
	s_cbranch_vccnz .LBB0_365
	v_mul_f32_e32 v129, 0xbfb8aa3b, v80
	v_mul_f32_e32 v130, 0xbfb8aa3b, v85
	v_exp_f32_e32 v129, v129
	v_exp_f32_e32 v130, v130
	v_mul_f32_e32 v131, 0xbfb8aa3b, v86
	v_mul_f32_e32 v133, 0xbfb8aa3b, v82
	v_add_f32_e32 v129, 1.0, v129
	v_rcp_f32_e32 v132, v129
	v_add_f32_e32 v129, 1.0, v130
	v_mul_f32_e32 v130, 0xbfb8aa3b, v81
	v_exp_f32_e32 v130, v130
	v_exp_f32_e32 v131, v131
	v_exp_f32_e32 v133, v133
	v_mul_f32_e32 v128, 0xbfb8aa3b, v84
	v_add_f32_e32 v142, 1.0, v130
	v_add_f32_e32 v130, 1.0, v131
	v_add_f32_e32 v131, 1.0, v133
	v_mul_f32_e32 v133, 0xbfb8aa3b, v87
	v_mul_f32_e32 v134, 0xbfb8aa3b, v83
	v_exp_f32_e32 v128, v128
	v_exp_f32_e32 v133, v133
	v_exp_f32_e32 v135, v134
	v_rcp_f32_e32 v134, v131
	v_add_f32_e32 v128, 1.0, v128
	v_add_f32_e32 v131, 1.0, v133
	v_add_f32_e32 v133, 1.0, v135
	v_rcp_f32_e32 v128, v128
	v_rcp_f32_e32 v129, v129
	v_rcp_f32_e32 v130, v130
	v_rcp_f32_e32 v131, v131
	v_rcp_f32_e32 v135, v133
	v_rcp_f32_e32 v133, v142
	v_pk_mul_f32 v[128:129], v[84:85], v[128:129]
	v_pk_mul_f32 v[130:131], v[86:87], v[130:131]
	v_pk_mul_f32 v[134:135], v[82:83], v[134:135]
	v_pk_mul_f32 v[132:133], v[80:81], v[132:133]
.LBB0_365:
	v_cvt_pk_bf16_f32 v128, v128, v129
	v_cvt_pk_bf16_f32 v129, v130, v131
	v_cvt_pk_bf16_f32 v130, v132, v133
	v_cvt_pk_bf16_f32 v131, v134, v135
	global_store_dwordx4 v[138:139], v[128:131], off offset:256 sc1
	v_mov_b64_e32 v[134:135], v[74:75]
	s_and_b64 vcc, exec, s[38:39]
	v_mov_b64_e32 v[130:131], v[78:79]
	v_mov_b64_e32 v[128:129], v[76:77]
	v_mov_b64_e32 v[132:133], v[72:73]
	s_cbranch_vccnz .LBB0_367
	v_mul_f32_e32 v129, 0xbfb8aa3b, v72
	v_mul_f32_e32 v130, 0xbfb8aa3b, v77
	v_exp_f32_e32 v129, v129
	v_exp_f32_e32 v130, v130
	v_mul_f32_e32 v131, 0xbfb8aa3b, v78
	v_mul_f32_e32 v133, 0xbfb8aa3b, v74
	v_add_f32_e32 v129, 1.0, v129
	v_rcp_f32_e32 v132, v129
	v_add_f32_e32 v129, 1.0, v130
	v_mul_f32_e32 v130, 0xbfb8aa3b, v73
	v_exp_f32_e32 v130, v130
	v_exp_f32_e32 v131, v131
	v_exp_f32_e32 v133, v133
	v_mul_f32_e32 v128, 0xbfb8aa3b, v76
	v_add_f32_e32 v138, 1.0, v130
	v_add_f32_e32 v130, 1.0, v131
	v_add_f32_e32 v131, 1.0, v133
	v_mul_f32_e32 v133, 0xbfb8aa3b, v79
	v_mul_f32_e32 v134, 0xbfb8aa3b, v75
	v_exp_f32_e32 v128, v128
	v_exp_f32_e32 v133, v133
	v_exp_f32_e32 v135, v134
	v_rcp_f32_e32 v134, v131
	v_add_f32_e32 v128, 1.0, v128
	v_add_f32_e32 v131, 1.0, v133
	v_add_f32_e32 v133, 1.0, v135
	v_rcp_f32_e32 v128, v128
	v_rcp_f32_e32 v129, v129
	v_rcp_f32_e32 v130, v130
	v_rcp_f32_e32 v131, v131
	v_rcp_f32_e32 v135, v133
	v_rcp_f32_e32 v133, v138
	v_pk_mul_f32 v[128:129], v[76:77], v[128:129]
	v_pk_mul_f32 v[130:131], v[78:79], v[130:131]
	v_pk_mul_f32 v[134:135], v[74:75], v[134:135]
	v_pk_mul_f32 v[132:133], v[72:73], v[132:133]
; __device__ __forceinline__ unsigned cvt_pk_bf16(float lo, float hi) { f32x2_t v = {lo, hi}; bf16x2_t r = __builtin_convertvector(v, bf16x2_t); return __builtin_bit_cast(unsigned, r); }
; __device__ __forceinline__ float sigmoidf_(float v) { return __builtin_amdgcn_rcpf(1.0f + __builtin_amdgcn_exp2f(-1.4426950408889634f * v)); }
;     __device__ __forceinline__ void operator()(const f32x4 (&acc)[2][2][4][2], const Unit& u, int wr, int wc, int fr, int fq) const {
;     ...
; #pragma unroll
;         for (int ai = 0; ai < 2; ++ai)
; #pragma unroll
;             for (int m = 0; m < 4; ++m) { bf16_t* rowp = O + (size_t)(row0 + ai * HALF + m * 16) * NIN + col0;
; #pragma unroll
;                 for (int bj = 0; bj < 2; ++bj) { f32x4 v0 = acc[ai][bj][m][0], v1 = acc[ai][bj][m][1];
;                     if (mode != 0) {
; #pragma unroll
;                         for (int j = 0; j < 4; ++j) { v0[j] *= sigmoidf_(v0[j]); v1[j] *= sigmoidf_(v1[j]); }
;                     }
;                     u32x4 w; w.x = cvt_pk_bf16(v0[0], v0[1]); w.y = cvt_pk_bf16(v0[2], v0[3]); w.z = cvt_pk_bf16(v1[0], v1[1]); w.w = cvt_pk_bf16(v1[2], v1[3]);
;                     *(u32x4*)(rowp + bj * HALF) = w; } }
.LBB0_367:
	v_add_u32_e32 v142, 48, v141
	v_mov_b64_e32 v[138:139], s[4:5]
	v_mad_i64_i32 v[138:139], s[2:3], v142, s14, v[138:139]
	v_lshl_add_u64 v[138:139], v[136:137], 1, v[138:139]
	v_cvt_pk_bf16_f32 v128, v128, v129
	v_cvt_pk_bf16_f32 v129, v130, v131
	v_cvt_pk_bf16_f32 v130, v132, v133
	v_cvt_pk_bf16_f32 v131, v134, v135
	global_store_dwordx4 v[138:139], v[128:131], off sc1
	v_mov_b64_e32 v[134:135], v[66:67]
	s_and_b64 vcc, exec, s[38:39]
	v_mov_b64_e32 v[130:131], v[70:71]
	v_mov_b64_e32 v[128:129], v[68:69]
	v_mov_b64_e32 v[132:133], v[64:65]
	s_cbranch_vccnz .LBB0_369
	v_mul_f32_e32 v129, 0xbfb8aa3b, v64
	v_mul_f32_e32 v130, 0xbfb8aa3b, v69
	v_exp_f32_e32 v129, v129
	v_exp_f32_e32 v130, v130
	v_mul_f32_e32 v131, 0xbfb8aa3b, v70
	v_mul_f32_e32 v133, 0xbfb8aa3b, v66
	v_add_f32_e32 v129, 1.0, v129
	v_rcp_f32_e32 v132, v129
	v_add_f32_e32 v129, 1.0, v130
	v_mul_f32_e32 v130, 0xbfb8aa3b, v65
	v_exp_f32_e32 v130, v130
	v_exp_f32_e32 v131, v131
	v_exp_f32_e32 v133, v133
	v_mul_f32_e32 v128, 0xbfb8aa3b, v68
	v_add_f32_e32 v142, 1.0, v130
	v_add_f32_e32 v130, 1.0, v131
	v_add_f32_e32 v131, 1.0, v133
	v_mul_f32_e32 v133, 0xbfb8aa3b, v71
	v_mul_f32_e32 v134, 0xbfb8aa3b, v67
	v_exp_f32_e32 v128, v128
	v_exp_f32_e32 v133, v133
	v_exp_f32_e32 v135, v134
	v_rcp_f32_e32 v134, v131
	v_add_f32_e32 v128, 1.0, v128
	v_add_f32_e32 v131, 1.0, v133
	v_add_f32_e32 v133, 1.0, v135
	v_rcp_f32_e32 v128, v128
	v_rcp_f32_e32 v129, v129
	v_rcp_f32_e32 v130, v130
	v_rcp_f32_e32 v131, v131
	v_rcp_f32_e32 v135, v133
	v_rcp_f32_e32 v133, v142
	v_pk_mul_f32 v[128:129], v[68:69], v[128:129]
	v_pk_mul_f32 v[130:131], v[70:71], v[130:131]
	v_pk_mul_f32 v[134:135], v[66:67], v[134:135]
	v_pk_mul_f32 v[132:133], v[64:65], v[132:133]
.LBB0_369:
	v_cvt_pk_bf16_f32 v128, v128, v129
	v_cvt_pk_bf16_f32 v129, v130, v131
	v_cvt_pk_bf16_f32 v130, v132, v133
	v_cvt_pk_bf16_f32 v131, v134, v135
	global_store_dwordx4 v[138:139], v[128:131], off offset:256 sc1
	v_mov_b64_e32 v[134:135], v[58:59]
	s_and_b64 vcc, exec, s[38:39]
	v_mov_b64_e32 v[130:131], v[62:63]
	v_mov_b64_e32 v[128:129], v[60:61]
	v_mov_b64_e32 v[132:133], v[56:57]
	s_cbranch_vccnz .LBB0_371
	v_mul_f32_e32 v129, 0xbfb8aa3b, v56
	v_mul_f32_e32 v130, 0xbfb8aa3b, v61
	v_exp_f32_e32 v129, v129
	v_exp_f32_e32 v130, v130
	v_mul_f32_e32 v131, 0xbfb8aa3b, v62
	v_mul_f32_e32 v133, 0xbfb8aa3b, v58
	v_add_f32_e32 v129, 1.0, v129
	v_rcp_f32_e32 v132, v129
	v_add_f32_e32 v129, 1.0, v130
	v_mul_f32_e32 v130, 0xbfb8aa3b, v57
	v_exp_f32_e32 v130, v130
	v_exp_f32_e32 v131, v131
	v_exp_f32_e32 v133, v133
	v_mul_f32_e32 v128, 0xbfb8aa3b, v60
	v_add_f32_e32 v138, 1.0, v130
	v_add_f32_e32 v130, 1.0, v131
	v_add_f32_e32 v131, 1.0, v133
	v_mul_f32_e32 v133, 0xbfb8aa3b, v63
	v_mul_f32_e32 v134, 0xbfb8aa3b, v59
	v_exp_f32_e32 v128, v128
	v_exp_f32_e32 v133, v133
	v_exp_f32_e32 v135, v134
	v_rcp_f32_e32 v134, v131
	v_add_f32_e32 v128, 1.0, v128
	v_add_f32_e32 v131, 1.0, v133
	v_add_f32_e32 v133, 1.0, v135
	v_rcp_f32_e32 v128, v128
	v_rcp_f32_e32 v129, v129
	v_rcp_f32_e32 v130, v130
	v_rcp_f32_e32 v131, v131
	v_rcp_f32_e32 v135, v133
	v_rcp_f32_e32 v133, v138
	v_pk_mul_f32 v[128:129], v[60:61], v[128:129]
	v_pk_mul_f32 v[130:131], v[62:63], v[130:131]
	v_pk_mul_f32 v[134:135], v[58:59], v[134:135]
	v_pk_mul_f32 v[132:133], v[56:57], v[132:133]
.LBB0_371:
	v_add_u32_e32 v142, 0x80, v141
	v_mov_b64_e32 v[138:139], s[4:5]
	v_mad_i64_i32 v[138:139], s[2:3], v142, s14, v[138:139]
	v_lshl_add_u64 v[138:139], v[136:137], 1, v[138:139]
	v_cvt_pk_bf16_f32 v128, v128, v129
	v_cvt_pk_bf16_f32 v129, v130, v131
	v_cvt_pk_bf16_f32 v130, v132, v133
	v_cvt_pk_bf16_f32 v131, v134, v135
	global_store_dwordx4 v[138:139], v[128:131], off sc1
	v_mov_b64_e32 v[134:135], v[50:51]
	s_and_b64 vcc, exec, s[38:39]
	v_mov_b64_e32 v[130:131], v[54:55]
	v_mov_b64_e32 v[128:129], v[52:53]
	v_mov_b64_e32 v[132:133], v[48:49]
	s_cbranch_vccnz .LBB0_373
	v_mul_f32_e32 v129, 0xbfb8aa3b, v48
	v_mul_f32_e32 v130, 0xbfb8aa3b, v53
	v_exp_f32_e32 v129, v129
	v_exp_f32_e32 v130, v130
	v_mul_f32_e32 v131, 0xbfb8aa3b, v54
	v_mul_f32_e32 v133, 0xbfb8aa3b, v50
	v_add_f32_e32 v129, 1.0, v129
	v_rcp_f32_e32 v132, v129
	v_add_f32_e32 v129, 1.0, v130
	v_mul_f32_e32 v130, 0xbfb8aa3b, v49
	v_exp_f32_e32 v130, v130
	v_exp_f32_e32 v131, v131
	v_exp_f32_e32 v133, v133
	v_mul_f32_e32 v128, 0xbfb8aa3b, v52
	v_add_f32_e32 v142, 1.0, v130
	v_add_f32_e32 v130, 1.0, v131
	v_add_f32_e32 v131, 1.0, v133
	v_mul_f32_e32 v133, 0xbfb8aa3b, v55
	v_mul_f32_e32 v134, 0xbfb8aa3b, v51
	v_exp_f32_e32 v128, v128
	v_exp_f32_e32 v133, v133
	v_exp_f32_e32 v135, v134
	v_rcp_f32_e32 v134, v131
	v_add_f32_e32 v128, 1.0, v128
	v_add_f32_e32 v131, 1.0, v133
	v_add_f32_e32 v133, 1.0, v135
	v_rcp_f32_e32 v128, v128
	v_rcp_f32_e32 v129, v129
	v_rcp_f32_e32 v130, v130
	v_rcp_f32_e32 v131, v131
	v_rcp_f32_e32 v135, v133
	v_rcp_f32_e32 v133, v142
	v_pk_mul_f32 v[128:129], v[52:53], v[128:129]
	v_pk_mul_f32 v[130:131], v[54:55], v[130:131]
	v_pk_mul_f32 v[134:135], v[50:51], v[134:135]
	v_pk_mul_f32 v[132:133], v[48:49], v[132:133]
; __device__ __forceinline__ unsigned cvt_pk_bf16(float lo, float hi) { f32x2_t v = {lo, hi}; bf16x2_t r = __builtin_convertvector(v, bf16x2_t); return __builtin_bit_cast(unsigned, r); }
; __device__ __forceinline__ float sigmoidf_(float v) { return __builtin_amdgcn_rcpf(1.0f + __builtin_amdgcn_exp2f(-1.4426950408889634f * v)); }
;     __device__ __forceinline__ void operator()(const f32x4 (&acc)[2][2][4][2], const Unit& u, int wr, int wc, int fr, int fq) const {
;     ...
; #pragma unroll
;         for (int ai = 0; ai < 2; ++ai)
; #pragma unroll
;             for (int m = 0; m < 4; ++m) { bf16_t* rowp = O + (size_t)(row0 + ai * HALF + m * 16) * NIN + col0;
; #pragma unroll
;                 for (int bj = 0; bj < 2; ++bj) { f32x4 v0 = acc[ai][bj][m][0], v1 = acc[ai][bj][m][1];
;                     if (mode != 0) {
; #pragma unroll
;                         for (int j = 0; j < 4; ++j) { v0[j] *= sigmoidf_(v0[j]); v1[j] *= sigmoidf_(v1[j]); }
;                     }
;                     u32x4 w; w.x = cvt_pk_bf16(v0[0], v0[1]); w.y = cvt_pk_bf16(v0[2], v0[3]); w.z = cvt_pk_bf16(v1[0], v1[1]); w.w = cvt_pk_bf16(v1[2], v1[3]);
;                     *(u32x4*)(rowp + bj * HALF) = w; } }
.LBB0_373:
	v_cvt_pk_bf16_f32 v128, v128, v129
	v_cvt_pk_bf16_f32 v129, v130, v131
	v_cvt_pk_bf16_f32 v130, v132, v133
	v_cvt_pk_bf16_f32 v131, v134, v135
	global_store_dwordx4 v[138:139], v[128:131], off offset:256 sc1
	v_mov_b64_e32 v[134:135], v[42:43]
	s_and_b64 vcc, exec, s[38:39]
	v_mov_b64_e32 v[130:131], v[46:47]
	v_mov_b64_e32 v[128:129], v[44:45]
	v_mov_b64_e32 v[132:133], v[40:41]
	s_cbranch_vccnz .LBB0_375
	v_mul_f32_e32 v129, 0xbfb8aa3b, v40
	v_mul_f32_e32 v130, 0xbfb8aa3b, v45
	v_exp_f32_e32 v129, v129
	v_exp_f32_e32 v130, v130
	v_mul_f32_e32 v131, 0xbfb8aa3b, v46
	v_mul_f32_e32 v133, 0xbfb8aa3b, v42
	v_add_f32_e32 v129, 1.0, v129
	v_rcp_f32_e32 v132, v129
	v_add_f32_e32 v129, 1.0, v130
	v_mul_f32_e32 v130, 0xbfb8aa3b, v41
	v_exp_f32_e32 v130, v130
	v_exp_f32_e32 v131, v131
	v_exp_f32_e32 v133, v133
	v_mul_f32_e32 v128, 0xbfb8aa3b, v44
	v_add_f32_e32 v138, 1.0, v130
	v_add_f32_e32 v130, 1.0, v131
	v_add_f32_e32 v131, 1.0, v133
	v_mul_f32_e32 v133, 0xbfb8aa3b, v47
	v_mul_f32_e32 v134, 0xbfb8aa3b, v43
	v_exp_f32_e32 v128, v128
	v_exp_f32_e32 v133, v133
	v_exp_f32_e32 v135, v134
	v_rcp_f32_e32 v134, v131
	v_add_f32_e32 v128, 1.0, v128
	v_add_f32_e32 v131, 1.0, v133
	v_add_f32_e32 v133, 1.0, v135
	v_rcp_f32_e32 v128, v128
	v_rcp_f32_e32 v129, v129
	v_rcp_f32_e32 v130, v130
	v_rcp_f32_e32 v131, v131
	v_rcp_f32_e32 v135, v133
	v_rcp_f32_e32 v133, v138
	v_pk_mul_f32 v[128:129], v[44:45], v[128:129]
	v_pk_mul_f32 v[130:131], v[46:47], v[130:131]
	v_pk_mul_f32 v[134:135], v[42:43], v[134:135]
	v_pk_mul_f32 v[132:133], v[40:41], v[132:133]
.LBB0_375:
	v_add_u32_e32 v142, 0x90, v141
	v_mov_b64_e32 v[138:139], s[4:5]
	v_mad_i64_i32 v[138:139], s[2:3], v142, s14, v[138:139]
	v_lshl_add_u64 v[138:139], v[136:137], 1, v[138:139]
	v_cvt_pk_bf16_f32 v128, v128, v129
	v_cvt_pk_bf16_f32 v129, v130, v131
	v_cvt_pk_bf16_f32 v130, v132, v133
	v_cvt_pk_bf16_f32 v131, v134, v135
	global_store_dwordx4 v[138:139], v[128:131], off sc1
	v_mov_b64_e32 v[134:135], v[34:35]
	s_and_b64 vcc, exec, s[38:39]
	v_mov_b64_e32 v[130:131], v[38:39]
	v_mov_b64_e32 v[128:129], v[36:37]
	v_mov_b64_e32 v[132:133], v[32:33]
	s_cbranch_vccnz .LBB0_377
	v_mul_f32_e32 v129, 0xbfb8aa3b, v32
	v_mul_f32_e32 v130, 0xbfb8aa3b, v37
	v_exp_f32_e32 v129, v129
	v_exp_f32_e32 v130, v130
	v_mul_f32_e32 v131, 0xbfb8aa3b, v38
	v_mul_f32_e32 v133, 0xbfb8aa3b, v34
	v_add_f32_e32 v129, 1.0, v129
	v_rcp_f32_e32 v132, v129
	v_add_f32_e32 v129, 1.0, v130
	v_mul_f32_e32 v130, 0xbfb8aa3b, v33
	v_exp_f32_e32 v130, v130
	v_exp_f32_e32 v131, v131
	v_exp_f32_e32 v133, v133
	v_mul_f32_e32 v128, 0xbfb8aa3b, v36
	v_add_f32_e32 v142, 1.0, v130
	v_add_f32_e32 v130, 1.0, v131
	v_add_f32_e32 v131, 1.0, v133
	v_mul_f32_e32 v133, 0xbfb8aa3b, v39
	v_mul_f32_e32 v134, 0xbfb8aa3b, v35
	v_exp_f32_e32 v128, v128
	v_exp_f32_e32 v133, v133
	v_exp_f32_e32 v135, v134
	v_rcp_f32_e32 v134, v131
	v_add_f32_e32 v128, 1.0, v128
	v_add_f32_e32 v131, 1.0, v133
	v_add_f32_e32 v133, 1.0, v135
	v_rcp_f32_e32 v128, v128
	v_rcp_f32_e32 v129, v129
	v_rcp_f32_e32 v130, v130
	v_rcp_f32_e32 v131, v131
	v_rcp_f32_e32 v135, v133
	v_rcp_f32_e32 v133, v142
	v_pk_mul_f32 v[128:129], v[36:37], v[128:129]
	v_pk_mul_f32 v[130:131], v[38:39], v[130:131]
	v_pk_mul_f32 v[134:135], v[34:35], v[134:135]
	v_pk_mul_f32 v[132:133], v[32:33], v[132:133]
.LBB0_377:
	v_cvt_pk_bf16_f32 v128, v128, v129
	v_cvt_pk_bf16_f32 v129, v130, v131
	v_cvt_pk_bf16_f32 v130, v132, v133
	v_cvt_pk_bf16_f32 v131, v134, v135
	global_store_dwordx4 v[138:139], v[128:131], off offset:256 sc1
	v_mov_b64_e32 v[134:135], v[26:27]
	s_and_b64 vcc, exec, s[38:39]
	v_mov_b64_e32 v[130:131], v[30:31]
	v_mov_b64_e32 v[128:129], v[28:29]
	v_mov_b64_e32 v[132:133], v[24:25]
	s_cbranch_vccnz .LBB0_379
	v_mul_f32_e32 v129, 0xbfb8aa3b, v24
	v_mul_f32_e32 v130, 0xbfb8aa3b, v29
	v_exp_f32_e32 v129, v129
	v_exp_f32_e32 v130, v130
	v_mul_f32_e32 v131, 0xbfb8aa3b, v30
	v_mul_f32_e32 v133, 0xbfb8aa3b, v26
	v_add_f32_e32 v129, 1.0, v129
	v_rcp_f32_e32 v132, v129
	v_add_f32_e32 v129, 1.0, v130
	v_mul_f32_e32 v130, 0xbfb8aa3b, v25
	v_exp_f32_e32 v130, v130
	v_exp_f32_e32 v131, v131
	v_exp_f32_e32 v133, v133
	v_mul_f32_e32 v128, 0xbfb8aa3b, v28
	v_add_f32_e32 v138, 1.0, v130
	v_add_f32_e32 v130, 1.0, v131
	v_add_f32_e32 v131, 1.0, v133
	v_mul_f32_e32 v133, 0xbfb8aa3b, v31
	v_mul_f32_e32 v134, 0xbfb8aa3b, v27
	v_exp_f32_e32 v128, v128
	v_exp_f32_e32 v133, v133
	v_exp_f32_e32 v135, v134
	v_rcp_f32_e32 v134, v131
	v_add_f32_e32 v128, 1.0, v128
	v_add_f32_e32 v131, 1.0, v133
	v_add_f32_e32 v133, 1.0, v135
	v_rcp_f32_e32 v128, v128
	v_rcp_f32_e32 v129, v129
	v_rcp_f32_e32 v130, v130
	v_rcp_f32_e32 v131, v131
	v_rcp_f32_e32 v135, v133
	v_rcp_f32_e32 v133, v138
	v_pk_mul_f32 v[128:129], v[28:29], v[128:129]
	v_pk_mul_f32 v[130:131], v[30:31], v[130:131]
	v_pk_mul_f32 v[134:135], v[26:27], v[134:135]
	v_pk_mul_f32 v[132:133], v[24:25], v[132:133]
; __device__ __forceinline__ unsigned cvt_pk_bf16(float lo, float hi) { f32x2_t v = {lo, hi}; bf16x2_t r = __builtin_convertvector(v, bf16x2_t); return __builtin_bit_cast(unsigned, r); }
; __device__ __forceinline__ float sigmoidf_(float v) { return __builtin_amdgcn_rcpf(1.0f + __builtin_amdgcn_exp2f(-1.4426950408889634f * v)); }
; #define PG8_BAR __builtin_amdgcn_s_barrier()
;     __device__ __forceinline__ void operator()(const f32x4 (&acc)[2][2][4][2], const Unit& u, int wr, int wc, int fr, int fq) const {
;     ...
; #pragma unroll
;         for (int ai = 0; ai < 2; ++ai)
; #pragma unroll
;             for (int m = 0; m < 4; ++m) { bf16_t* rowp = O + (size_t)(row0 + ai * HALF + m * 16) * NIN + col0;
; #pragma unroll
;                 for (int bj = 0; bj < 2; ++bj) { f32x4 v0 = acc[ai][bj][m][0], v1 = acc[ai][bj][m][1];
;                     if (mode != 0) {
; #pragma unroll
;                         for (int j = 0; j < 4; ++j) { v0[j] *= sigmoidf_(v0[j]); v1[j] *= sigmoidf_(v1[j]); }
;                     }
;                     u32x4 w; w.x = cvt_pk_bf16(v0[0], v0[1]); w.y = cvt_pk_bf16(v0[2], v0[3]); w.z = cvt_pk_bf16(v1[0], v1[1]); w.w = cvt_pk_bf16(v1[2], v1[3]);
;                     *(u32x4*)(rowp + bj * HALF) = w; } }
; template <class Epi, class Sched>
; __device__ __forceinline__ void gemm_phase(LAS unsigned char* lds, const Gemm g, const Sched& S, const Epi& E, const int tid) {
;     ...
;         if (wr == 0) PG8_BAR;
;         E(acc, cur, wr, wc, fr, fq);
;         if (!has_next) break;
.LBB0_379:
	v_add_u32_e32 v142, 0xa0, v141
	v_mov_b64_e32 v[138:139], s[4:5]
	v_mad_i64_i32 v[138:139], s[2:3], v142, s14, v[138:139]
	v_lshl_add_u64 v[138:139], v[136:137], 1, v[138:139]
	v_cvt_pk_bf16_f32 v128, v128, v129
	v_cvt_pk_bf16_f32 v129, v130, v131
	v_cvt_pk_bf16_f32 v130, v132, v133
	v_cvt_pk_bf16_f32 v131, v134, v135
	global_store_dwordx4 v[138:139], v[128:131], off sc1
	v_mov_b64_e32 v[134:135], v[18:19]
	s_and_b64 vcc, exec, s[38:39]
	v_mov_b64_e32 v[130:131], v[22:23]
	v_mov_b64_e32 v[128:129], v[20:21]
	v_mov_b64_e32 v[132:133], v[16:17]
	s_cbranch_vccnz .LBB0_381
	v_mul_f32_e32 v129, 0xbfb8aa3b, v16
	v_mul_f32_e32 v130, 0xbfb8aa3b, v21
	v_exp_f32_e32 v129, v129
	v_exp_f32_e32 v130, v130
	v_mul_f32_e32 v131, 0xbfb8aa3b, v22
	v_mul_f32_e32 v133, 0xbfb8aa3b, v18
	v_add_f32_e32 v129, 1.0, v129
	v_rcp_f32_e32 v132, v129
	v_add_f32_e32 v129, 1.0, v130
	v_mul_f32_e32 v130, 0xbfb8aa3b, v17
	v_exp_f32_e32 v130, v130
	v_exp_f32_e32 v131, v131
	v_exp_f32_e32 v133, v133
	v_mul_f32_e32 v128, 0xbfb8aa3b, v20
	v_add_f32_e32 v142, 1.0, v130
	v_add_f32_e32 v130, 1.0, v131
	v_add_f32_e32 v131, 1.0, v133
	v_mul_f32_e32 v133, 0xbfb8aa3b, v23
	v_mul_f32_e32 v134, 0xbfb8aa3b, v19
	v_exp_f32_e32 v128, v128
	v_exp_f32_e32 v133, v133
	v_exp_f32_e32 v135, v134
	v_rcp_f32_e32 v134, v131
	v_add_f32_e32 v128, 1.0, v128
	v_add_f32_e32 v131, 1.0, v133
	v_add_f32_e32 v133, 1.0, v135
	v_rcp_f32_e32 v128, v128
	v_rcp_f32_e32 v129, v129
	v_rcp_f32_e32 v130, v130
	v_rcp_f32_e32 v131, v131
	v_rcp_f32_e32 v135, v133
	v_rcp_f32_e32 v133, v142
	v_pk_mul_f32 v[128:129], v[20:21], v[128:129]
	v_pk_mul_f32 v[130:131], v[22:23], v[130:131]
	v_pk_mul_f32 v[134:135], v[18:19], v[134:135]
	v_pk_mul_f32 v[132:133], v[16:17], v[132:133]
.LBB0_381:
	v_cvt_pk_bf16_f32 v128, v128, v129
	v_cvt_pk_bf16_f32 v129, v130, v131
	v_cvt_pk_bf16_f32 v130, v132, v133
	v_cvt_pk_bf16_f32 v131, v134, v135
	global_store_dwordx4 v[138:139], v[128:131], off offset:256 sc1
	v_mov_b64_e32 v[134:135], v[10:11]
	s_and_b64 vcc, exec, s[38:39]
	v_mov_b64_e32 v[130:131], v[14:15]
	v_mov_b64_e32 v[128:129], v[12:13]
	v_mov_b64_e32 v[132:133], v[8:9]
	s_cbranch_vccnz .LBB0_383
	v_mul_f32_e32 v129, 0xbfb8aa3b, v8
	v_mul_f32_e32 v130, 0xbfb8aa3b, v13
	v_exp_f32_e32 v129, v129
	v_exp_f32_e32 v130, v130
	v_mul_f32_e32 v131, 0xbfb8aa3b, v14
	v_mul_f32_e32 v133, 0xbfb8aa3b, v10
	v_add_f32_e32 v129, 1.0, v129
	v_rcp_f32_e32 v132, v129
	v_add_f32_e32 v129, 1.0, v130
	v_mul_f32_e32 v130, 0xbfb8aa3b, v9
	v_exp_f32_e32 v130, v130
	v_exp_f32_e32 v131, v131
	v_exp_f32_e32 v133, v133
	v_mul_f32_e32 v128, 0xbfb8aa3b, v12
	v_add_f32_e32 v138, 1.0, v130
	v_add_f32_e32 v130, 1.0, v131
	v_add_f32_e32 v131, 1.0, v133
	v_mul_f32_e32 v133, 0xbfb8aa3b, v15
	v_mul_f32_e32 v134, 0xbfb8aa3b, v11
	v_exp_f32_e32 v128, v128
	v_exp_f32_e32 v133, v133
	v_exp_f32_e32 v135, v134
	v_rcp_f32_e32 v134, v131
	v_add_f32_e32 v128, 1.0, v128
	v_add_f32_e32 v131, 1.0, v133
	v_add_f32_e32 v133, 1.0, v135
	v_rcp_f32_e32 v128, v128
	v_rcp_f32_e32 v129, v129
	v_rcp_f32_e32 v130, v130
	v_rcp_f32_e32 v131, v131
	v_rcp_f32_e32 v135, v133
	v_rcp_f32_e32 v133, v138
	v_pk_mul_f32 v[128:129], v[12:13], v[128:129]
	v_pk_mul_f32 v[130:131], v[14:15], v[130:131]
	v_pk_mul_f32 v[134:135], v[10:11], v[134:135]
	v_pk_mul_f32 v[132:133], v[8:9], v[132:133]
.LBB0_383:
	v_add_u32_e32 v141, 0xb0, v141
	v_mov_b64_e32 v[138:139], s[4:5]
	v_mad_i64_i32 v[138:139], s[2:3], v141, s14, v[138:139]
	v_lshl_add_u64 v[138:139], v[136:137], 1, v[138:139]
	v_cvt_pk_bf16_f32 v128, v128, v129
	v_cvt_pk_bf16_f32 v129, v130, v131
	v_cvt_pk_bf16_f32 v130, v132, v133
	v_cvt_pk_bf16_f32 v131, v134, v135
	global_store_dwordx4 v[138:139], v[128:131], off sc1
	v_mov_b64_e32 v[134:135], v[2:3]
	s_and_b64 vcc, exec, s[38:39]
	v_mov_b64_e32 v[130:131], v[6:7]
	v_mov_b64_e32 v[128:129], v[4:5]
	v_mov_b64_e32 v[132:133], v[0:1]
	s_cbranch_vccnz .LBB0_385
	v_mul_f32_e32 v129, 0xbfb8aa3b, v0
	v_mul_f32_e32 v130, 0xbfb8aa3b, v5
	v_exp_f32_e32 v129, v129
	v_exp_f32_e32 v130, v130
	v_mul_f32_e32 v131, 0xbfb8aa3b, v6
	v_mul_f32_e32 v133, 0xbfb8aa3b, v2
	v_add_f32_e32 v129, 1.0, v129
	v_rcp_f32_e32 v132, v129
	v_add_f32_e32 v129, 1.0, v130
	v_mul_f32_e32 v130, 0xbfb8aa3b, v1
	v_exp_f32_e32 v130, v130
	v_exp_f32_e32 v131, v131
	v_exp_f32_e32 v133, v133
	v_mul_f32_e32 v128, 0xbfb8aa3b, v4
	v_add_f32_e32 v137, 1.0, v130
	v_add_f32_e32 v130, 1.0, v131
	v_add_f32_e32 v131, 1.0, v133
	v_mul_f32_e32 v133, 0xbfb8aa3b, v7
	v_mul_f32_e32 v134, 0xbfb8aa3b, v3
	v_exp_f32_e32 v128, v128
	v_exp_f32_e32 v133, v133
	v_exp_f32_e32 v135, v134
	v_rcp_f32_e32 v134, v131
	v_add_f32_e32 v128, 1.0, v128
	v_add_f32_e32 v131, 1.0, v133
	v_add_f32_e32 v133, 1.0, v135
	v_rcp_f32_e32 v128, v128
	v_rcp_f32_e32 v129, v129
	v_rcp_f32_e32 v130, v130
	v_rcp_f32_e32 v131, v131
	v_rcp_f32_e32 v135, v133
	v_rcp_f32_e32 v133, v137
	v_pk_mul_f32 v[128:129], v[4:5], v[128:129]
	v_pk_mul_f32 v[130:131], v[6:7], v[130:131]
	v_pk_mul_f32 v[134:135], v[2:3], v[134:135]
	v_pk_mul_f32 v[132:133], v[0:1], v[132:133]
.LBB0_385:
	v_cvt_pk_bf16_f32 v128, v128, v129
	v_cvt_pk_bf16_f32 v129, v130, v131
	v_cvt_pk_bf16_f32 v130, v132, v133
	v_cvt_pk_bf16_f32 v131, v134, v135
	global_store_dwordx4 v[138:139], v[128:131], off offset:256 sc1
	s_branch .LBB0_352
; #define LAS __attribute__((address_space(3)))
; __device__ __forceinline__ unsigned cvt_pk_bf16(float lo, float hi) { f32x2_t v = {lo, hi}; bf16x2_t r = __builtin_convertvector(v, bf16x2_t); return __builtin_bit_cast(unsigned, r); }
; __device__ __forceinline__ float sigmoidf_(float v) { return __builtin_amdgcn_rcpf(1.0f + __builtin_amdgcn_exp2f(-1.4426950408889634f * v)); }
;     __device__ __forceinline__ void operator()(const f32x4 (&acc)[2][2][4][2], const Unit& u, int wr, int wc, int fr, int fq) const {
;     ...
;         if (mode == 2) {
;             const int gt = u.pn - C_G / BM;
;             u32x4* gf = GF + ((size_t)(((gt >> 3) * 64 + u.pm) * 8 + (gt & 7)) * 8 + (wr * 4 + wc)) * 1024 + fq * 16 + fr;
;             f32x4 bv[2][2];
; #pragma unroll
;             for (int bj = 0; bj < 2; ++bj)
; #pragma unroll
;                 for (int n = 0; n < 2; ++n) bv[bj][n] = *(const LAS f32x4*)(bgate + (col0 - C_G) + bj * HALF + 4 * n);
; #pragma unroll
;             for (int ai = 0; ai < 2; ++ai)
; #pragma unroll
;                 for (int m = 0; m < 4; ++m)
; #pragma unroll
;                     for (int bj = 0; bj < 2; ++bj) { const f32x4 v0 = acc[ai][bj][m][0] + bv[bj][0], v1 = acc[ai][bj][m][1] + bv[bj][1];
;                         u32x4 w; w.x = cvt_pk_bf16(sigmoidf_(v0[0]), sigmoidf_(v0[1])); w.y = cvt_pk_bf16(sigmoidf_(v0[2]), sigmoidf_(v0[3]));
;                         w.z = cvt_pk_bf16(sigmoidf_(v1[0]), sigmoidf_(v1[1])); w.w = cvt_pk_bf16(sigmoidf_(v1[2]), sigmoidf_(v1[3]));
;                         gf[((ai * 4 + m) * 2 + bj) * 64] = w; }
.LBB0_386:
	v_readlane_b32 s11, v251, 11
	v_lshlrev_b32_e32 v160, 4, v140
	s_sub_i32 s2, s46, 46
	v_lshl_add_u32 v128, v136, 2, s11
	v_add_u32_e32 v129, 0xffff4800, v128
	v_add_u32_e32 v130, 0xffff4810, v128
	ds_read_b128 v[140:143], v129
	ds_read_b128 v[136:139], v130
	s_lshl_b32 s3, s2, 3
	s_and_b32 s3, s3, 0x1fffffc0
	s_add_i32 s3, s3, s44
	s_lshl_b32 s3, s3, 3
	s_and_b32 s2, s2, 7
	s_waitcnt lgkmcnt(0)
	v_pk_add_f32 v[120:121], v[120:121], v[136:137]
	s_or_b32 s2, s3, s2
	v_mul_f32_e32 v120, 0xbfb8aa3b, v120
	s_ashr_i32 s3, s2, 31
	v_exp_f32_e32 v120, v120
	v_mul_f32_e32 v121, 0xbfb8aa3b, v121
	s_lshl_b64 s[2:3], s[2:3], 17
	v_exp_f32_e32 v121, v121
	s_add_u32 s2, s60, s2
	v_ashrrev_i32_e32 v161, 31, v160
	s_addc_u32 s3, s61, s3
	v_ashrrev_i32_e32 v155, 31, v154
	v_add_u32_e32 v129, 0xffff4a00, v128
	v_add_u32_e32 v128, 0xffff4a10, v128
	v_lshl_add_u64 v[160:161], v[160:161], 4, s[2:3]
	v_pk_add_f32 v[122:123], v[122:123], v[138:139]
	v_add_f32_e32 v120, 1.0, v120
	ds_read_b128 v[132:135], v129
	ds_read_b128 v[128:131], v128
	v_lshl_add_u64 v[154:155], v[154:155], 4, v[160:161]
	v_pk_add_f32 v[126:127], v[126:127], v[142:143]
	v_pk_add_f32 v[124:125], v[124:125], v[140:141]
	v_rcp_f32_e32 v160, v120
	v_add_f32_e32 v120, 1.0, v121
	v_mul_f32_e32 v121, 0xbfb8aa3b, v122
	v_mul_f32_e32 v124, 0xbfb8aa3b, v124
	v_mul_f32_e32 v125, 0xbfb8aa3b, v125
	v_mul_f32_e32 v126, 0xbfb8aa3b, v126
	v_mul_f32_e32 v127, 0xbfb8aa3b, v127
	v_exp_f32_e32 v121, v121
	v_mul_f32_e32 v122, 0xbfb8aa3b, v123
	v_exp_f32_e32 v124, v124
	v_exp_f32_e32 v125, v125
	v_exp_f32_e32 v126, v126
	v_exp_f32_e32 v127, v127
	v_exp_f32_e32 v122, v122
	v_rcp_f32_e32 v123, v120
	v_add_f32_e32 v120, 1.0, v121
	s_waitcnt lgkmcnt(0)
	v_pk_add_f32 v[112:113], v[112:113], v[128:129]
	v_add_f32_e32 v124, 1.0, v124
	v_add_f32_e32 v125, 1.0, v125
	v_add_f32_e32 v126, 1.0, v126
	v_add_f32_e32 v127, 1.0, v127
	v_rcp_f32_e32 v161, v120
	v_add_f32_e32 v120, 1.0, v122
	v_mul_f32_e32 v112, 0xbfb8aa3b, v112
	v_rcp_f32_e32 v124, v124
	v_rcp_f32_e32 v125, v125
	v_rcp_f32_e32 v126, v126
	v_rcp_f32_e32 v127, v127
	v_rcp_f32_e32 v162, v120
	v_exp_f32_e32 v112, v112
	v_mul_f32_e32 v113, 0xbfb8aa3b, v113
	v_exp_f32_e32 v113, v113
	v_cvt_pk_bf16_f32 v120, v124, v125
	v_cvt_pk_bf16_f32 v121, v126, v127
	v_cvt_pk_bf16_f32 v122, v160, v123
	v_cvt_pk_bf16_f32 v123, v161, v162
	v_pk_add_f32 v[114:115], v[114:115], v[130:131]
	v_add_f32_e32 v112, 1.0, v112
	global_store_dwordx4 v[154:155], v[120:123], off sc1
	v_pk_add_f32 v[118:119], v[118:119], v[134:135]
	v_pk_add_f32 v[116:117], v[116:117], v[132:133]
	v_rcp_f32_e32 v120, v112
	v_add_f32_e32 v112, 1.0, v113
	v_mul_f32_e32 v113, 0xbfb8aa3b, v114
	v_mul_f32_e32 v116, 0xbfb8aa3b, v116
	v_mul_f32_e32 v117, 0xbfb8aa3b, v117
	v_mul_f32_e32 v118, 0xbfb8aa3b, v118
	v_mul_f32_e32 v119, 0xbfb8aa3b, v119
	v_exp_f32_e32 v113, v113
	v_mul_f32_e32 v114, 0xbfb8aa3b, v115
	v_exp_f32_e32 v116, v116
	v_exp_f32_e32 v117, v117
	v_exp_f32_e32 v118, v118
	v_exp_f32_e32 v119, v119
	v_exp_f32_e32 v114, v114
	v_rcp_f32_e32 v115, v112
	v_add_f32_e32 v112, 1.0, v113
	v_pk_add_f32 v[104:105], v[104:105], v[136:137]
	v_add_f32_e32 v116, 1.0, v116
	v_add_f32_e32 v117, 1.0, v117
	v_add_f32_e32 v118, 1.0, v118
	v_add_f32_e32 v119, 1.0, v119
	v_rcp_f32_e32 v121, v112
	v_add_f32_e32 v112, 1.0, v114
	v_mul_f32_e32 v104, 0xbfb8aa3b, v104
	v_rcp_f32_e32 v116, v116
	v_rcp_f32_e32 v117, v117
	v_rcp_f32_e32 v118, v118
	v_rcp_f32_e32 v119, v119
	v_rcp_f32_e32 v122, v112
	v_exp_f32_e32 v104, v104
	v_mul_f32_e32 v105, 0xbfb8aa3b, v105
	v_exp_f32_e32 v105, v105
	v_cvt_pk_bf16_f32 v112, v116, v117
	v_cvt_pk_bf16_f32 v113, v118, v119
	v_cvt_pk_bf16_f32 v114, v120, v115
	v_cvt_pk_bf16_f32 v115, v121, v122
	v_pk_add_f32 v[106:107], v[106:107], v[138:139]
	v_add_f32_e32 v104, 1.0, v104
	global_store_dwordx4 v[154:155], v[112:115], off offset:1024 sc1
	v_pk_add_f32 v[110:111], v[110:111], v[142:143]
	v_pk_add_f32 v[108:109], v[108:109], v[140:141]
	v_rcp_f32_e32 v112, v104
	v_add_f32_e32 v104, 1.0, v105
	v_mul_f32_e32 v105, 0xbfb8aa3b, v106
	v_mul_f32_e32 v108, 0xbfb8aa3b, v108
	v_mul_f32_e32 v109, 0xbfb8aa3b, v109
	v_mul_f32_e32 v110, 0xbfb8aa3b, v110
	v_mul_f32_e32 v111, 0xbfb8aa3b, v111
	v_exp_f32_e32 v105, v105
	v_mul_f32_e32 v106, 0xbfb8aa3b, v107
	v_exp_f32_e32 v108, v108
	v_exp_f32_e32 v109, v109
	v_exp_f32_e32 v110, v110
	v_exp_f32_e32 v111, v111
	v_exp_f32_e32 v106, v106
	v_rcp_f32_e32 v107, v104
	v_add_f32_e32 v104, 1.0, v105
	v_pk_add_f32 v[96:97], v[96:97], v[128:129]
	v_add_f32_e32 v108, 1.0, v108
	v_add_f32_e32 v109, 1.0, v109
	v_add_f32_e32 v110, 1.0, v110
	v_add_f32_e32 v111, 1.0, v111
	v_rcp_f32_e32 v113, v104
	v_add_f32_e32 v104, 1.0, v106
	v_mul_f32_e32 v96, 0xbfb8aa3b, v96
	v_rcp_f32_e32 v108, v108
	v_rcp_f32_e32 v109, v109
	v_rcp_f32_e32 v110, v110
	v_rcp_f32_e32 v111, v111
	v_rcp_f32_e32 v114, v104
	v_exp_f32_e32 v96, v96
	v_mul_f32_e32 v97, 0xbfb8aa3b, v97
	v_exp_f32_e32 v97, v97
	v_cvt_pk_bf16_f32 v104, v108, v109
	v_cvt_pk_bf16_f32 v105, v110, v111
	v_cvt_pk_bf16_f32 v106, v112, v107
	v_cvt_pk_bf16_f32 v107, v113, v114
	v_pk_add_f32 v[98:99], v[98:99], v[130:131]
	v_add_f32_e32 v96, 1.0, v96
	global_store_dwordx4 v[154:155], v[104:107], off offset:2048 sc1
	v_pk_add_f32 v[102:103], v[102:103], v[134:135]
	v_pk_add_f32 v[100:101], v[100:101], v[132:133]
	v_rcp_f32_e32 v104, v96
	v_add_f32_e32 v96, 1.0, v97
	v_mul_f32_e32 v97, 0xbfb8aa3b, v98
	v_mul_f32_e32 v100, 0xbfb8aa3b, v100
	v_mul_f32_e32 v101, 0xbfb8aa3b, v101
	v_mul_f32_e32 v102, 0xbfb8aa3b, v102
	v_mul_f32_e32 v103, 0xbfb8aa3b, v103
	v_exp_f32_e32 v97, v97
	v_mul_f32_e32 v98, 0xbfb8aa3b, v99
	v_exp_f32_e32 v100, v100
; #define LAS __attribute__((address_space(3)))
; __device__ __forceinline__ unsigned cvt_pk_bf16(float lo, float hi) { f32x2_t v = {lo, hi}; bf16x2_t r = __builtin_convertvector(v, bf16x2_t); return __builtin_bit_cast(unsigned, r); }
; __device__ __forceinline__ float sigmoidf_(float v) { return __builtin_amdgcn_rcpf(1.0f + __builtin_amdgcn_exp2f(-1.4426950408889634f * v)); }
;     __device__ __forceinline__ void operator()(const f32x4 (&acc)[2][2][4][2], const Unit& u, int wr, int wc, int fr, int fq) const {
;     ...
;             f32x4 bv[2][2];
; #pragma unroll
;             for (int bj = 0; bj < 2; ++bj)
; #pragma unroll
;                 for (int n = 0; n < 2; ++n) bv[bj][n] = *(const LAS f32x4*)(bgate + (col0 - C_G) + bj * HALF + 4 * n);
; #pragma unroll
;             for (int ai = 0; ai < 2; ++ai)
; #pragma unroll
;                 for (int m = 0; m < 4; ++m)
; #pragma unroll
;                     for (int bj = 0; bj < 2; ++bj) { const f32x4 v0 = acc[ai][bj][m][0] + bv[bj][0], v1 = acc[ai][bj][m][1] + bv[bj][1];
;                         u32x4 w; w.x = cvt_pk_bf16(sigmoidf_(v0[0]), sigmoidf_(v0[1])); w.y = cvt_pk_bf16(sigmoidf_(v0[2]), sigmoidf_(v0[3]));
;                         w.z = cvt_pk_bf16(sigmoidf_(v1[0]), sigmoidf_(v1[1])); w.w = cvt_pk_bf16(sigmoidf_(v1[2]), sigmoidf_(v1[3]));
;                         gf[((ai * 4 + m) * 2 + bj) * 64] = w; }
	v_exp_f32_e32 v101, v101
	v_exp_f32_e32 v102, v102
	v_exp_f32_e32 v103, v103
	v_exp_f32_e32 v98, v98
	v_pk_add_f32 v[94:95], v[94:95], v[142:143]
	v_rcp_f32_e32 v99, v96
	v_mul_f32_e32 v94, 0xbfb8aa3b, v94
	v_mul_f32_e32 v95, 0xbfb8aa3b, v95
	v_add_f32_e32 v96, 1.0, v97
	v_pk_add_f32 v[92:93], v[92:93], v[140:141]
	v_pk_add_f32 v[90:91], v[90:91], v[138:139]
	v_pk_add_f32 v[88:89], v[88:89], v[136:137]
	v_exp_f32_e32 v94, v94
	v_exp_f32_e32 v95, v95
	v_add_f32_e32 v100, 1.0, v100
	v_add_f32_e32 v101, 1.0, v101
	v_add_f32_e32 v102, 1.0, v102
	v_add_f32_e32 v103, 1.0, v103
	v_rcp_f32_e32 v105, v96
	v_add_f32_e32 v96, 1.0, v98
	v_mul_f32_e32 v92, 0xbfb8aa3b, v92
	v_mul_f32_e32 v93, 0xbfb8aa3b, v93
	v_mul_f32_e32 v88, 0xbfb8aa3b, v88
	v_mul_f32_e32 v89, 0xbfb8aa3b, v89
	v_mul_f32_e32 v90, 0xbfb8aa3b, v90
	v_rcp_f32_e32 v100, v100
	v_rcp_f32_e32 v101, v101
	v_rcp_f32_e32 v102, v102
	v_rcp_f32_e32 v103, v103
	v_rcp_f32_e32 v106, v96
	v_exp_f32_e32 v92, v92
	v_exp_f32_e32 v93, v93
	v_exp_f32_e32 v88, v88
	v_exp_f32_e32 v89, v89
	v_exp_f32_e32 v90, v90
	v_mul_f32_e32 v91, 0xbfb8aa3b, v91
	v_exp_f32_e32 v91, v91
	v_add_f32_e32 v94, 1.0, v94
	v_add_f32_e32 v95, 1.0, v95
	v_rcp_f32_e32 v94, v94
	v_rcp_f32_e32 v95, v95
	v_cvt_pk_bf16_f32 v96, v100, v101
	v_cvt_pk_bf16_f32 v97, v102, v103
	v_cvt_pk_bf16_f32 v98, v104, v99
	v_cvt_pk_bf16_f32 v99, v105, v106
	v_add_f32_e32 v92, 1.0, v92
	v_add_f32_e32 v93, 1.0, v93
	v_add_f32_e32 v88, 1.0, v88
	v_add_f32_e32 v89, 1.0, v89
	v_add_f32_e32 v90, 1.0, v90
	v_pk_add_f32 v[80:81], v[80:81], v[128:129]
	global_store_dwordx4 v[154:155], v[96:99], off offset:3072 sc1
	v_rcp_f32_e32 v92, v92
	v_rcp_f32_e32 v93, v93
	v_rcp_f32_e32 v88, v88
	v_rcp_f32_e32 v89, v89
	v_rcp_f32_e32 v96, v90
	v_add_f32_e32 v90, 1.0, v91
	v_mul_f32_e32 v80, 0xbfb8aa3b, v80
	v_rcp_f32_e32 v97, v90
	v_exp_f32_e32 v80, v80
	v_mul_f32_e32 v81, 0xbfb8aa3b, v81
	v_cvt_pk_bf16_f32 v91, v94, v95
	v_add_co_u32_e32 v94, vcc, s33, v154
	v_exp_f32_e32 v81, v81
	s_nop 0
	v_addc_co_u32_e32 v95, vcc, 0, v155, vcc
	s_movk_i32 s2, 0x2000
	v_cvt_pk_bf16_f32 v90, v92, v93
	v_cvt_pk_bf16_f32 v92, v88, v89
	v_add_co_u32_e32 v88, vcc, s2, v154
	v_cvt_pk_bf16_f32 v93, v96, v97
	s_nop 0
	v_addc_co_u32_e32 v89, vcc, 0, v155, vcc
	v_pk_add_f32 v[82:83], v[82:83], v[130:131]
	v_add_f32_e32 v80, 1.0, v80
	global_store_dwordx4 v[88:89], v[90:93], off offset:-4096 sc1
	v_pk_add_f32 v[86:87], v[86:87], v[134:135]
	v_pk_add_f32 v[84:85], v[84:85], v[132:133]
	v_rcp_f32_e32 v90, v80
	v_add_f32_e32 v80, 1.0, v81
	v_mul_f32_e32 v81, 0xbfb8aa3b, v82
	v_mul_f32_e32 v84, 0xbfb8aa3b, v84
	v_mul_f32_e32 v85, 0xbfb8aa3b, v85
	v_mul_f32_e32 v86, 0xbfb8aa3b, v86
	v_mul_f32_e32 v87, 0xbfb8aa3b, v87
	v_exp_f32_e32 v81, v81
	v_mul_f32_e32 v82, 0xbfb8aa3b, v83
	v_exp_f32_e32 v84, v84
	v_exp_f32_e32 v85, v85
	v_exp_f32_e32 v86, v86
	v_exp_f32_e32 v87, v87
	v_exp_f32_e32 v82, v82
	v_rcp_f32_e32 v83, v80
	v_add_f32_e32 v80, 1.0, v81
	v_pk_add_f32 v[72:73], v[72:73], v[136:137]
	v_add_f32_e32 v84, 1.0, v84
	v_add_f32_e32 v85, 1.0, v85
	v_add_f32_e32 v86, 1.0, v86
	v_add_f32_e32 v87, 1.0, v87
	v_rcp_f32_e32 v91, v80
	v_add_f32_e32 v80, 1.0, v82
	v_mul_f32_e32 v72, 0xbfb8aa3b, v72
	v_rcp_f32_e32 v84, v84
	v_rcp_f32_e32 v85, v85
	v_rcp_f32_e32 v86, v86
	v_rcp_f32_e32 v87, v87
	v_rcp_f32_e32 v92, v80
	v_exp_f32_e32 v72, v72
	v_mul_f32_e32 v73, 0xbfb8aa3b, v73
	v_exp_f32_e32 v73, v73
	v_cvt_pk_bf16_f32 v80, v84, v85
	v_cvt_pk_bf16_f32 v81, v86, v87
	v_cvt_pk_bf16_f32 v82, v90, v83
	v_cvt_pk_bf16_f32 v83, v91, v92
	v_pk_add_f32 v[74:75], v[74:75], v[138:139]
	v_add_f32_e32 v72, 1.0, v72
	global_store_dwordx4 v[94:95], v[80:83], off offset:1024 sc1
	v_pk_add_f32 v[78:79], v[78:79], v[142:143]
	v_pk_add_f32 v[76:77], v[76:77], v[140:141]
	v_rcp_f32_e32 v80, v72
	v_add_f32_e32 v72, 1.0, v73
	v_mul_f32_e32 v73, 0xbfb8aa3b, v74
	v_mul_f32_e32 v76, 0xbfb8aa3b, v76
	v_mul_f32_e32 v77, 0xbfb8aa3b, v77
	v_mul_f32_e32 v78, 0xbfb8aa3b, v78
	v_mul_f32_e32 v79, 0xbfb8aa3b, v79
	v_exp_f32_e32 v73, v73
	v_mul_f32_e32 v74, 0xbfb8aa3b, v75
	v_exp_f32_e32 v76, v76
	v_exp_f32_e32 v77, v77
	v_exp_f32_e32 v78, v78
	v_exp_f32_e32 v79, v79
	v_exp_f32_e32 v74, v74
	v_rcp_f32_e32 v75, v72
	v_add_f32_e32 v72, 1.0, v73
	v_pk_add_f32 v[64:65], v[64:65], v[128:129]
	v_add_f32_e32 v76, 1.0, v76
	v_add_f32_e32 v77, 1.0, v77
	v_add_f32_e32 v78, 1.0, v78
	v_add_f32_e32 v79, 1.0, v79
	v_rcp_f32_e32 v81, v72
	v_add_f32_e32 v72, 1.0, v74
	v_mul_f32_e32 v64, 0xbfb8aa3b, v64
	v_rcp_f32_e32 v76, v76
	v_rcp_f32_e32 v77, v77
	v_rcp_f32_e32 v78, v78
	v_rcp_f32_e32 v79, v79
	v_rcp_f32_e32 v82, v72
	v_exp_f32_e32 v64, v64
	v_mul_f32_e32 v65, 0xbfb8aa3b, v65
	v_exp_f32_e32 v65, v65
	v_cvt_pk_bf16_f32 v72, v76, v77
	v_cvt_pk_bf16_f32 v73, v78, v79
	v_cvt_pk_bf16_f32 v74, v80, v75
	v_cvt_pk_bf16_f32 v75, v81, v82
	v_pk_add_f32 v[66:67], v[66:67], v[130:131]
	v_add_f32_e32 v64, 1.0, v64
	global_store_dwordx4 v[94:95], v[72:75], off offset:2048 sc1
	v_pk_add_f32 v[70:71], v[70:71], v[134:135]
	v_pk_add_f32 v[68:69], v[68:69], v[132:133]
	v_rcp_f32_e32 v72, v64
	v_add_f32_e32 v64, 1.0, v65
	v_mul_f32_e32 v65, 0xbfb8aa3b, v66
	v_mul_f32_e32 v68, 0xbfb8aa3b, v68
	v_mul_f32_e32 v69, 0xbfb8aa3b, v69
	v_mul_f32_e32 v70, 0xbfb8aa3b, v70
	v_mul_f32_e32 v71, 0xbfb8aa3b, v71
	v_exp_f32_e32 v65, v65
	v_mul_f32_e32 v66, 0xbfb8aa3b, v67
	v_exp_f32_e32 v68, v68
	v_exp_f32_e32 v69, v69
	v_exp_f32_e32 v70, v70
	v_exp_f32_e32 v71, v71
	v_exp_f32_e32 v66, v66
	v_rcp_f32_e32 v67, v64
	v_add_f32_e32 v64, 1.0, v65
	v_pk_add_f32 v[56:57], v[56:57], v[136:137]
	v_add_f32_e32 v68, 1.0, v68
	v_add_f32_e32 v69, 1.0, v69
	v_add_f32_e32 v70, 1.0, v70
; #define LAS __attribute__((address_space(3)))
; __device__ __forceinline__ unsigned cvt_pk_bf16(float lo, float hi) { f32x2_t v = {lo, hi}; bf16x2_t r = __builtin_convertvector(v, bf16x2_t); return __builtin_bit_cast(unsigned, r); }
; __device__ __forceinline__ float sigmoidf_(float v) { return __builtin_amdgcn_rcpf(1.0f + __builtin_amdgcn_exp2f(-1.4426950408889634f * v)); }
;     __device__ __forceinline__ void operator()(const f32x4 (&acc)[2][2][4][2], const Unit& u, int wr, int wc, int fr, int fq) const {
;     ...
;             f32x4 bv[2][2];
; #pragma unroll
;             for (int bj = 0; bj < 2; ++bj)
; #pragma unroll
;                 for (int n = 0; n < 2; ++n) bv[bj][n] = *(const LAS f32x4*)(bgate + (col0 - C_G) + bj * HALF + 4 * n);
; #pragma unroll
;             for (int ai = 0; ai < 2; ++ai)
; #pragma unroll
;                 for (int m = 0; m < 4; ++m)
; #pragma unroll
;                     for (int bj = 0; bj < 2; ++bj) { const f32x4 v0 = acc[ai][bj][m][0] + bv[bj][0], v1 = acc[ai][bj][m][1] + bv[bj][1];
;                         u32x4 w; w.x = cvt_pk_bf16(sigmoidf_(v0[0]), sigmoidf_(v0[1])); w.y = cvt_pk_bf16(sigmoidf_(v0[2]), sigmoidf_(v0[3]));
;                         w.z = cvt_pk_bf16(sigmoidf_(v1[0]), sigmoidf_(v1[1])); w.w = cvt_pk_bf16(sigmoidf_(v1[2]), sigmoidf_(v1[3]));
;                         gf[((ai * 4 + m) * 2 + bj) * 64] = w; }
	v_add_f32_e32 v71, 1.0, v71
	v_rcp_f32_e32 v73, v64
	v_add_f32_e32 v64, 1.0, v66
	v_mul_f32_e32 v56, 0xbfb8aa3b, v56
	v_rcp_f32_e32 v68, v68
	v_rcp_f32_e32 v69, v69
	v_rcp_f32_e32 v70, v70
	v_rcp_f32_e32 v71, v71
	v_rcp_f32_e32 v74, v64
	v_exp_f32_e32 v56, v56
	v_mul_f32_e32 v57, 0xbfb8aa3b, v57
	v_exp_f32_e32 v57, v57
	v_cvt_pk_bf16_f32 v64, v68, v69
	v_cvt_pk_bf16_f32 v65, v70, v71
	v_cvt_pk_bf16_f32 v66, v72, v67
	v_cvt_pk_bf16_f32 v67, v73, v74
	v_pk_add_f32 v[58:59], v[58:59], v[138:139]
	v_add_f32_e32 v56, 1.0, v56
	global_store_dwordx4 v[94:95], v[64:67], off offset:3072 sc1
	v_pk_add_f32 v[62:63], v[62:63], v[142:143]
	v_pk_add_f32 v[60:61], v[60:61], v[140:141]
	v_rcp_f32_e32 v64, v56
	v_add_f32_e32 v56, 1.0, v57
	v_mul_f32_e32 v57, 0xbfb8aa3b, v58
	v_mul_f32_e32 v60, 0xbfb8aa3b, v60
	v_mul_f32_e32 v61, 0xbfb8aa3b, v61
	v_mul_f32_e32 v62, 0xbfb8aa3b, v62
	v_mul_f32_e32 v63, 0xbfb8aa3b, v63
	v_exp_f32_e32 v57, v57
	v_mul_f32_e32 v58, 0xbfb8aa3b, v59
	v_exp_f32_e32 v60, v60
	v_exp_f32_e32 v61, v61
	v_exp_f32_e32 v62, v62
	v_exp_f32_e32 v63, v63
	v_exp_f32_e32 v58, v58
	v_rcp_f32_e32 v59, v56
	v_add_f32_e32 v56, 1.0, v57
	v_pk_add_f32 v[48:49], v[48:49], v[128:129]
	v_add_f32_e32 v60, 1.0, v60
	v_add_f32_e32 v61, 1.0, v61
	v_add_f32_e32 v62, 1.0, v62
	v_add_f32_e32 v63, 1.0, v63
	v_rcp_f32_e32 v65, v56
	v_add_f32_e32 v56, 1.0, v58
	v_mul_f32_e32 v48, 0xbfb8aa3b, v48
	v_rcp_f32_e32 v60, v60
	v_rcp_f32_e32 v61, v61
	v_rcp_f32_e32 v62, v62
	v_rcp_f32_e32 v63, v63
	v_rcp_f32_e32 v66, v56
	v_exp_f32_e32 v48, v48
	v_mul_f32_e32 v49, 0xbfb8aa3b, v49
	v_exp_f32_e32 v49, v49
	v_cvt_pk_bf16_f32 v56, v60, v61
	v_cvt_pk_bf16_f32 v57, v62, v63
	v_cvt_pk_bf16_f32 v58, v64, v59
	v_cvt_pk_bf16_f32 v59, v65, v66
	v_pk_add_f32 v[50:51], v[50:51], v[130:131]
	v_add_f32_e32 v48, 1.0, v48
	global_store_dwordx4 v[88:89], v[56:59], off sc1
	v_pk_add_f32 v[54:55], v[54:55], v[134:135]
	v_pk_add_f32 v[52:53], v[52:53], v[132:133]
	v_rcp_f32_e32 v56, v48
	v_add_f32_e32 v48, 1.0, v49
	v_mul_f32_e32 v49, 0xbfb8aa3b, v50
	v_mul_f32_e32 v52, 0xbfb8aa3b, v52
	v_mul_f32_e32 v53, 0xbfb8aa3b, v53
	v_mul_f32_e32 v54, 0xbfb8aa3b, v54
	v_mul_f32_e32 v55, 0xbfb8aa3b, v55
	v_exp_f32_e32 v49, v49
	v_mul_f32_e32 v50, 0xbfb8aa3b, v51
	v_exp_f32_e32 v52, v52
	v_exp_f32_e32 v53, v53
	v_exp_f32_e32 v54, v54
	v_exp_f32_e32 v55, v55
	v_exp_f32_e32 v50, v50
	v_rcp_f32_e32 v51, v48
	v_add_f32_e32 v48, 1.0, v49
	v_pk_add_f32 v[40:41], v[40:41], v[136:137]
	v_add_f32_e32 v52, 1.0, v52
	v_add_f32_e32 v53, 1.0, v53
	v_add_f32_e32 v54, 1.0, v54
	v_add_f32_e32 v55, 1.0, v55
	v_rcp_f32_e32 v57, v48
	v_add_f32_e32 v48, 1.0, v50
	v_mul_f32_e32 v40, 0xbfb8aa3b, v40
	v_rcp_f32_e32 v52, v52
	v_rcp_f32_e32 v53, v53
	v_rcp_f32_e32 v54, v54
	v_rcp_f32_e32 v55, v55
	v_rcp_f32_e32 v58, v48
	v_exp_f32_e32 v40, v40
	v_mul_f32_e32 v41, 0xbfb8aa3b, v41
	v_exp_f32_e32 v41, v41
	v_cvt_pk_bf16_f32 v48, v52, v53
	v_cvt_pk_bf16_f32 v49, v54, v55
	v_cvt_pk_bf16_f32 v50, v56, v51
	v_cvt_pk_bf16_f32 v51, v57, v58
	v_pk_add_f32 v[42:43], v[42:43], v[138:139]
	v_add_f32_e32 v40, 1.0, v40
	global_store_dwordx4 v[88:89], v[48:51], off offset:1024 sc1
	v_pk_add_f32 v[46:47], v[46:47], v[142:143]
	v_pk_add_f32 v[44:45], v[44:45], v[140:141]
	v_rcp_f32_e32 v48, v40
	v_add_f32_e32 v40, 1.0, v41
	v_mul_f32_e32 v41, 0xbfb8aa3b, v42
	v_mul_f32_e32 v44, 0xbfb8aa3b, v44
	v_mul_f32_e32 v45, 0xbfb8aa3b, v45
	v_mul_f32_e32 v46, 0xbfb8aa3b, v46
	v_mul_f32_e32 v47, 0xbfb8aa3b, v47
	v_exp_f32_e32 v41, v41
	v_mul_f32_e32 v42, 0xbfb8aa3b, v43
	v_exp_f32_e32 v44, v44
	v_exp_f32_e32 v45, v45
	v_exp_f32_e32 v46, v46
	v_exp_f32_e32 v47, v47
	v_exp_f32_e32 v42, v42
	v_rcp_f32_e32 v43, v40
	v_add_f32_e32 v40, 1.0, v41
	v_pk_add_f32 v[32:33], v[32:33], v[128:129]
	v_add_f32_e32 v44, 1.0, v44
	v_add_f32_e32 v45, 1.0, v45
	v_add_f32_e32 v46, 1.0, v46
	v_add_f32_e32 v47, 1.0, v47
	v_rcp_f32_e32 v49, v40
	v_add_f32_e32 v40, 1.0, v42
	v_mul_f32_e32 v32, 0xbfb8aa3b, v32
	v_rcp_f32_e32 v44, v44
	v_rcp_f32_e32 v45, v45
	v_rcp_f32_e32 v46, v46
	v_rcp_f32_e32 v47, v47
	v_rcp_f32_e32 v50, v40
	v_exp_f32_e32 v32, v32
	v_mul_f32_e32 v33, 0xbfb8aa3b, v33
	v_exp_f32_e32 v33, v33
	v_cvt_pk_bf16_f32 v40, v44, v45
	v_cvt_pk_bf16_f32 v41, v46, v47
	v_cvt_pk_bf16_f32 v42, v48, v43
	v_cvt_pk_bf16_f32 v43, v49, v50
	v_pk_add_f32 v[34:35], v[34:35], v[130:131]
	v_add_f32_e32 v32, 1.0, v32
	global_store_dwordx4 v[88:89], v[40:43], off offset:2048 sc1
	v_pk_add_f32 v[38:39], v[38:39], v[134:135]
	v_pk_add_f32 v[36:37], v[36:37], v[132:133]
	v_rcp_f32_e32 v40, v32
	v_add_f32_e32 v32, 1.0, v33
	v_mul_f32_e32 v33, 0xbfb8aa3b, v34
	v_mul_f32_e32 v36, 0xbfb8aa3b, v36
	v_mul_f32_e32 v37, 0xbfb8aa3b, v37
	v_mul_f32_e32 v38, 0xbfb8aa3b, v38
	v_mul_f32_e32 v39, 0xbfb8aa3b, v39
	v_exp_f32_e32 v33, v33
	v_mul_f32_e32 v34, 0xbfb8aa3b, v35
	v_exp_f32_e32 v36, v36
	v_exp_f32_e32 v37, v37
	v_exp_f32_e32 v38, v38
	v_exp_f32_e32 v39, v39
	v_exp_f32_e32 v34, v34
	v_rcp_f32_e32 v35, v32
	v_add_f32_e32 v32, 1.0, v33
	v_pk_add_f32 v[24:25], v[24:25], v[136:137]
	v_add_f32_e32 v36, 1.0, v36
	v_add_f32_e32 v37, 1.0, v37
	v_add_f32_e32 v38, 1.0, v38
	v_add_f32_e32 v39, 1.0, v39
	v_rcp_f32_e32 v41, v32
	v_add_f32_e32 v32, 1.0, v34
	v_mul_f32_e32 v24, 0xbfb8aa3b, v24
	v_rcp_f32_e32 v36, v36
	v_rcp_f32_e32 v37, v37
	v_rcp_f32_e32 v38, v38
	v_rcp_f32_e32 v39, v39
; #define LAS __attribute__((address_space(3)))
; __device__ __forceinline__ unsigned cvt_pk_bf16(float lo, float hi) { f32x2_t v = {lo, hi}; bf16x2_t r = __builtin_convertvector(v, bf16x2_t); return __builtin_bit_cast(unsigned, r); }
; __device__ __forceinline__ float sigmoidf_(float v) { return __builtin_amdgcn_rcpf(1.0f + __builtin_amdgcn_exp2f(-1.4426950408889634f * v)); }
; #define PG8_BAR __builtin_amdgcn_s_barrier()
;     __device__ __forceinline__ void operator()(const f32x4 (&acc)[2][2][4][2], const Unit& u, int wr, int wc, int fr, int fq) const {
;     ...
;             f32x4 bv[2][2];
; #pragma unroll
;             for (int bj = 0; bj < 2; ++bj)
; #pragma unroll
;                 for (int n = 0; n < 2; ++n) bv[bj][n] = *(const LAS f32x4*)(bgate + (col0 - C_G) + bj * HALF + 4 * n);
; #pragma unroll
;             for (int ai = 0; ai < 2; ++ai)
; #pragma unroll
;                 for (int m = 0; m < 4; ++m)
; #pragma unroll
;                     for (int bj = 0; bj < 2; ++bj) { const f32x4 v0 = acc[ai][bj][m][0] + bv[bj][0], v1 = acc[ai][bj][m][1] + bv[bj][1];
;                         u32x4 w; w.x = cvt_pk_bf16(sigmoidf_(v0[0]), sigmoidf_(v0[1])); w.y = cvt_pk_bf16(sigmoidf_(v0[2]), sigmoidf_(v0[3]));
;                         w.z = cvt_pk_bf16(sigmoidf_(v1[0]), sigmoidf_(v1[1])); w.w = cvt_pk_bf16(sigmoidf_(v1[2]), sigmoidf_(v1[3]));
;                         gf[((ai * 4 + m) * 2 + bj) * 64] = w; }
; template <class Epi, class Sched>
; __device__ __forceinline__ void gemm_phase(LAS unsigned char* lds, const Gemm g, const Sched& S, const Epi& E, const int tid) {
;     ...
;         if (wr == 0) PG8_BAR;
;         E(acc, cur, wr, wc, fr, fq);
;         if (!has_next) break;
	v_rcp_f32_e32 v42, v32
	v_exp_f32_e32 v24, v24
	v_mul_f32_e32 v25, 0xbfb8aa3b, v25
	v_exp_f32_e32 v25, v25
	v_cvt_pk_bf16_f32 v32, v36, v37
	v_cvt_pk_bf16_f32 v33, v38, v39
	v_cvt_pk_bf16_f32 v34, v40, v35
	v_cvt_pk_bf16_f32 v35, v41, v42
	v_pk_add_f32 v[28:29], v[28:29], v[140:141]
	v_pk_add_f32 v[26:27], v[26:27], v[138:139]
	v_add_f32_e32 v24, 1.0, v24
	global_store_dwordx4 v[88:89], v[32:35], off offset:3072 sc1
	v_pk_add_f32 v[30:31], v[30:31], v[142:143]
	v_mul_f32_e32 v28, 0xbfb8aa3b, v28
	v_mul_f32_e32 v29, 0xbfb8aa3b, v29
	v_rcp_f32_e32 v32, v24
	v_add_f32_e32 v24, 1.0, v25
	v_mul_f32_e32 v25, 0xbfb8aa3b, v26
	v_exp_f32_e32 v28, v28
	v_exp_f32_e32 v29, v29
	v_mul_f32_e32 v30, 0xbfb8aa3b, v30
	v_mul_f32_e32 v31, 0xbfb8aa3b, v31
	v_exp_f32_e32 v25, v25
	v_mul_f32_e32 v26, 0xbfb8aa3b, v27
	v_exp_f32_e32 v30, v30
	v_exp_f32_e32 v31, v31
	v_exp_f32_e32 v26, v26
	v_add_f32_e32 v28, 1.0, v28
	v_add_f32_e32 v29, 1.0, v29
	v_rcp_f32_e32 v27, v24
	v_add_f32_e32 v24, 1.0, v25
	v_pk_add_f32 v[16:17], v[16:17], v[128:129]
	v_rcp_f32_e32 v28, v28
	v_rcp_f32_e32 v29, v29
	v_add_f32_e32 v30, 1.0, v30
	v_add_f32_e32 v31, 1.0, v31
	v_rcp_f32_e32 v33, v24
	v_add_f32_e32 v24, 1.0, v26
	v_mul_f32_e32 v16, 0xbfb8aa3b, v16
	v_rcp_f32_e32 v30, v30
	v_rcp_f32_e32 v31, v31
	v_rcp_f32_e32 v34, v24
	v_exp_f32_e32 v16, v16
	v_mul_f32_e32 v17, 0xbfb8aa3b, v17
	v_exp_f32_e32 v17, v17
	s_movk_i32 s2, 0x3000
	v_cvt_pk_bf16_f32 v24, v28, v29
	v_add_co_u32_e32 v28, vcc, s2, v154
	v_cvt_pk_bf16_f32 v25, v30, v31
	v_cvt_pk_bf16_f32 v26, v32, v27
	v_cvt_pk_bf16_f32 v27, v33, v34
	v_addc_co_u32_e32 v29, vcc, 0, v155, vcc
	v_pk_add_f32 v[18:19], v[18:19], v[130:131]
	v_add_f32_e32 v16, 1.0, v16
	global_store_dwordx4 v[28:29], v[24:27], off sc1
	v_pk_add_f32 v[22:23], v[22:23], v[134:135]
	v_pk_add_f32 v[20:21], v[20:21], v[132:133]
	v_rcp_f32_e32 v24, v16
	v_add_f32_e32 v16, 1.0, v17
	v_mul_f32_e32 v17, 0xbfb8aa3b, v18
	v_mul_f32_e32 v20, 0xbfb8aa3b, v20
	v_mul_f32_e32 v21, 0xbfb8aa3b, v21
	v_mul_f32_e32 v22, 0xbfb8aa3b, v22
	v_mul_f32_e32 v23, 0xbfb8aa3b, v23
	v_exp_f32_e32 v17, v17
	v_mul_f32_e32 v18, 0xbfb8aa3b, v19
	v_exp_f32_e32 v20, v20
	v_exp_f32_e32 v21, v21
	v_exp_f32_e32 v22, v22
	v_exp_f32_e32 v23, v23
	v_exp_f32_e32 v18, v18
	v_rcp_f32_e32 v19, v16
	v_add_f32_e32 v16, 1.0, v17
	v_pk_add_f32 v[8:9], v[8:9], v[136:137]
	v_add_f32_e32 v20, 1.0, v20
	v_add_f32_e32 v21, 1.0, v21
	v_add_f32_e32 v22, 1.0, v22
	v_add_f32_e32 v23, 1.0, v23
	v_rcp_f32_e32 v25, v16
	v_add_f32_e32 v16, 1.0, v18
	v_mul_f32_e32 v8, 0xbfb8aa3b, v8
	v_rcp_f32_e32 v20, v20
	v_rcp_f32_e32 v21, v21
	v_rcp_f32_e32 v22, v22
	v_rcp_f32_e32 v23, v23
	v_rcp_f32_e32 v26, v16
	v_exp_f32_e32 v8, v8
	v_mul_f32_e32 v9, 0xbfb8aa3b, v9
	v_exp_f32_e32 v9, v9
	v_cvt_pk_bf16_f32 v16, v20, v21
	v_cvt_pk_bf16_f32 v17, v22, v23
	v_cvt_pk_bf16_f32 v18, v24, v19
	v_cvt_pk_bf16_f32 v19, v25, v26
	v_pk_add_f32 v[10:11], v[10:11], v[138:139]
	v_add_f32_e32 v8, 1.0, v8
	global_store_dwordx4 v[28:29], v[16:19], off offset:1024 sc1
	v_pk_add_f32 v[14:15], v[14:15], v[142:143]
	v_pk_add_f32 v[12:13], v[12:13], v[140:141]
	v_rcp_f32_e32 v16, v8
	v_add_f32_e32 v8, 1.0, v9
	v_mul_f32_e32 v9, 0xbfb8aa3b, v10
	v_mul_f32_e32 v12, 0xbfb8aa3b, v12
	v_mul_f32_e32 v13, 0xbfb8aa3b, v13
	v_mul_f32_e32 v14, 0xbfb8aa3b, v14
	v_mul_f32_e32 v15, 0xbfb8aa3b, v15
	v_exp_f32_e32 v9, v9
	v_mul_f32_e32 v10, 0xbfb8aa3b, v11
	v_exp_f32_e32 v12, v12
	v_exp_f32_e32 v13, v13
	v_exp_f32_e32 v14, v14
	v_exp_f32_e32 v15, v15
	v_exp_f32_e32 v10, v10
	v_rcp_f32_e32 v11, v8
	v_add_f32_e32 v8, 1.0, v9
	v_pk_add_f32 v[0:1], v[0:1], v[128:129]
	v_add_f32_e32 v12, 1.0, v12
	v_add_f32_e32 v13, 1.0, v13
	v_add_f32_e32 v14, 1.0, v14
	v_add_f32_e32 v15, 1.0, v15
	v_rcp_f32_e32 v17, v8
	v_add_f32_e32 v8, 1.0, v10
	v_mul_f32_e32 v0, 0xbfb8aa3b, v0
	v_rcp_f32_e32 v12, v12
	v_rcp_f32_e32 v13, v13
	v_rcp_f32_e32 v14, v14
	v_rcp_f32_e32 v15, v15
	v_rcp_f32_e32 v18, v8
	v_exp_f32_e32 v0, v0
	v_mul_f32_e32 v1, 0xbfb8aa3b, v1
	v_exp_f32_e32 v1, v1
	v_cvt_pk_bf16_f32 v8, v12, v13
	v_cvt_pk_bf16_f32 v9, v14, v15
	v_cvt_pk_bf16_f32 v10, v16, v11
	v_cvt_pk_bf16_f32 v11, v17, v18
	v_pk_add_f32 v[2:3], v[2:3], v[130:131]
	v_add_f32_e32 v0, 1.0, v0
	global_store_dwordx4 v[28:29], v[8:11], off offset:2048 sc1
	v_pk_add_f32 v[6:7], v[6:7], v[134:135]
	v_pk_add_f32 v[4:5], v[4:5], v[132:133]
	v_rcp_f32_e32 v8, v0
	v_add_f32_e32 v0, 1.0, v1
	v_mul_f32_e32 v1, 0xbfb8aa3b, v2
	v_mul_f32_e32 v4, 0xbfb8aa3b, v4
	v_mul_f32_e32 v5, 0xbfb8aa3b, v5
	v_mul_f32_e32 v6, 0xbfb8aa3b, v6
	v_mul_f32_e32 v7, 0xbfb8aa3b, v7
	v_exp_f32_e32 v1, v1
	v_mul_f32_e32 v2, 0xbfb8aa3b, v3
	v_exp_f32_e32 v4, v4
	v_exp_f32_e32 v5, v5
	v_exp_f32_e32 v6, v6
	v_exp_f32_e32 v7, v7
	v_exp_f32_e32 v2, v2
	v_rcp_f32_e32 v3, v0
	v_add_f32_e32 v0, 1.0, v1
	v_add_f32_e32 v4, 1.0, v4
	v_add_f32_e32 v5, 1.0, v5
	v_add_f32_e32 v6, 1.0, v6
	v_add_f32_e32 v7, 1.0, v7
	v_rcp_f32_e32 v9, v0
	v_add_f32_e32 v0, 1.0, v2
	v_rcp_f32_e32 v4, v4
	v_rcp_f32_e32 v5, v5
	v_rcp_f32_e32 v6, v6
	v_rcp_f32_e32 v7, v7
	v_rcp_f32_e32 v10, v0
	v_cvt_pk_bf16_f32 v0, v4, v5
	v_cvt_pk_bf16_f32 v2, v8, v3
	v_cvt_pk_bf16_f32 v1, v6, v7
	v_cvt_pk_bf16_f32 v3, v9, v10
	global_store_dwordx4 v[28:29], v[0:3], off offset:3072 sc1
	s_andn2_b64 vcc, exec, s[36:37]
	s_mov_b64 s[2:3], -1
	s_cbranch_vccnz .LBB0_343
